# GEMM loops: duplicate LDS waits removed; scalar/VALU bookkeeping that sat between the last MFMA of a segment and its barrier moved behind the barrier (or ahead of the segment for the loop tail)
# speedup vs baseline: 1.0112x; 1.0021x over previous
.LBB0_252:
	s_add_u32 s0, s0, 0x80
	s_addc_u32 s1, s1, 0
	s_add_u32 s47, s4, 0x100
	s_addc_u32 s48, s5, 0
	s_mov_b32 s4, 0
	s_waitcnt lgkmcnt(0)
	s_waitcnt vmcnt(0)
	s_add_i32 s49, s4, 2
	s_add_u32 s16, s0, 0x80
	s_addc_u32 s5, s1, 0
	s_add_i32 s65, 0, 0x10000
	v_add_u32_e32 v142, s65, v145
	ds_read_b128 v[148:151], v142
	ds_read_b128 v[152:155], v142 offset:1024
	ds_read_b128 v[156:159], v142 offset:2048
	ds_read_b128 v[160:163], v142 offset:3072
	s_cmp_eq_u32 s41, s4
	s_cselect_b32 s4, s10, s16
	s_cselect_b32 s5, s11, s5
	s_cselect_b32 s17, s13, s48
	s_cselect_b32 s16, s12, s47
	v_lshl_add_u64 v[142:143], s[0:1], 0, v[138:139]
	s_add_i32 m0, s26, 0xc000
	ds_read_b128 v[164:167], v146
	ds_read_b128 v[168:171], v146 offset:1024
	ds_read_b128 v[172:175], v146 offset:2048
	ds_read_b128 v[176:179], v146 offset:3072
	ds_read_b128 v[180:183], v146 offset:4096
	ds_read_b128 v[204:207], v146 offset:5120
	ds_read_b128 v[208:211], v146 offset:6144
	ds_read_b128 v[212:215], v146 offset:7168
	global_load_lds_dwordx4 v[142:143], off
	v_lshl_add_u64 v[142:143], s[0:1], 0, v[140:141]
	s_add_i32 m0, s26, 0xe000
	s_nop 0
	global_load_lds_dwordx4 v[142:143], off
	s_waitcnt lgkmcnt(8)
	s_barrier
	s_waitcnt lgkmcnt(0)
	v_mfma_f32_16x16x32_bf16 v[126:129], v[148:151], v[164:167], 0
	v_mfma_f32_16x16x32_bf16 v[122:125], v[156:159], v[164:167], 0
	v_mfma_f32_16x16x32_bf16 v[110:113], v[148:151], v[172:175], 0
	v_mfma_f32_16x16x32_bf16 v[106:109], v[156:159], v[172:175], 0
	v_mfma_f32_16x16x32_bf16 v[94:97], v[148:151], v[180:183], 0
	v_mfma_f32_16x16x32_bf16 v[90:93], v[156:159], v[180:183], 0
	v_mfma_f32_16x16x32_bf16 v[78:81], v[148:151], v[208:211], 0
	v_mfma_f32_16x16x32_bf16 v[74:77], v[156:159], v[208:211], 0
	v_mfma_f32_16x16x32_bf16 v[126:129], v[152:155], v[168:171], v[126:129]
	v_mfma_f32_16x16x32_bf16 v[122:125], v[160:163], v[168:171], v[122:125]
	v_mfma_f32_16x16x32_bf16 v[110:113], v[152:155], v[176:179], v[110:113]
	v_mfma_f32_16x16x32_bf16 v[106:109], v[160:163], v[176:179], v[106:109]
	v_mfma_f32_16x16x32_bf16 v[94:97], v[152:155], v[204:207], v[94:97]
	v_mfma_f32_16x16x32_bf16 v[90:93], v[160:163], v[204:207], v[90:93]
	v_mfma_f32_16x16x32_bf16 v[78:81], v[152:155], v[212:215], v[78:81]
	v_mfma_f32_16x16x32_bf16 v[74:77], v[160:163], v[212:215], v[74:77]
	s_barrier
	s_add_i32 s66, 0, 0x14000
	v_add_u32_e32 v142, s66, v145
	s_add_i32 s65, s65, s24
	ds_read_b128 v[216:219], v142
	ds_read_b128 v[220:223], v142 offset:1024
	ds_read_b128 v[224:227], v142 offset:2048
	ds_read_b128 v[228:231], v142 offset:3072
	v_lshl_add_u64 v[142:143], s[16:17], 0, v[132:133]
	s_mov_b32 m0, s65
	v_lshl_add_u64 v[184:185], s[16:17], 0, v[136:137]
	global_load_lds_dwordx4 v[142:143], off
	s_add_i32 m0, s65, 0x2000
	s_nop 0
	global_load_lds_dwordx4 v[184:185], off
	s_barrier
	s_waitcnt lgkmcnt(0)
	v_mfma_f32_16x16x32_bf16 v[114:117], v[216:219], v[164:167], 0
	v_mfma_f32_16x16x32_bf16 v[118:121], v[224:227], v[164:167], 0
	v_mfma_f32_16x16x32_bf16 v[98:101], v[216:219], v[172:175], 0
	v_mfma_f32_16x16x32_bf16 v[102:105], v[224:227], v[172:175], 0
	v_mfma_f32_16x16x32_bf16 v[82:85], v[216:219], v[180:183], 0
	v_mfma_f32_16x16x32_bf16 v[86:89], v[224:227], v[180:183], 0
	v_mfma_f32_16x16x32_bf16 v[66:69], v[216:219], v[208:211], 0
	v_mfma_f32_16x16x32_bf16 v[70:73], v[224:227], v[208:211], 0
	v_mfma_f32_16x16x32_bf16 v[114:117], v[220:223], v[168:171], v[114:117]
	v_mfma_f32_16x16x32_bf16 v[118:121], v[228:231], v[168:171], v[118:121]
	v_mfma_f32_16x16x32_bf16 v[98:101], v[220:223], v[176:179], v[98:101]
	v_mfma_f32_16x16x32_bf16 v[102:105], v[228:231], v[176:179], v[102:105]
	v_mfma_f32_16x16x32_bf16 v[82:85], v[220:223], v[204:207], v[82:85]
	v_mfma_f32_16x16x32_bf16 v[86:89], v[228:231], v[204:207], v[86:89]
	v_mfma_f32_16x16x32_bf16 v[66:69], v[220:223], v[212:215], v[66:69]
	v_mfma_f32_16x16x32_bf16 v[70:73], v[228:231], v[212:215], v[70:73]
	s_barrier
	s_mov_b32 m0, s26
	v_lshl_add_u64 v[232:233], s[4:5], 0, v[130:131]
	ds_read_b128 v[164:167], v146 offset:16384
	ds_read_b128 v[168:171], v146 offset:17408
	ds_read_b128 v[172:175], v146 offset:18432
	ds_read_b128 v[176:179], v146 offset:19456
	ds_read_b128 v[180:183], v146 offset:20480
	ds_read_b128 v[204:207], v146 offset:21504
	ds_read_b128 v[208:211], v146 offset:22528
	ds_read_b128 v[212:215], v146 offset:23552
	global_load_lds_dwordx4 v[232:233], off
	v_lshl_add_u64 v[234:235], s[4:5], 0, v[134:135]
	s_mov_b32 m0, s27
	s_nop 0
	global_load_lds_dwordx4 v[234:235], off
	s_barrier
	s_waitcnt lgkmcnt(0)
	v_mfma_f32_16x16x32_bf16 v[62:65], v[148:151], v[164:167], 0
	v_mfma_f32_16x16x32_bf16 v[58:61], v[156:159], v[164:167], 0
	v_mfma_f32_16x16x32_bf16 v[46:49], v[148:151], v[172:175], 0
	v_mfma_f32_16x16x32_bf16 v[42:45], v[156:159], v[172:175], 0
	v_mfma_f32_16x16x32_bf16 v[30:33], v[148:151], v[180:183], 0
	v_mfma_f32_16x16x32_bf16 v[26:29], v[156:159], v[180:183], 0
	v_mfma_f32_16x16x32_bf16 v[14:17], v[148:151], v[208:211], 0
	v_mfma_f32_16x16x32_bf16 v[10:13], v[156:159], v[208:211], 0
	v_mfma_f32_16x16x32_bf16 v[62:65], v[152:155], v[168:171], v[62:65]
	v_mfma_f32_16x16x32_bf16 v[58:61], v[160:163], v[168:171], v[58:61]
	v_mfma_f32_16x16x32_bf16 v[46:49], v[152:155], v[176:179], v[46:49]
	v_mfma_f32_16x16x32_bf16 v[42:45], v[160:163], v[176:179], v[42:45]
	v_mfma_f32_16x16x32_bf16 v[30:33], v[152:155], v[204:207], v[30:33]
	v_mfma_f32_16x16x32_bf16 v[26:29], v[160:163], v[204:207], v[26:29]
	v_mfma_f32_16x16x32_bf16 v[14:17], v[152:155], v[212:215], v[14:17]
	v_mfma_f32_16x16x32_bf16 v[10:13], v[160:163], v[212:215], v[10:13]
	s_barrier
	s_add_u32 s16, s16, s92
	s_addc_u32 s17, s17, 0
	s_add_i32 s65, s66, s24
	v_lshl_add_u64 v[236:237], s[16:17], 0, v[132:133]
	s_mov_b32 m0, s65
	v_lshl_add_u64 v[238:239], s[16:17], 0, v[136:137]
	global_load_lds_dwordx4 v[236:237], off
	s_add_i32 m0, s65, 0x2000
	s_nop 0
	global_load_lds_dwordx4 v[238:239], off
	s_waitcnt vmcnt(6)
	s_barrier
	v_mfma_f32_16x16x32_bf16 v[50:53], v[216:219], v[164:167], 0
	v_mfma_f32_16x16x32_bf16 v[54:57], v[224:227], v[164:167], 0
	v_mfma_f32_16x16x32_bf16 v[34:37], v[216:219], v[172:175], 0
	v_mfma_f32_16x16x32_bf16 v[38:41], v[224:227], v[172:175], 0
	v_mfma_f32_16x16x32_bf16 v[18:21], v[216:219], v[180:183], 0
	v_mfma_f32_16x16x32_bf16 v[22:25], v[224:227], v[180:183], 0
	v_mfma_f32_16x16x32_bf16 v[6:9], v[216:219], v[208:211], 0
	v_mfma_f32_16x16x32_bf16 v[2:5], v[224:227], v[208:211], 0
	v_mfma_f32_16x16x32_bf16 v[50:53], v[220:223], v[168:171], v[50:53]
	v_mfma_f32_16x16x32_bf16 v[54:57], v[228:231], v[168:171], v[54:57]
	v_mfma_f32_16x16x32_bf16 v[34:37], v[220:223], v[176:179], v[34:37]
	v_mfma_f32_16x16x32_bf16 v[38:41], v[228:231], v[176:179], v[38:41]
	v_mfma_f32_16x16x32_bf16 v[18:21], v[220:223], v[204:207], v[18:21]
	v_mfma_f32_16x16x32_bf16 v[22:25], v[228:231], v[204:207], v[22:25]
	v_mfma_f32_16x16x32_bf16 v[6:9], v[220:223], v[212:215], v[6:9]
	v_mfma_f32_16x16x32_bf16 v[2:5], v[228:231], v[212:215], v[2:5]
	s_barrier
	s_add_i32 s16, 0, 0x18000
	v_add_u32_e32 v147, s16, v145
	ds_read_b128 v[148:151], v147
	ds_read_b128 v[152:155], v147 offset:1024
	ds_read_b128 v[156:159], v147 offset:2048
	ds_read_b128 v[160:163], v147 offset:3072
	s_add_u32 s4, s4, s92
	s_addc_u32 s5, s5, 0
	s_mov_b32 m0, s28
	v_lshl_add_u64 v[216:217], s[4:5], 0, v[130:131]
	ds_read_b128 v[164:167], v146 offset:32768
	ds_read_b128 v[168:171], v146 offset:33792
	ds_read_b128 v[172:175], v146 offset:34816
	ds_read_b128 v[176:179], v146 offset:35840
	ds_read_b128 v[180:183], v146 offset:36864
	ds_read_b128 v[204:207], v146 offset:37888
	ds_read_b128 v[208:211], v146 offset:38912
	ds_read_b128 v[212:215], v146 offset:39936
	global_load_lds_dwordx4 v[216:217], off
	v_lshl_add_u64 v[216:217], s[4:5], 0, v[134:135]
	s_mov_b32 m0, s29
	s_nop 0
	global_load_lds_dwordx4 v[216:217], off
	s_waitcnt lgkmcnt(8)
	s_barrier
	s_waitcnt lgkmcnt(0)
	v_mfma_f32_16x16x32_bf16 v[126:129], v[148:151], v[164:167], v[126:129]
	v_mfma_f32_16x16x32_bf16 v[122:125], v[156:159], v[164:167], v[122:125]
	v_mfma_f32_16x16x32_bf16 v[110:113], v[148:151], v[172:175], v[110:113]
	v_mfma_f32_16x16x32_bf16 v[106:109], v[156:159], v[172:175], v[106:109]
	v_mfma_f32_16x16x32_bf16 v[94:97], v[148:151], v[180:183], v[94:97]
	v_mfma_f32_16x16x32_bf16 v[90:93], v[156:159], v[180:183], v[90:93]
	v_mfma_f32_16x16x32_bf16 v[78:81], v[148:151], v[208:211], v[78:81]
	v_mfma_f32_16x16x32_bf16 v[74:77], v[156:159], v[208:211], v[74:77]
	v_mfma_f32_16x16x32_bf16 v[126:129], v[152:155], v[168:171], v[126:129]
	v_mfma_f32_16x16x32_bf16 v[122:125], v[160:163], v[168:171], v[122:125]
	v_mfma_f32_16x16x32_bf16 v[110:113], v[152:155], v[176:179], v[110:113]
	v_mfma_f32_16x16x32_bf16 v[106:109], v[160:163], v[176:179], v[106:109]
	v_mfma_f32_16x16x32_bf16 v[94:97], v[152:155], v[204:207], v[94:97]
	v_mfma_f32_16x16x32_bf16 v[90:93], v[160:163], v[204:207], v[90:93]
	v_mfma_f32_16x16x32_bf16 v[78:81], v[152:155], v[212:215], v[78:81]
	v_mfma_f32_16x16x32_bf16 v[74:77], v[160:163], v[212:215], v[74:77]
	s_barrier
	s_add_i32 s4, 0, 0x1c000
	s_add_i32 s5, s16, s24
	v_add_u32_e32 v147, s4, v145
	v_lshl_add_u64 v[142:143], v[142:143], 0, s[6:7]
	s_mov_b32 m0, s5
	ds_read_b128 v[216:219], v147
	ds_read_b128 v[220:223], v147 offset:1024
	ds_read_b128 v[224:227], v147 offset:2048
	ds_read_b128 v[228:231], v147 offset:3072
	global_load_lds_dwordx4 v[142:143], off
	v_lshl_add_u64 v[142:143], v[184:185], 0, s[6:7]
	s_add_i32 m0, s5, 0x2000
	s_nop 0
	global_load_lds_dwordx4 v[142:143], off
	s_barrier
	s_waitcnt lgkmcnt(0)
	v_mfma_f32_16x16x32_bf16 v[114:117], v[216:219], v[164:167], v[114:117]
	v_mfma_f32_16x16x32_bf16 v[118:121], v[224:227], v[164:167], v[118:121]
	v_mfma_f32_16x16x32_bf16 v[98:101], v[216:219], v[172:175], v[98:101]
	v_mfma_f32_16x16x32_bf16 v[102:105], v[224:227], v[172:175], v[102:105]
	v_mfma_f32_16x16x32_bf16 v[82:85], v[216:219], v[180:183], v[82:85]
	v_mfma_f32_16x16x32_bf16 v[86:89], v[224:227], v[180:183], v[86:89]
	v_mfma_f32_16x16x32_bf16 v[66:69], v[216:219], v[208:211], v[66:69]
	v_mfma_f32_16x16x32_bf16 v[70:73], v[224:227], v[208:211], v[70:73]
	v_mfma_f32_16x16x32_bf16 v[114:117], v[220:223], v[168:171], v[114:117]
	v_mfma_f32_16x16x32_bf16 v[118:121], v[228:231], v[168:171], v[118:121]
	v_mfma_f32_16x16x32_bf16 v[98:101], v[220:223], v[176:179], v[98:101]
	v_mfma_f32_16x16x32_bf16 v[102:105], v[228:231], v[176:179], v[102:105]
	v_mfma_f32_16x16x32_bf16 v[82:85], v[220:223], v[204:207], v[82:85]
	v_mfma_f32_16x16x32_bf16 v[86:89], v[228:231], v[204:207], v[86:89]
	v_mfma_f32_16x16x32_bf16 v[66:69], v[220:223], v[212:215], v[66:69]
	v_mfma_f32_16x16x32_bf16 v[70:73], v[228:231], v[212:215], v[70:73]
	s_barrier
	s_mov_b32 m0, s35
	v_lshl_add_u64 v[142:143], v[232:233], 0, s[6:7]
	ds_read_b128 v[164:167], v146 offset:49152
	ds_read_b128 v[168:171], v146 offset:50176
	ds_read_b128 v[172:175], v146 offset:51200
	ds_read_b128 v[176:179], v146 offset:52224
	ds_read_b128 v[180:183], v146 offset:53248
	ds_read_b128 v[204:207], v146 offset:54272
	ds_read_b128 v[208:211], v146 offset:55296
	ds_read_b128 v[212:215], v146 offset:56320
	global_load_lds_dwordx4 v[142:143], off
	v_lshl_add_u64 v[142:143], v[234:235], 0, s[6:7]
	s_mov_b32 m0, s40
	s_nop 0
	global_load_lds_dwordx4 v[142:143], off
	s_barrier
	s_waitcnt lgkmcnt(0)
	v_mfma_f32_16x16x32_bf16 v[62:65], v[148:151], v[164:167], v[62:65]
	v_mfma_f32_16x16x32_bf16 v[58:61], v[156:159], v[164:167], v[58:61]
	v_mfma_f32_16x16x32_bf16 v[46:49], v[148:151], v[172:175], v[46:49]
	v_mfma_f32_16x16x32_bf16 v[42:45], v[156:159], v[172:175], v[42:45]
	v_mfma_f32_16x16x32_bf16 v[30:33], v[148:151], v[180:183], v[30:33]
	v_mfma_f32_16x16x32_bf16 v[26:29], v[156:159], v[180:183], v[26:29]
	v_mfma_f32_16x16x32_bf16 v[14:17], v[148:151], v[208:211], v[14:17]
	v_mfma_f32_16x16x32_bf16 v[10:13], v[156:159], v[208:211], v[10:13]
	v_mfma_f32_16x16x32_bf16 v[62:65], v[152:155], v[168:171], v[62:65]
	v_mfma_f32_16x16x32_bf16 v[58:61], v[160:163], v[168:171], v[58:61]
	v_mfma_f32_16x16x32_bf16 v[46:49], v[152:155], v[176:179], v[46:49]
	v_mfma_f32_16x16x32_bf16 v[42:45], v[160:163], v[176:179], v[42:45]
	v_mfma_f32_16x16x32_bf16 v[30:33], v[152:155], v[204:207], v[30:33]
	v_mfma_f32_16x16x32_bf16 v[26:29], v[160:163], v[204:207], v[26:29]
	v_mfma_f32_16x16x32_bf16 v[14:17], v[152:155], v[212:215], v[14:17]
	v_mfma_f32_16x16x32_bf16 v[10:13], v[160:163], v[212:215], v[10:13]
	s_barrier
	s_add_i32 s4, s4, s24
	v_lshl_add_u64 v[142:143], v[236:237], 0, s[6:7]
	s_mov_b32 m0, s4
	s_nop 0
	global_load_lds_dwordx4 v[142:143], off
	v_lshl_add_u64 v[142:143], v[238:239], 0, s[6:7]
	s_add_i32 m0, s4, 0x2000
	s_nop 0
	global_load_lds_dwordx4 v[142:143], off
	s_add_u32 s0, s0, 0x100
	s_addc_u32 s1, s1, 0
	s_add_u32 s47, s47, 0x100
	s_addc_u32 s48, s48, 0
	s_cmp_ge_u32 s49, s30
	s_mov_b32 s4, s49
	s_waitcnt vmcnt(6)
	s_barrier
	v_mfma_f32_16x16x32_bf16 v[50:53], v[216:219], v[164:167], v[50:53]
	v_mfma_f32_16x16x32_bf16 v[54:57], v[224:227], v[164:167], v[54:57]
	v_mfma_f32_16x16x32_bf16 v[34:37], v[216:219], v[172:175], v[34:37]
	v_mfma_f32_16x16x32_bf16 v[38:41], v[224:227], v[172:175], v[38:41]
	v_mfma_f32_16x16x32_bf16 v[18:21], v[216:219], v[180:183], v[18:21]
	v_mfma_f32_16x16x32_bf16 v[22:25], v[224:227], v[180:183], v[22:25]
	v_mfma_f32_16x16x32_bf16 v[6:9], v[216:219], v[208:211], v[6:9]
	v_mfma_f32_16x16x32_bf16 v[2:5], v[224:227], v[208:211], v[2:5]
	v_mfma_f32_16x16x32_bf16 v[50:53], v[220:223], v[168:171], v[50:53]
	v_mfma_f32_16x16x32_bf16 v[54:57], v[228:231], v[168:171], v[54:57]
	v_mfma_f32_16x16x32_bf16 v[34:37], v[220:223], v[176:179], v[34:37]
	v_mfma_f32_16x16x32_bf16 v[38:41], v[228:231], v[176:179], v[38:41]
	v_mfma_f32_16x16x32_bf16 v[18:21], v[220:223], v[204:207], v[18:21]
	v_mfma_f32_16x16x32_bf16 v[22:25], v[228:231], v[204:207], v[22:25]
	v_mfma_f32_16x16x32_bf16 v[6:9], v[220:223], v[212:215], v[6:9]
	v_mfma_f32_16x16x32_bf16 v[2:5], v[228:231], v[212:215], v[2:5]
	s_barrier
	s_cbranch_scc1 .Lkexit_253
.LBB0_253:
	s_add_i32 s49, s4, 2
	s_add_u32 s16, s0, 0x80
	s_addc_u32 s5, s1, 0
	s_add_i32 s65, 0, 0x10000
	v_add_u32_e32 v142, s65, v145
	ds_read_b128 v[148:151], v142
	ds_read_b128 v[152:155], v142 offset:1024
	ds_read_b128 v[156:159], v142 offset:2048
	ds_read_b128 v[160:163], v142 offset:3072
	s_cmp_eq_u32 s41, s4
	s_cselect_b32 s4, s10, s16
	s_cselect_b32 s5, s11, s5
	s_cselect_b32 s17, s13, s48
	s_cselect_b32 s16, s12, s47
	v_lshl_add_u64 v[142:143], s[0:1], 0, v[138:139]
	s_add_i32 m0, s26, 0xc000
	ds_read_b128 v[164:167], v146
	ds_read_b128 v[168:171], v146 offset:1024
	ds_read_b128 v[172:175], v146 offset:2048
	ds_read_b128 v[176:179], v146 offset:3072
	ds_read_b128 v[180:183], v146 offset:4096
	ds_read_b128 v[204:207], v146 offset:5120
	ds_read_b128 v[208:211], v146 offset:6144
	ds_read_b128 v[212:215], v146 offset:7168
	global_load_lds_dwordx4 v[142:143], off
	v_lshl_add_u64 v[142:143], s[0:1], 0, v[140:141]
	s_add_i32 m0, s26, 0xe000
	s_nop 0
	global_load_lds_dwordx4 v[142:143], off
	s_waitcnt lgkmcnt(8)
	s_barrier
	s_waitcnt lgkmcnt(0)
	v_mfma_f32_16x16x32_bf16 v[126:129], v[148:151], v[164:167], v[126:129]
	v_mfma_f32_16x16x32_bf16 v[122:125], v[156:159], v[164:167], v[122:125]
	v_mfma_f32_16x16x32_bf16 v[110:113], v[148:151], v[172:175], v[110:113]
	v_mfma_f32_16x16x32_bf16 v[106:109], v[156:159], v[172:175], v[106:109]
	v_mfma_f32_16x16x32_bf16 v[94:97], v[148:151], v[180:183], v[94:97]
	v_mfma_f32_16x16x32_bf16 v[90:93], v[156:159], v[180:183], v[90:93]
	v_mfma_f32_16x16x32_bf16 v[78:81], v[148:151], v[208:211], v[78:81]
	v_mfma_f32_16x16x32_bf16 v[74:77], v[156:159], v[208:211], v[74:77]
	v_mfma_f32_16x16x32_bf16 v[126:129], v[152:155], v[168:171], v[126:129]
	v_mfma_f32_16x16x32_bf16 v[122:125], v[160:163], v[168:171], v[122:125]
	v_mfma_f32_16x16x32_bf16 v[110:113], v[152:155], v[176:179], v[110:113]
	v_mfma_f32_16x16x32_bf16 v[106:109], v[160:163], v[176:179], v[106:109]
	v_mfma_f32_16x16x32_bf16 v[94:97], v[152:155], v[204:207], v[94:97]
	v_mfma_f32_16x16x32_bf16 v[90:93], v[160:163], v[204:207], v[90:93]
	v_mfma_f32_16x16x32_bf16 v[78:81], v[152:155], v[212:215], v[78:81]
	v_mfma_f32_16x16x32_bf16 v[74:77], v[160:163], v[212:215], v[74:77]
	s_barrier
	s_add_i32 s66, 0, 0x14000
	v_add_u32_e32 v142, s66, v145
	s_add_i32 s65, s65, s24
	ds_read_b128 v[216:219], v142
	ds_read_b128 v[220:223], v142 offset:1024
	ds_read_b128 v[224:227], v142 offset:2048
	ds_read_b128 v[228:231], v142 offset:3072
	v_lshl_add_u64 v[142:143], s[16:17], 0, v[132:133]
	s_mov_b32 m0, s65
	v_lshl_add_u64 v[184:185], s[16:17], 0, v[136:137]
	global_load_lds_dwordx4 v[142:143], off
	s_add_i32 m0, s65, 0x2000
	s_nop 0
	global_load_lds_dwordx4 v[184:185], off
	s_barrier
	s_waitcnt lgkmcnt(0)
	v_mfma_f32_16x16x32_bf16 v[114:117], v[216:219], v[164:167], v[114:117]
	v_mfma_f32_16x16x32_bf16 v[118:121], v[224:227], v[164:167], v[118:121]
	v_mfma_f32_16x16x32_bf16 v[98:101], v[216:219], v[172:175], v[98:101]
	v_mfma_f32_16x16x32_bf16 v[102:105], v[224:227], v[172:175], v[102:105]
	v_mfma_f32_16x16x32_bf16 v[82:85], v[216:219], v[180:183], v[82:85]
	v_mfma_f32_16x16x32_bf16 v[86:89], v[224:227], v[180:183], v[86:89]
	v_mfma_f32_16x16x32_bf16 v[66:69], v[216:219], v[208:211], v[66:69]
	v_mfma_f32_16x16x32_bf16 v[70:73], v[224:227], v[208:211], v[70:73]
	v_mfma_f32_16x16x32_bf16 v[114:117], v[220:223], v[168:171], v[114:117]
	v_mfma_f32_16x16x32_bf16 v[118:121], v[228:231], v[168:171], v[118:121]
	v_mfma_f32_16x16x32_bf16 v[98:101], v[220:223], v[176:179], v[98:101]
	v_mfma_f32_16x16x32_bf16 v[102:105], v[228:231], v[176:179], v[102:105]
	v_mfma_f32_16x16x32_bf16 v[82:85], v[220:223], v[204:207], v[82:85]
	v_mfma_f32_16x16x32_bf16 v[86:89], v[228:231], v[204:207], v[86:89]
	v_mfma_f32_16x16x32_bf16 v[66:69], v[220:223], v[212:215], v[66:69]
	v_mfma_f32_16x16x32_bf16 v[70:73], v[228:231], v[212:215], v[70:73]
	s_barrier
	s_mov_b32 m0, s26
	v_lshl_add_u64 v[232:233], s[4:5], 0, v[130:131]
	ds_read_b128 v[164:167], v146 offset:16384
	ds_read_b128 v[168:171], v146 offset:17408
	ds_read_b128 v[172:175], v146 offset:18432
	ds_read_b128 v[176:179], v146 offset:19456
	ds_read_b128 v[180:183], v146 offset:20480
	ds_read_b128 v[204:207], v146 offset:21504
	ds_read_b128 v[208:211], v146 offset:22528
	ds_read_b128 v[212:215], v146 offset:23552
	global_load_lds_dwordx4 v[232:233], off
	v_lshl_add_u64 v[234:235], s[4:5], 0, v[134:135]
	s_mov_b32 m0, s27
	s_nop 0
	global_load_lds_dwordx4 v[234:235], off
	s_barrier
	s_waitcnt lgkmcnt(0)
	v_mfma_f32_16x16x32_bf16 v[62:65], v[148:151], v[164:167], v[62:65]
	v_mfma_f32_16x16x32_bf16 v[58:61], v[156:159], v[164:167], v[58:61]
	v_mfma_f32_16x16x32_bf16 v[46:49], v[148:151], v[172:175], v[46:49]
	v_mfma_f32_16x16x32_bf16 v[42:45], v[156:159], v[172:175], v[42:45]
	v_mfma_f32_16x16x32_bf16 v[30:33], v[148:151], v[180:183], v[30:33]
	v_mfma_f32_16x16x32_bf16 v[26:29], v[156:159], v[180:183], v[26:29]
	v_mfma_f32_16x16x32_bf16 v[14:17], v[148:151], v[208:211], v[14:17]
	v_mfma_f32_16x16x32_bf16 v[10:13], v[156:159], v[208:211], v[10:13]
	v_mfma_f32_16x16x32_bf16 v[62:65], v[152:155], v[168:171], v[62:65]
	v_mfma_f32_16x16x32_bf16 v[58:61], v[160:163], v[168:171], v[58:61]
	v_mfma_f32_16x16x32_bf16 v[46:49], v[152:155], v[176:179], v[46:49]
	v_mfma_f32_16x16x32_bf16 v[42:45], v[160:163], v[176:179], v[42:45]
	v_mfma_f32_16x16x32_bf16 v[30:33], v[152:155], v[204:207], v[30:33]
	v_mfma_f32_16x16x32_bf16 v[26:29], v[160:163], v[204:207], v[26:29]
	v_mfma_f32_16x16x32_bf16 v[14:17], v[152:155], v[212:215], v[14:17]
	v_mfma_f32_16x16x32_bf16 v[10:13], v[160:163], v[212:215], v[10:13]
	s_barrier
	s_add_u32 s16, s16, s92
	s_addc_u32 s17, s17, 0
	s_add_i32 s65, s66, s24
	v_lshl_add_u64 v[236:237], s[16:17], 0, v[132:133]
	s_mov_b32 m0, s65
	v_lshl_add_u64 v[238:239], s[16:17], 0, v[136:137]
	global_load_lds_dwordx4 v[236:237], off
	s_add_i32 m0, s65, 0x2000
	s_nop 0
	global_load_lds_dwordx4 v[238:239], off
	s_waitcnt vmcnt(6)
	s_barrier
	v_mfma_f32_16x16x32_bf16 v[50:53], v[216:219], v[164:167], v[50:53]
	v_mfma_f32_16x16x32_bf16 v[54:57], v[224:227], v[164:167], v[54:57]
	v_mfma_f32_16x16x32_bf16 v[34:37], v[216:219], v[172:175], v[34:37]
	v_mfma_f32_16x16x32_bf16 v[38:41], v[224:227], v[172:175], v[38:41]
	v_mfma_f32_16x16x32_bf16 v[18:21], v[216:219], v[180:183], v[18:21]
	v_mfma_f32_16x16x32_bf16 v[22:25], v[224:227], v[180:183], v[22:25]
	v_mfma_f32_16x16x32_bf16 v[6:9], v[216:219], v[208:211], v[6:9]
	v_mfma_f32_16x16x32_bf16 v[2:5], v[224:227], v[208:211], v[2:5]
	v_mfma_f32_16x16x32_bf16 v[50:53], v[220:223], v[168:171], v[50:53]
	v_mfma_f32_16x16x32_bf16 v[54:57], v[228:231], v[168:171], v[54:57]
	v_mfma_f32_16x16x32_bf16 v[34:37], v[220:223], v[176:179], v[34:37]
	v_mfma_f32_16x16x32_bf16 v[38:41], v[228:231], v[176:179], v[38:41]
	v_mfma_f32_16x16x32_bf16 v[18:21], v[220:223], v[204:207], v[18:21]
	v_mfma_f32_16x16x32_bf16 v[22:25], v[228:231], v[204:207], v[22:25]
	v_mfma_f32_16x16x32_bf16 v[6:9], v[220:223], v[212:215], v[6:9]
	v_mfma_f32_16x16x32_bf16 v[2:5], v[228:231], v[212:215], v[2:5]
	s_barrier
	s_add_i32 s16, 0, 0x18000
	v_add_u32_e32 v147, s16, v145
	ds_read_b128 v[148:151], v147
	ds_read_b128 v[152:155], v147 offset:1024
	ds_read_b128 v[156:159], v147 offset:2048
	ds_read_b128 v[160:163], v147 offset:3072
	s_add_u32 s4, s4, s92
	s_addc_u32 s5, s5, 0
	s_mov_b32 m0, s28
	v_lshl_add_u64 v[216:217], s[4:5], 0, v[130:131]
	ds_read_b128 v[164:167], v146 offset:32768
	ds_read_b128 v[168:171], v146 offset:33792
	ds_read_b128 v[172:175], v146 offset:34816
	ds_read_b128 v[176:179], v146 offset:35840
	ds_read_b128 v[180:183], v146 offset:36864
	ds_read_b128 v[204:207], v146 offset:37888
	ds_read_b128 v[208:211], v146 offset:38912
	ds_read_b128 v[212:215], v146 offset:39936
	global_load_lds_dwordx4 v[216:217], off
	v_lshl_add_u64 v[216:217], s[4:5], 0, v[134:135]
	s_mov_b32 m0, s29
	s_nop 0
	global_load_lds_dwordx4 v[216:217], off
	s_waitcnt lgkmcnt(8)
	s_barrier
	s_waitcnt lgkmcnt(0)
	v_mfma_f32_16x16x32_bf16 v[126:129], v[148:151], v[164:167], v[126:129]
	v_mfma_f32_16x16x32_bf16 v[122:125], v[156:159], v[164:167], v[122:125]
	v_mfma_f32_16x16x32_bf16 v[110:113], v[148:151], v[172:175], v[110:113]
	v_mfma_f32_16x16x32_bf16 v[106:109], v[156:159], v[172:175], v[106:109]
	v_mfma_f32_16x16x32_bf16 v[94:97], v[148:151], v[180:183], v[94:97]
	v_mfma_f32_16x16x32_bf16 v[90:93], v[156:159], v[180:183], v[90:93]
	v_mfma_f32_16x16x32_bf16 v[78:81], v[148:151], v[208:211], v[78:81]
	v_mfma_f32_16x16x32_bf16 v[74:77], v[156:159], v[208:211], v[74:77]
	v_mfma_f32_16x16x32_bf16 v[126:129], v[152:155], v[168:171], v[126:129]
	v_mfma_f32_16x16x32_bf16 v[122:125], v[160:163], v[168:171], v[122:125]
	v_mfma_f32_16x16x32_bf16 v[110:113], v[152:155], v[176:179], v[110:113]
	v_mfma_f32_16x16x32_bf16 v[106:109], v[160:163], v[176:179], v[106:109]
	v_mfma_f32_16x16x32_bf16 v[94:97], v[152:155], v[204:207], v[94:97]
	v_mfma_f32_16x16x32_bf16 v[90:93], v[160:163], v[204:207], v[90:93]
	v_mfma_f32_16x16x32_bf16 v[78:81], v[152:155], v[212:215], v[78:81]
	v_mfma_f32_16x16x32_bf16 v[74:77], v[160:163], v[212:215], v[74:77]
	s_barrier
	s_add_i32 s4, 0, 0x1c000
	s_add_i32 s5, s16, s24
	v_add_u32_e32 v147, s4, v145
	v_lshl_add_u64 v[142:143], v[142:143], 0, s[6:7]
	s_mov_b32 m0, s5
	ds_read_b128 v[216:219], v147
	ds_read_b128 v[220:223], v147 offset:1024
	ds_read_b128 v[224:227], v147 offset:2048
	ds_read_b128 v[228:231], v147 offset:3072
	global_load_lds_dwordx4 v[142:143], off
	v_lshl_add_u64 v[142:143], v[184:185], 0, s[6:7]
	s_add_i32 m0, s5, 0x2000
	s_nop 0
	global_load_lds_dwordx4 v[142:143], off
	s_barrier
	s_waitcnt lgkmcnt(0)
	v_mfma_f32_16x16x32_bf16 v[114:117], v[216:219], v[164:167], v[114:117]
	v_mfma_f32_16x16x32_bf16 v[118:121], v[224:227], v[164:167], v[118:121]
	v_mfma_f32_16x16x32_bf16 v[98:101], v[216:219], v[172:175], v[98:101]
	v_mfma_f32_16x16x32_bf16 v[102:105], v[224:227], v[172:175], v[102:105]
	v_mfma_f32_16x16x32_bf16 v[82:85], v[216:219], v[180:183], v[82:85]
	v_mfma_f32_16x16x32_bf16 v[86:89], v[224:227], v[180:183], v[86:89]
	v_mfma_f32_16x16x32_bf16 v[66:69], v[216:219], v[208:211], v[66:69]
	v_mfma_f32_16x16x32_bf16 v[70:73], v[224:227], v[208:211], v[70:73]
	v_mfma_f32_16x16x32_bf16 v[114:117], v[220:223], v[168:171], v[114:117]
	v_mfma_f32_16x16x32_bf16 v[118:121], v[228:231], v[168:171], v[118:121]
	v_mfma_f32_16x16x32_bf16 v[98:101], v[220:223], v[176:179], v[98:101]
	v_mfma_f32_16x16x32_bf16 v[102:105], v[228:231], v[176:179], v[102:105]
	v_mfma_f32_16x16x32_bf16 v[82:85], v[220:223], v[204:207], v[82:85]
	v_mfma_f32_16x16x32_bf16 v[86:89], v[228:231], v[204:207], v[86:89]
	v_mfma_f32_16x16x32_bf16 v[66:69], v[220:223], v[212:215], v[66:69]
	v_mfma_f32_16x16x32_bf16 v[70:73], v[228:231], v[212:215], v[70:73]
	s_barrier
	s_mov_b32 m0, s35
	v_lshl_add_u64 v[142:143], v[232:233], 0, s[6:7]
	ds_read_b128 v[164:167], v146 offset:49152
	ds_read_b128 v[168:171], v146 offset:50176
	ds_read_b128 v[172:175], v146 offset:51200
	ds_read_b128 v[176:179], v146 offset:52224
	ds_read_b128 v[180:183], v146 offset:53248
	ds_read_b128 v[204:207], v146 offset:54272
	ds_read_b128 v[208:211], v146 offset:55296
	ds_read_b128 v[212:215], v146 offset:56320
	global_load_lds_dwordx4 v[142:143], off
	v_lshl_add_u64 v[142:143], v[234:235], 0, s[6:7]
	s_mov_b32 m0, s40
	s_nop 0
	global_load_lds_dwordx4 v[142:143], off
	s_barrier
	s_waitcnt lgkmcnt(0)
	v_mfma_f32_16x16x32_bf16 v[62:65], v[148:151], v[164:167], v[62:65]
	v_mfma_f32_16x16x32_bf16 v[58:61], v[156:159], v[164:167], v[58:61]
	v_mfma_f32_16x16x32_bf16 v[46:49], v[148:151], v[172:175], v[46:49]
	v_mfma_f32_16x16x32_bf16 v[42:45], v[156:159], v[172:175], v[42:45]
	v_mfma_f32_16x16x32_bf16 v[30:33], v[148:151], v[180:183], v[30:33]
	v_mfma_f32_16x16x32_bf16 v[26:29], v[156:159], v[180:183], v[26:29]
	v_mfma_f32_16x16x32_bf16 v[14:17], v[148:151], v[208:211], v[14:17]
	v_mfma_f32_16x16x32_bf16 v[10:13], v[156:159], v[208:211], v[10:13]
	v_mfma_f32_16x16x32_bf16 v[62:65], v[152:155], v[168:171], v[62:65]
	v_mfma_f32_16x16x32_bf16 v[58:61], v[160:163], v[168:171], v[58:61]
	v_mfma_f32_16x16x32_bf16 v[46:49], v[152:155], v[176:179], v[46:49]
	v_mfma_f32_16x16x32_bf16 v[42:45], v[160:163], v[176:179], v[42:45]
	v_mfma_f32_16x16x32_bf16 v[30:33], v[152:155], v[204:207], v[30:33]
	v_mfma_f32_16x16x32_bf16 v[26:29], v[160:163], v[204:207], v[26:29]
	v_mfma_f32_16x16x32_bf16 v[14:17], v[152:155], v[212:215], v[14:17]
	v_mfma_f32_16x16x32_bf16 v[10:13], v[160:163], v[212:215], v[10:13]
	s_barrier
	s_add_i32 s4, s4, s24
	v_lshl_add_u64 v[142:143], v[236:237], 0, s[6:7]
	s_mov_b32 m0, s4
	s_nop 0
	global_load_lds_dwordx4 v[142:143], off
	v_lshl_add_u64 v[142:143], v[238:239], 0, s[6:7]
	s_add_i32 m0, s4, 0x2000
	s_nop 0
	global_load_lds_dwordx4 v[142:143], off
	s_add_u32 s0, s0, 0x100
	s_addc_u32 s1, s1, 0
	s_add_u32 s47, s47, 0x100
	s_addc_u32 s48, s48, 0
	s_cmp_ge_u32 s49, s30
	s_mov_b32 s4, s49
	s_waitcnt vmcnt(6)
	s_barrier
	v_mfma_f32_16x16x32_bf16 v[50:53], v[216:219], v[164:167], v[50:53]
	v_mfma_f32_16x16x32_bf16 v[54:57], v[224:227], v[164:167], v[54:57]
	v_mfma_f32_16x16x32_bf16 v[34:37], v[216:219], v[172:175], v[34:37]
	v_mfma_f32_16x16x32_bf16 v[38:41], v[224:227], v[172:175], v[38:41]
	v_mfma_f32_16x16x32_bf16 v[18:21], v[216:219], v[180:183], v[18:21]
	v_mfma_f32_16x16x32_bf16 v[22:25], v[224:227], v[180:183], v[22:25]
	v_mfma_f32_16x16x32_bf16 v[6:9], v[216:219], v[208:211], v[6:9]
	v_mfma_f32_16x16x32_bf16 v[2:5], v[224:227], v[208:211], v[2:5]
	v_mfma_f32_16x16x32_bf16 v[50:53], v[220:223], v[168:171], v[50:53]
	v_mfma_f32_16x16x32_bf16 v[54:57], v[228:231], v[168:171], v[54:57]
	v_mfma_f32_16x16x32_bf16 v[34:37], v[220:223], v[176:179], v[34:37]
	v_mfma_f32_16x16x32_bf16 v[38:41], v[228:231], v[176:179], v[38:41]
	v_mfma_f32_16x16x32_bf16 v[18:21], v[220:223], v[204:207], v[18:21]
	v_mfma_f32_16x16x32_bf16 v[22:25], v[228:231], v[204:207], v[22:25]
	v_mfma_f32_16x16x32_bf16 v[6:9], v[220:223], v[212:215], v[6:9]
	v_mfma_f32_16x16x32_bf16 v[2:5], v[228:231], v[212:215], v[2:5]
	s_barrier
	s_cbranch_scc0 .LBB0_253

.LBB0_281:
	s_add_u32 s0, s0, 0x80
	s_addc_u32 s1, s1, 0
	s_add_u32 s20, s4, 0x100
	s_addc_u32 s21, s5, 0
	s_mov_b32 s4, 0
	s_waitcnt lgkmcnt(0)
	s_add_i32 s22, s4, 2
	s_add_u32 s10, s0, 0x80
	s_addc_u32 s5, s1, 0
	s_add_i32 s23, 0, 0x10000
	v_add_u32_e32 v154, s23, v165
	ds_read_b128 v[142:145], v154
	ds_read_b128 v[146:149], v154 offset:1024
	ds_read_b128 v[150:153], v154 offset:2048
	ds_read_b128 v[154:157], v154 offset:3072
	s_cmp_eq_u32 s44, s4
	s_cselect_b32 s4, s16, s10
	s_cselect_b32 s5, s17, s5
	s_cselect_b32 s11, s13, s21
	s_cselect_b32 s10, s12, s20
	v_lshl_add_u64 v[162:163], s[0:1], 0, v[138:139]
	s_add_i32 m0, s29, 0xc000
	ds_read_b128 v[158:161], v166
	ds_read_b128 v[168:171], v166 offset:1024
	ds_read_b128 v[172:175], v166 offset:2048
	ds_read_b128 v[176:179], v166 offset:3072
	ds_read_b128 v[180:183], v166 offset:4096
	ds_read_b128 v[204:207], v166 offset:5120
	ds_read_b128 v[208:211], v166 offset:6144
	ds_read_b128 v[212:215], v166 offset:7168
	global_load_lds_dwordx4 v[162:163], off
	v_lshl_add_u64 v[162:163], s[0:1], 0, v[140:141]
	s_add_i32 m0, s29, 0xe000
	s_nop 0
	global_load_lds_dwordx4 v[162:163], off
	s_waitcnt lgkmcnt(8)
	s_barrier
	s_waitcnt lgkmcnt(0)
	v_mfma_f32_16x16x32_bf16 v[126:129], v[142:145], v[158:161], 0
	v_mfma_f32_16x16x32_bf16 v[122:125], v[150:153], v[158:161], 0
	v_mfma_f32_16x16x32_bf16 v[110:113], v[142:145], v[172:175], 0
	v_mfma_f32_16x16x32_bf16 v[106:109], v[150:153], v[172:175], 0
	v_mfma_f32_16x16x32_bf16 v[94:97], v[142:145], v[180:183], 0
	v_mfma_f32_16x16x32_bf16 v[90:93], v[150:153], v[180:183], 0
	v_mfma_f32_16x16x32_bf16 v[78:81], v[142:145], v[208:211], 0
	v_mfma_f32_16x16x32_bf16 v[74:77], v[150:153], v[208:211], 0
	v_mfma_f32_16x16x32_bf16 v[126:129], v[146:149], v[168:171], v[126:129]
	v_mfma_f32_16x16x32_bf16 v[122:125], v[154:157], v[168:171], v[122:125]
	v_mfma_f32_16x16x32_bf16 v[110:113], v[146:149], v[176:179], v[110:113]
	v_mfma_f32_16x16x32_bf16 v[106:109], v[154:157], v[176:179], v[106:109]
	v_mfma_f32_16x16x32_bf16 v[94:97], v[146:149], v[204:207], v[94:97]
	v_mfma_f32_16x16x32_bf16 v[90:93], v[154:157], v[204:207], v[90:93]
	v_mfma_f32_16x16x32_bf16 v[78:81], v[146:149], v[212:215], v[78:81]
	v_mfma_f32_16x16x32_bf16 v[74:77], v[154:157], v[212:215], v[74:77]
	s_barrier
	s_add_i32 s24, 0, 0x14000
	v_add_u32_e32 v162, s24, v165
	s_add_i32 s23, s23, s28
	ds_read_b128 v[216:219], v162
	ds_read_b128 v[220:223], v162 offset:1024
	ds_read_b128 v[224:227], v162 offset:2048
	ds_read_b128 v[228:231], v162 offset:3072
	v_lshl_add_u64 v[162:163], s[10:11], 0, v[132:133]
	s_mov_b32 m0, s23
	v_lshl_add_u64 v[184:185], s[10:11], 0, v[136:137]
	global_load_lds_dwordx4 v[162:163], off
	s_add_i32 m0, s23, 0x2000
	s_nop 0
	global_load_lds_dwordx4 v[184:185], off
	s_barrier
	s_waitcnt lgkmcnt(0)
	v_mfma_f32_16x16x32_bf16 v[118:121], v[216:219], v[158:161], 0
	v_mfma_f32_16x16x32_bf16 v[114:117], v[224:227], v[158:161], 0
	v_mfma_f32_16x16x32_bf16 v[102:105], v[216:219], v[172:175], 0
	v_mfma_f32_16x16x32_bf16 v[98:101], v[224:227], v[172:175], 0
	v_mfma_f32_16x16x32_bf16 v[86:89], v[216:219], v[180:183], 0
	v_mfma_f32_16x16x32_bf16 v[82:85], v[224:227], v[180:183], 0
	v_mfma_f32_16x16x32_bf16 v[70:73], v[216:219], v[208:211], 0
	v_mfma_f32_16x16x32_bf16 v[66:69], v[224:227], v[208:211], 0
	v_mfma_f32_16x16x32_bf16 v[118:121], v[220:223], v[168:171], v[118:121]
	v_mfma_f32_16x16x32_bf16 v[114:117], v[228:231], v[168:171], v[114:117]
	v_mfma_f32_16x16x32_bf16 v[102:105], v[220:223], v[176:179], v[102:105]
	v_mfma_f32_16x16x32_bf16 v[98:101], v[228:231], v[176:179], v[98:101]
	v_mfma_f32_16x16x32_bf16 v[86:89], v[220:223], v[204:207], v[86:89]
	v_mfma_f32_16x16x32_bf16 v[82:85], v[228:231], v[204:207], v[82:85]
	v_mfma_f32_16x16x32_bf16 v[70:73], v[220:223], v[212:215], v[70:73]
	v_mfma_f32_16x16x32_bf16 v[66:69], v[228:231], v[212:215], v[66:69]
	s_barrier
	s_mov_b32 m0, s29
	v_lshl_add_u64 v[232:233], s[4:5], 0, v[130:131]
	ds_read_b128 v[158:161], v166 offset:16384
	ds_read_b128 v[168:171], v166 offset:17408
	ds_read_b128 v[172:175], v166 offset:18432
	ds_read_b128 v[176:179], v166 offset:19456
	ds_read_b128 v[180:183], v166 offset:20480
	ds_read_b128 v[204:207], v166 offset:21504
	ds_read_b128 v[208:211], v166 offset:22528
	ds_read_b128 v[212:215], v166 offset:23552
	global_load_lds_dwordx4 v[232:233], off
	v_lshl_add_u64 v[234:235], s[4:5], 0, v[134:135]
	s_mov_b32 m0, s30
	s_nop 0
	global_load_lds_dwordx4 v[234:235], off
	s_barrier
	s_waitcnt lgkmcnt(0)
	v_mfma_f32_16x16x32_bf16 v[62:65], v[142:145], v[158:161], 0
	v_mfma_f32_16x16x32_bf16 v[58:61], v[150:153], v[158:161], 0
	v_mfma_f32_16x16x32_bf16 v[46:49], v[142:145], v[172:175], 0
	v_mfma_f32_16x16x32_bf16 v[42:45], v[150:153], v[172:175], 0
	v_mfma_f32_16x16x32_bf16 v[30:33], v[142:145], v[180:183], 0
	v_mfma_f32_16x16x32_bf16 v[26:29], v[150:153], v[180:183], 0
	v_mfma_f32_16x16x32_bf16 v[14:17], v[142:145], v[208:211], 0
	v_mfma_f32_16x16x32_bf16 v[10:13], v[150:153], v[208:211], 0
	v_mfma_f32_16x16x32_bf16 v[62:65], v[146:149], v[168:171], v[62:65]
	v_mfma_f32_16x16x32_bf16 v[58:61], v[154:157], v[168:171], v[58:61]
	v_mfma_f32_16x16x32_bf16 v[46:49], v[146:149], v[176:179], v[46:49]
	v_mfma_f32_16x16x32_bf16 v[42:45], v[154:157], v[176:179], v[42:45]
	v_mfma_f32_16x16x32_bf16 v[30:33], v[146:149], v[204:207], v[30:33]
	v_mfma_f32_16x16x32_bf16 v[26:29], v[154:157], v[204:207], v[26:29]
	v_mfma_f32_16x16x32_bf16 v[14:17], v[146:149], v[212:215], v[14:17]
	v_mfma_f32_16x16x32_bf16 v[10:13], v[154:157], v[212:215], v[10:13]
	s_barrier
	s_add_u32 s10, s10, s92
	s_addc_u32 s11, s11, 0
	s_add_i32 s23, s24, s28
	v_lshl_add_u64 v[236:237], s[10:11], 0, v[132:133]
	s_mov_b32 m0, s23
	v_lshl_add_u64 v[238:239], s[10:11], 0, v[136:137]
	global_load_lds_dwordx4 v[236:237], off
	s_add_i32 m0, s23, 0x2000
	s_nop 0
	global_load_lds_dwordx4 v[238:239], off
	s_waitcnt vmcnt(6)
	s_barrier
	v_mfma_f32_16x16x32_bf16 v[54:57], v[216:219], v[158:161], 0
	v_mfma_f32_16x16x32_bf16 v[50:53], v[224:227], v[158:161], 0
	v_mfma_f32_16x16x32_bf16 v[38:41], v[216:219], v[172:175], 0
	v_mfma_f32_16x16x32_bf16 v[34:37], v[224:227], v[172:175], 0
	v_mfma_f32_16x16x32_bf16 v[22:25], v[216:219], v[180:183], 0
	v_mfma_f32_16x16x32_bf16 v[18:21], v[224:227], v[180:183], 0
	v_mfma_f32_16x16x32_bf16 v[6:9], v[216:219], v[208:211], 0
	v_mfma_f32_16x16x32_bf16 v[2:5], v[224:227], v[208:211], 0
	v_mfma_f32_16x16x32_bf16 v[54:57], v[220:223], v[168:171], v[54:57]
	v_mfma_f32_16x16x32_bf16 v[50:53], v[228:231], v[168:171], v[50:53]
	v_mfma_f32_16x16x32_bf16 v[38:41], v[220:223], v[176:179], v[38:41]
	v_mfma_f32_16x16x32_bf16 v[34:37], v[228:231], v[176:179], v[34:37]
	v_mfma_f32_16x16x32_bf16 v[22:25], v[220:223], v[204:207], v[22:25]
	v_mfma_f32_16x16x32_bf16 v[18:21], v[228:231], v[204:207], v[18:21]
	v_mfma_f32_16x16x32_bf16 v[6:9], v[220:223], v[212:215], v[6:9]
	v_mfma_f32_16x16x32_bf16 v[2:5], v[228:231], v[212:215], v[2:5]
	s_barrier
	s_add_i32 s10, 0, 0x18000
	v_add_u32_e32 v154, s10, v165
	ds_read_b128 v[142:145], v154
	ds_read_b128 v[146:149], v154 offset:1024
	ds_read_b128 v[150:153], v154 offset:2048
	ds_read_b128 v[154:157], v154 offset:3072
	s_add_u32 s4, s4, s92
	s_addc_u32 s5, s5, 0
	s_mov_b32 m0, s31
	v_lshl_add_u64 v[216:217], s[4:5], 0, v[130:131]
	ds_read_b128 v[158:161], v166 offset:32768
	ds_read_b128 v[168:171], v166 offset:33792
	ds_read_b128 v[172:175], v166 offset:34816
	ds_read_b128 v[176:179], v166 offset:35840
	ds_read_b128 v[180:183], v166 offset:36864
	ds_read_b128 v[204:207], v166 offset:37888
	ds_read_b128 v[208:211], v166 offset:38912
	ds_read_b128 v[212:215], v166 offset:39936
	global_load_lds_dwordx4 v[216:217], off
	v_lshl_add_u64 v[216:217], s[4:5], 0, v[134:135]
	s_mov_b32 m0, s34
	s_nop 0
	global_load_lds_dwordx4 v[216:217], off
	s_waitcnt lgkmcnt(8)
	s_barrier
	s_waitcnt lgkmcnt(0)
	v_mfma_f32_16x16x32_bf16 v[126:129], v[142:145], v[158:161], v[126:129]
	v_mfma_f32_16x16x32_bf16 v[122:125], v[150:153], v[158:161], v[122:125]
	v_mfma_f32_16x16x32_bf16 v[110:113], v[142:145], v[172:175], v[110:113]
	v_mfma_f32_16x16x32_bf16 v[106:109], v[150:153], v[172:175], v[106:109]
	v_mfma_f32_16x16x32_bf16 v[94:97], v[142:145], v[180:183], v[94:97]
	v_mfma_f32_16x16x32_bf16 v[90:93], v[150:153], v[180:183], v[90:93]
	v_mfma_f32_16x16x32_bf16 v[78:81], v[142:145], v[208:211], v[78:81]
	v_mfma_f32_16x16x32_bf16 v[74:77], v[150:153], v[208:211], v[74:77]
	v_mfma_f32_16x16x32_bf16 v[126:129], v[146:149], v[168:171], v[126:129]
	v_mfma_f32_16x16x32_bf16 v[122:125], v[154:157], v[168:171], v[122:125]
	v_mfma_f32_16x16x32_bf16 v[110:113], v[146:149], v[176:179], v[110:113]
	v_mfma_f32_16x16x32_bf16 v[106:109], v[154:157], v[176:179], v[106:109]
	v_mfma_f32_16x16x32_bf16 v[94:97], v[146:149], v[204:207], v[94:97]
	v_mfma_f32_16x16x32_bf16 v[90:93], v[154:157], v[204:207], v[90:93]
	v_mfma_f32_16x16x32_bf16 v[78:81], v[146:149], v[212:215], v[78:81]
	v_mfma_f32_16x16x32_bf16 v[74:77], v[154:157], v[212:215], v[74:77]
	s_barrier
	s_add_i32 s4, 0, 0x1c000
	s_add_i32 s5, s10, s28
	v_add_u32_e32 v167, s4, v165
	v_lshl_add_u64 v[162:163], v[162:163], 0, s[6:7]
	s_mov_b32 m0, s5
	ds_read_b128 v[216:219], v167
	ds_read_b128 v[220:223], v167 offset:1024
	ds_read_b128 v[224:227], v167 offset:2048
	ds_read_b128 v[228:231], v167 offset:3072
	global_load_lds_dwordx4 v[162:163], off
	v_lshl_add_u64 v[162:163], v[184:185], 0, s[6:7]
	s_add_i32 m0, s5, 0x2000
	s_nop 0
	global_load_lds_dwordx4 v[162:163], off
	s_barrier
	s_waitcnt lgkmcnt(0)
	v_mfma_f32_16x16x32_bf16 v[118:121], v[216:219], v[158:161], v[118:121]
	v_mfma_f32_16x16x32_bf16 v[114:117], v[224:227], v[158:161], v[114:117]
	v_mfma_f32_16x16x32_bf16 v[102:105], v[216:219], v[172:175], v[102:105]
	v_mfma_f32_16x16x32_bf16 v[98:101], v[224:227], v[172:175], v[98:101]
	v_mfma_f32_16x16x32_bf16 v[86:89], v[216:219], v[180:183], v[86:89]
	v_mfma_f32_16x16x32_bf16 v[82:85], v[224:227], v[180:183], v[82:85]
	v_mfma_f32_16x16x32_bf16 v[70:73], v[216:219], v[208:211], v[70:73]
	v_mfma_f32_16x16x32_bf16 v[66:69], v[224:227], v[208:211], v[66:69]
	v_mfma_f32_16x16x32_bf16 v[118:121], v[220:223], v[168:171], v[118:121]
	v_mfma_f32_16x16x32_bf16 v[114:117], v[228:231], v[168:171], v[114:117]
	v_mfma_f32_16x16x32_bf16 v[102:105], v[220:223], v[176:179], v[102:105]
	v_mfma_f32_16x16x32_bf16 v[98:101], v[228:231], v[176:179], v[98:101]
	v_mfma_f32_16x16x32_bf16 v[86:89], v[220:223], v[204:207], v[86:89]
	v_mfma_f32_16x16x32_bf16 v[82:85], v[228:231], v[204:207], v[82:85]
	v_mfma_f32_16x16x32_bf16 v[70:73], v[220:223], v[212:215], v[70:73]
	v_mfma_f32_16x16x32_bf16 v[66:69], v[228:231], v[212:215], v[66:69]
	s_barrier
	s_mov_b32 m0, s42
	v_lshl_add_u64 v[162:163], v[232:233], 0, s[6:7]
	ds_read_b128 v[158:161], v166 offset:49152
	ds_read_b128 v[168:171], v166 offset:50176
	ds_read_b128 v[172:175], v166 offset:51200
	ds_read_b128 v[176:179], v166 offset:52224
	ds_read_b128 v[180:183], v166 offset:53248
	ds_read_b128 v[204:207], v166 offset:54272
	ds_read_b128 v[208:211], v166 offset:55296
	ds_read_b128 v[212:215], v166 offset:56320
	global_load_lds_dwordx4 v[162:163], off
	v_lshl_add_u64 v[162:163], v[234:235], 0, s[6:7]
	s_mov_b32 m0, s43
	s_nop 0
	global_load_lds_dwordx4 v[162:163], off
	s_barrier
	s_waitcnt lgkmcnt(0)
	v_mfma_f32_16x16x32_bf16 v[62:65], v[142:145], v[158:161], v[62:65]
	v_mfma_f32_16x16x32_bf16 v[58:61], v[150:153], v[158:161], v[58:61]
	v_mfma_f32_16x16x32_bf16 v[46:49], v[142:145], v[172:175], v[46:49]
	v_mfma_f32_16x16x32_bf16 v[42:45], v[150:153], v[172:175], v[42:45]
	v_mfma_f32_16x16x32_bf16 v[30:33], v[142:145], v[180:183], v[30:33]
	v_mfma_f32_16x16x32_bf16 v[26:29], v[150:153], v[180:183], v[26:29]
	v_mfma_f32_16x16x32_bf16 v[14:17], v[142:145], v[208:211], v[14:17]
	v_mfma_f32_16x16x32_bf16 v[10:13], v[150:153], v[208:211], v[10:13]
	v_mfma_f32_16x16x32_bf16 v[62:65], v[146:149], v[168:171], v[62:65]
	v_mfma_f32_16x16x32_bf16 v[58:61], v[154:157], v[168:171], v[58:61]
	v_mfma_f32_16x16x32_bf16 v[46:49], v[146:149], v[176:179], v[46:49]
	v_mfma_f32_16x16x32_bf16 v[42:45], v[154:157], v[176:179], v[42:45]
	v_mfma_f32_16x16x32_bf16 v[30:33], v[146:149], v[204:207], v[30:33]
	v_mfma_f32_16x16x32_bf16 v[26:29], v[154:157], v[204:207], v[26:29]
	v_mfma_f32_16x16x32_bf16 v[14:17], v[146:149], v[212:215], v[14:17]
	v_mfma_f32_16x16x32_bf16 v[10:13], v[154:157], v[212:215], v[10:13]
	s_barrier
	s_add_i32 s4, s4, s28
	v_lshl_add_u64 v[142:143], v[236:237], 0, s[6:7]
	s_mov_b32 m0, s4
	s_nop 0
	global_load_lds_dwordx4 v[142:143], off
	v_lshl_add_u64 v[142:143], v[238:239], 0, s[6:7]
	s_add_i32 m0, s4, 0x2000
	s_nop 0
	global_load_lds_dwordx4 v[142:143], off
	s_add_u32 s0, s0, 0x100
	s_addc_u32 s1, s1, 0
	s_add_u32 s20, s20, 0x100
	s_addc_u32 s21, s21, 0
	s_cmp_ge_u32 s22, s35
	s_mov_b32 s4, s22
	s_waitcnt vmcnt(6)
	s_barrier
	v_mfma_f32_16x16x32_bf16 v[54:57], v[216:219], v[158:161], v[54:57]
	v_mfma_f32_16x16x32_bf16 v[50:53], v[224:227], v[158:161], v[50:53]
	v_mfma_f32_16x16x32_bf16 v[38:41], v[216:219], v[172:175], v[38:41]
	v_mfma_f32_16x16x32_bf16 v[34:37], v[224:227], v[172:175], v[34:37]
	v_mfma_f32_16x16x32_bf16 v[22:25], v[216:219], v[180:183], v[22:25]
	v_mfma_f32_16x16x32_bf16 v[18:21], v[224:227], v[180:183], v[18:21]
	v_mfma_f32_16x16x32_bf16 v[6:9], v[216:219], v[208:211], v[6:9]
	v_mfma_f32_16x16x32_bf16 v[2:5], v[224:227], v[208:211], v[2:5]
	v_mfma_f32_16x16x32_bf16 v[54:57], v[220:223], v[168:171], v[54:57]
	v_mfma_f32_16x16x32_bf16 v[50:53], v[228:231], v[168:171], v[50:53]
	v_mfma_f32_16x16x32_bf16 v[38:41], v[220:223], v[176:179], v[38:41]
	v_mfma_f32_16x16x32_bf16 v[34:37], v[228:231], v[176:179], v[34:37]
	v_mfma_f32_16x16x32_bf16 v[22:25], v[220:223], v[204:207], v[22:25]
	v_mfma_f32_16x16x32_bf16 v[18:21], v[228:231], v[204:207], v[18:21]
	v_mfma_f32_16x16x32_bf16 v[6:9], v[220:223], v[212:215], v[6:9]
	v_mfma_f32_16x16x32_bf16 v[2:5], v[228:231], v[212:215], v[2:5]
	s_barrier
	s_cbranch_scc1 .Lkexit_282
.LBB0_282:
	s_add_i32 s22, s4, 2
	s_add_u32 s10, s0, 0x80
	s_addc_u32 s5, s1, 0
	s_add_i32 s23, 0, 0x10000
	v_add_u32_e32 v154, s23, v165
	ds_read_b128 v[142:145], v154
	ds_read_b128 v[146:149], v154 offset:1024
	ds_read_b128 v[150:153], v154 offset:2048
	ds_read_b128 v[154:157], v154 offset:3072
	s_cmp_eq_u32 s44, s4
	s_cselect_b32 s4, s16, s10
	s_cselect_b32 s5, s17, s5
	s_cselect_b32 s11, s13, s21
	s_cselect_b32 s10, s12, s20
	v_lshl_add_u64 v[162:163], s[0:1], 0, v[138:139]
	s_add_i32 m0, s29, 0xc000
	ds_read_b128 v[158:161], v166
	ds_read_b128 v[168:171], v166 offset:1024
	ds_read_b128 v[172:175], v166 offset:2048
	ds_read_b128 v[176:179], v166 offset:3072
	ds_read_b128 v[180:183], v166 offset:4096
	ds_read_b128 v[204:207], v166 offset:5120
	ds_read_b128 v[208:211], v166 offset:6144
	ds_read_b128 v[212:215], v166 offset:7168
	global_load_lds_dwordx4 v[162:163], off
	v_lshl_add_u64 v[162:163], s[0:1], 0, v[140:141]
	s_add_i32 m0, s29, 0xe000
	s_nop 0
	global_load_lds_dwordx4 v[162:163], off
	s_waitcnt lgkmcnt(8)
	s_barrier
	s_waitcnt lgkmcnt(0)
	v_mfma_f32_16x16x32_bf16 v[126:129], v[142:145], v[158:161], v[126:129]
	v_mfma_f32_16x16x32_bf16 v[122:125], v[150:153], v[158:161], v[122:125]
	v_mfma_f32_16x16x32_bf16 v[110:113], v[142:145], v[172:175], v[110:113]
	v_mfma_f32_16x16x32_bf16 v[106:109], v[150:153], v[172:175], v[106:109]
	v_mfma_f32_16x16x32_bf16 v[94:97], v[142:145], v[180:183], v[94:97]
	v_mfma_f32_16x16x32_bf16 v[90:93], v[150:153], v[180:183], v[90:93]
	v_mfma_f32_16x16x32_bf16 v[78:81], v[142:145], v[208:211], v[78:81]
	v_mfma_f32_16x16x32_bf16 v[74:77], v[150:153], v[208:211], v[74:77]
	v_mfma_f32_16x16x32_bf16 v[126:129], v[146:149], v[168:171], v[126:129]
	v_mfma_f32_16x16x32_bf16 v[122:125], v[154:157], v[168:171], v[122:125]
	v_mfma_f32_16x16x32_bf16 v[110:113], v[146:149], v[176:179], v[110:113]
	v_mfma_f32_16x16x32_bf16 v[106:109], v[154:157], v[176:179], v[106:109]
	v_mfma_f32_16x16x32_bf16 v[94:97], v[146:149], v[204:207], v[94:97]
	v_mfma_f32_16x16x32_bf16 v[90:93], v[154:157], v[204:207], v[90:93]
	v_mfma_f32_16x16x32_bf16 v[78:81], v[146:149], v[212:215], v[78:81]
	v_mfma_f32_16x16x32_bf16 v[74:77], v[154:157], v[212:215], v[74:77]
	s_barrier
	s_add_i32 s24, 0, 0x14000
	v_add_u32_e32 v162, s24, v165
	s_add_i32 s23, s23, s28
	ds_read_b128 v[216:219], v162
	ds_read_b128 v[220:223], v162 offset:1024
	ds_read_b128 v[224:227], v162 offset:2048
	ds_read_b128 v[228:231], v162 offset:3072
	v_lshl_add_u64 v[162:163], s[10:11], 0, v[132:133]
	s_mov_b32 m0, s23
	v_lshl_add_u64 v[184:185], s[10:11], 0, v[136:137]
	global_load_lds_dwordx4 v[162:163], off
	s_add_i32 m0, s23, 0x2000
	s_nop 0
	global_load_lds_dwordx4 v[184:185], off
	s_barrier
	s_waitcnt lgkmcnt(0)
	v_mfma_f32_16x16x32_bf16 v[118:121], v[216:219], v[158:161], v[118:121]
	v_mfma_f32_16x16x32_bf16 v[114:117], v[224:227], v[158:161], v[114:117]
	v_mfma_f32_16x16x32_bf16 v[102:105], v[216:219], v[172:175], v[102:105]
	v_mfma_f32_16x16x32_bf16 v[98:101], v[224:227], v[172:175], v[98:101]
	v_mfma_f32_16x16x32_bf16 v[86:89], v[216:219], v[180:183], v[86:89]
	v_mfma_f32_16x16x32_bf16 v[82:85], v[224:227], v[180:183], v[82:85]
	v_mfma_f32_16x16x32_bf16 v[70:73], v[216:219], v[208:211], v[70:73]
	v_mfma_f32_16x16x32_bf16 v[66:69], v[224:227], v[208:211], v[66:69]
	v_mfma_f32_16x16x32_bf16 v[118:121], v[220:223], v[168:171], v[118:121]
	v_mfma_f32_16x16x32_bf16 v[114:117], v[228:231], v[168:171], v[114:117]
	v_mfma_f32_16x16x32_bf16 v[102:105], v[220:223], v[176:179], v[102:105]
	v_mfma_f32_16x16x32_bf16 v[98:101], v[228:231], v[176:179], v[98:101]
	v_mfma_f32_16x16x32_bf16 v[86:89], v[220:223], v[204:207], v[86:89]
	v_mfma_f32_16x16x32_bf16 v[82:85], v[228:231], v[204:207], v[82:85]
	v_mfma_f32_16x16x32_bf16 v[70:73], v[220:223], v[212:215], v[70:73]
	v_mfma_f32_16x16x32_bf16 v[66:69], v[228:231], v[212:215], v[66:69]
	s_barrier
	s_mov_b32 m0, s29
	v_lshl_add_u64 v[232:233], s[4:5], 0, v[130:131]
	ds_read_b128 v[158:161], v166 offset:16384
	ds_read_b128 v[168:171], v166 offset:17408
	ds_read_b128 v[172:175], v166 offset:18432
	ds_read_b128 v[176:179], v166 offset:19456
	ds_read_b128 v[180:183], v166 offset:20480
	ds_read_b128 v[204:207], v166 offset:21504
	ds_read_b128 v[208:211], v166 offset:22528
	ds_read_b128 v[212:215], v166 offset:23552
	global_load_lds_dwordx4 v[232:233], off
	v_lshl_add_u64 v[234:235], s[4:5], 0, v[134:135]
	s_mov_b32 m0, s30
	s_nop 0
	global_load_lds_dwordx4 v[234:235], off
	s_barrier
	s_waitcnt lgkmcnt(0)
	v_mfma_f32_16x16x32_bf16 v[62:65], v[142:145], v[158:161], v[62:65]
	v_mfma_f32_16x16x32_bf16 v[58:61], v[150:153], v[158:161], v[58:61]
	v_mfma_f32_16x16x32_bf16 v[46:49], v[142:145], v[172:175], v[46:49]
	v_mfma_f32_16x16x32_bf16 v[42:45], v[150:153], v[172:175], v[42:45]
	v_mfma_f32_16x16x32_bf16 v[30:33], v[142:145], v[180:183], v[30:33]
	v_mfma_f32_16x16x32_bf16 v[26:29], v[150:153], v[180:183], v[26:29]
	v_mfma_f32_16x16x32_bf16 v[14:17], v[142:145], v[208:211], v[14:17]
	v_mfma_f32_16x16x32_bf16 v[10:13], v[150:153], v[208:211], v[10:13]
	v_mfma_f32_16x16x32_bf16 v[62:65], v[146:149], v[168:171], v[62:65]
	v_mfma_f32_16x16x32_bf16 v[58:61], v[154:157], v[168:171], v[58:61]
	v_mfma_f32_16x16x32_bf16 v[46:49], v[146:149], v[176:179], v[46:49]
	v_mfma_f32_16x16x32_bf16 v[42:45], v[154:157], v[176:179], v[42:45]
	v_mfma_f32_16x16x32_bf16 v[30:33], v[146:149], v[204:207], v[30:33]
	v_mfma_f32_16x16x32_bf16 v[26:29], v[154:157], v[204:207], v[26:29]
	v_mfma_f32_16x16x32_bf16 v[14:17], v[146:149], v[212:215], v[14:17]
	v_mfma_f32_16x16x32_bf16 v[10:13], v[154:157], v[212:215], v[10:13]
	s_barrier
	s_add_u32 s10, s10, s92
	s_addc_u32 s11, s11, 0
	s_add_i32 s23, s24, s28
	v_lshl_add_u64 v[236:237], s[10:11], 0, v[132:133]
	s_mov_b32 m0, s23
	v_lshl_add_u64 v[238:239], s[10:11], 0, v[136:137]
	global_load_lds_dwordx4 v[236:237], off
	s_add_i32 m0, s23, 0x2000
	s_nop 0
	global_load_lds_dwordx4 v[238:239], off
	s_waitcnt vmcnt(6)
	s_barrier
	v_mfma_f32_16x16x32_bf16 v[54:57], v[216:219], v[158:161], v[54:57]
	v_mfma_f32_16x16x32_bf16 v[50:53], v[224:227], v[158:161], v[50:53]
	v_mfma_f32_16x16x32_bf16 v[38:41], v[216:219], v[172:175], v[38:41]
	v_mfma_f32_16x16x32_bf16 v[34:37], v[224:227], v[172:175], v[34:37]
	v_mfma_f32_16x16x32_bf16 v[22:25], v[216:219], v[180:183], v[22:25]
	v_mfma_f32_16x16x32_bf16 v[18:21], v[224:227], v[180:183], v[18:21]
	v_mfma_f32_16x16x32_bf16 v[6:9], v[216:219], v[208:211], v[6:9]
	v_mfma_f32_16x16x32_bf16 v[2:5], v[224:227], v[208:211], v[2:5]
	v_mfma_f32_16x16x32_bf16 v[54:57], v[220:223], v[168:171], v[54:57]
	v_mfma_f32_16x16x32_bf16 v[50:53], v[228:231], v[168:171], v[50:53]
	v_mfma_f32_16x16x32_bf16 v[38:41], v[220:223], v[176:179], v[38:41]
	v_mfma_f32_16x16x32_bf16 v[34:37], v[228:231], v[176:179], v[34:37]
	v_mfma_f32_16x16x32_bf16 v[22:25], v[220:223], v[204:207], v[22:25]
	v_mfma_f32_16x16x32_bf16 v[18:21], v[228:231], v[204:207], v[18:21]
	v_mfma_f32_16x16x32_bf16 v[6:9], v[220:223], v[212:215], v[6:9]
	v_mfma_f32_16x16x32_bf16 v[2:5], v[228:231], v[212:215], v[2:5]
	s_barrier
	s_add_i32 s10, 0, 0x18000
	v_add_u32_e32 v154, s10, v165
	ds_read_b128 v[142:145], v154
	ds_read_b128 v[146:149], v154 offset:1024
	ds_read_b128 v[150:153], v154 offset:2048
	ds_read_b128 v[154:157], v154 offset:3072
	s_add_u32 s4, s4, s92
	s_addc_u32 s5, s5, 0
	s_mov_b32 m0, s31
	v_lshl_add_u64 v[216:217], s[4:5], 0, v[130:131]
	ds_read_b128 v[158:161], v166 offset:32768
	ds_read_b128 v[168:171], v166 offset:33792
	ds_read_b128 v[172:175], v166 offset:34816
	ds_read_b128 v[176:179], v166 offset:35840
	ds_read_b128 v[180:183], v166 offset:36864
	ds_read_b128 v[204:207], v166 offset:37888
	ds_read_b128 v[208:211], v166 offset:38912
	ds_read_b128 v[212:215], v166 offset:39936
	global_load_lds_dwordx4 v[216:217], off
	v_lshl_add_u64 v[216:217], s[4:5], 0, v[134:135]
	s_mov_b32 m0, s34
	s_nop 0
	global_load_lds_dwordx4 v[216:217], off
	s_waitcnt lgkmcnt(8)
	s_barrier
	s_waitcnt lgkmcnt(0)
	v_mfma_f32_16x16x32_bf16 v[126:129], v[142:145], v[158:161], v[126:129]
	v_mfma_f32_16x16x32_bf16 v[122:125], v[150:153], v[158:161], v[122:125]
	v_mfma_f32_16x16x32_bf16 v[110:113], v[142:145], v[172:175], v[110:113]
	v_mfma_f32_16x16x32_bf16 v[106:109], v[150:153], v[172:175], v[106:109]
	v_mfma_f32_16x16x32_bf16 v[94:97], v[142:145], v[180:183], v[94:97]
	v_mfma_f32_16x16x32_bf16 v[90:93], v[150:153], v[180:183], v[90:93]
	v_mfma_f32_16x16x32_bf16 v[78:81], v[142:145], v[208:211], v[78:81]
	v_mfma_f32_16x16x32_bf16 v[74:77], v[150:153], v[208:211], v[74:77]
	v_mfma_f32_16x16x32_bf16 v[126:129], v[146:149], v[168:171], v[126:129]
	v_mfma_f32_16x16x32_bf16 v[122:125], v[154:157], v[168:171], v[122:125]
	v_mfma_f32_16x16x32_bf16 v[110:113], v[146:149], v[176:179], v[110:113]
	v_mfma_f32_16x16x32_bf16 v[106:109], v[154:157], v[176:179], v[106:109]
	v_mfma_f32_16x16x32_bf16 v[94:97], v[146:149], v[204:207], v[94:97]
	v_mfma_f32_16x16x32_bf16 v[90:93], v[154:157], v[204:207], v[90:93]
	v_mfma_f32_16x16x32_bf16 v[78:81], v[146:149], v[212:215], v[78:81]
	v_mfma_f32_16x16x32_bf16 v[74:77], v[154:157], v[212:215], v[74:77]
	s_barrier
	s_add_i32 s4, 0, 0x1c000
	s_add_i32 s5, s10, s28
	v_add_u32_e32 v167, s4, v165
	v_lshl_add_u64 v[162:163], v[162:163], 0, s[6:7]
	s_mov_b32 m0, s5
	ds_read_b128 v[216:219], v167
	ds_read_b128 v[220:223], v167 offset:1024
	ds_read_b128 v[224:227], v167 offset:2048
	ds_read_b128 v[228:231], v167 offset:3072
	global_load_lds_dwordx4 v[162:163], off
	v_lshl_add_u64 v[162:163], v[184:185], 0, s[6:7]
	s_add_i32 m0, s5, 0x2000
	s_nop 0
	global_load_lds_dwordx4 v[162:163], off
	s_barrier
	s_waitcnt lgkmcnt(0)
	v_mfma_f32_16x16x32_bf16 v[118:121], v[216:219], v[158:161], v[118:121]
	v_mfma_f32_16x16x32_bf16 v[114:117], v[224:227], v[158:161], v[114:117]
	v_mfma_f32_16x16x32_bf16 v[102:105], v[216:219], v[172:175], v[102:105]
	v_mfma_f32_16x16x32_bf16 v[98:101], v[224:227], v[172:175], v[98:101]
	v_mfma_f32_16x16x32_bf16 v[86:89], v[216:219], v[180:183], v[86:89]
	v_mfma_f32_16x16x32_bf16 v[82:85], v[224:227], v[180:183], v[82:85]
	v_mfma_f32_16x16x32_bf16 v[70:73], v[216:219], v[208:211], v[70:73]
	v_mfma_f32_16x16x32_bf16 v[66:69], v[224:227], v[208:211], v[66:69]
	v_mfma_f32_16x16x32_bf16 v[118:121], v[220:223], v[168:171], v[118:121]
	v_mfma_f32_16x16x32_bf16 v[114:117], v[228:231], v[168:171], v[114:117]
	v_mfma_f32_16x16x32_bf16 v[102:105], v[220:223], v[176:179], v[102:105]
	v_mfma_f32_16x16x32_bf16 v[98:101], v[228:231], v[176:179], v[98:101]
	v_mfma_f32_16x16x32_bf16 v[86:89], v[220:223], v[204:207], v[86:89]
	v_mfma_f32_16x16x32_bf16 v[82:85], v[228:231], v[204:207], v[82:85]
	v_mfma_f32_16x16x32_bf16 v[70:73], v[220:223], v[212:215], v[70:73]
	v_mfma_f32_16x16x32_bf16 v[66:69], v[228:231], v[212:215], v[66:69]
	s_barrier
	s_mov_b32 m0, s42
	v_lshl_add_u64 v[162:163], v[232:233], 0, s[6:7]
	ds_read_b128 v[158:161], v166 offset:49152
	ds_read_b128 v[168:171], v166 offset:50176
	ds_read_b128 v[172:175], v166 offset:51200
	ds_read_b128 v[176:179], v166 offset:52224
	ds_read_b128 v[180:183], v166 offset:53248
	ds_read_b128 v[204:207], v166 offset:54272
	ds_read_b128 v[208:211], v166 offset:55296
	ds_read_b128 v[212:215], v166 offset:56320
	global_load_lds_dwordx4 v[162:163], off
	v_lshl_add_u64 v[162:163], v[234:235], 0, s[6:7]
	s_mov_b32 m0, s43
	s_nop 0
	global_load_lds_dwordx4 v[162:163], off
	s_barrier
	s_waitcnt lgkmcnt(0)
	v_mfma_f32_16x16x32_bf16 v[62:65], v[142:145], v[158:161], v[62:65]
	v_mfma_f32_16x16x32_bf16 v[58:61], v[150:153], v[158:161], v[58:61]
	v_mfma_f32_16x16x32_bf16 v[46:49], v[142:145], v[172:175], v[46:49]
	v_mfma_f32_16x16x32_bf16 v[42:45], v[150:153], v[172:175], v[42:45]
	v_mfma_f32_16x16x32_bf16 v[30:33], v[142:145], v[180:183], v[30:33]
	v_mfma_f32_16x16x32_bf16 v[26:29], v[150:153], v[180:183], v[26:29]
	v_mfma_f32_16x16x32_bf16 v[14:17], v[142:145], v[208:211], v[14:17]
	v_mfma_f32_16x16x32_bf16 v[10:13], v[150:153], v[208:211], v[10:13]
	v_mfma_f32_16x16x32_bf16 v[62:65], v[146:149], v[168:171], v[62:65]
	v_mfma_f32_16x16x32_bf16 v[58:61], v[154:157], v[168:171], v[58:61]
	v_mfma_f32_16x16x32_bf16 v[46:49], v[146:149], v[176:179], v[46:49]
	v_mfma_f32_16x16x32_bf16 v[42:45], v[154:157], v[176:179], v[42:45]
	v_mfma_f32_16x16x32_bf16 v[30:33], v[146:149], v[204:207], v[30:33]
	v_mfma_f32_16x16x32_bf16 v[26:29], v[154:157], v[204:207], v[26:29]
	v_mfma_f32_16x16x32_bf16 v[14:17], v[146:149], v[212:215], v[14:17]
	v_mfma_f32_16x16x32_bf16 v[10:13], v[154:157], v[212:215], v[10:13]
	s_barrier
	s_add_i32 s4, s4, s28
	v_lshl_add_u64 v[142:143], v[236:237], 0, s[6:7]
	s_mov_b32 m0, s4
	s_nop 0
	global_load_lds_dwordx4 v[142:143], off
	v_lshl_add_u64 v[142:143], v[238:239], 0, s[6:7]
	s_add_i32 m0, s4, 0x2000
	s_nop 0
	global_load_lds_dwordx4 v[142:143], off
	s_add_u32 s0, s0, 0x100
	s_addc_u32 s1, s1, 0
	s_add_u32 s20, s20, 0x100
	s_addc_u32 s21, s21, 0
	s_cmp_ge_u32 s22, s35
	s_mov_b32 s4, s22
	s_waitcnt vmcnt(6)
	s_barrier
	v_mfma_f32_16x16x32_bf16 v[54:57], v[216:219], v[158:161], v[54:57]
	v_mfma_f32_16x16x32_bf16 v[50:53], v[224:227], v[158:161], v[50:53]
	v_mfma_f32_16x16x32_bf16 v[38:41], v[216:219], v[172:175], v[38:41]
	v_mfma_f32_16x16x32_bf16 v[34:37], v[224:227], v[172:175], v[34:37]
	v_mfma_f32_16x16x32_bf16 v[22:25], v[216:219], v[180:183], v[22:25]
	v_mfma_f32_16x16x32_bf16 v[18:21], v[224:227], v[180:183], v[18:21]
	v_mfma_f32_16x16x32_bf16 v[6:9], v[216:219], v[208:211], v[6:9]
	v_mfma_f32_16x16x32_bf16 v[2:5], v[224:227], v[208:211], v[2:5]
	v_mfma_f32_16x16x32_bf16 v[54:57], v[220:223], v[168:171], v[54:57]
	v_mfma_f32_16x16x32_bf16 v[50:53], v[228:231], v[168:171], v[50:53]
	v_mfma_f32_16x16x32_bf16 v[38:41], v[220:223], v[176:179], v[38:41]
	v_mfma_f32_16x16x32_bf16 v[34:37], v[228:231], v[176:179], v[34:37]
	v_mfma_f32_16x16x32_bf16 v[22:25], v[220:223], v[204:207], v[22:25]
	v_mfma_f32_16x16x32_bf16 v[18:21], v[228:231], v[204:207], v[18:21]
	v_mfma_f32_16x16x32_bf16 v[6:9], v[220:223], v[212:215], v[6:9]
	v_mfma_f32_16x16x32_bf16 v[2:5], v[228:231], v[212:215], v[2:5]
	s_barrier
	s_cbranch_scc0 .LBB0_282

.LBB0_346:
	s_add_u32 s0, s0, 0x80
	s_addc_u32 s1, s1, 0
	s_add_u32 s12, s4, 0x100
	s_addc_u32 s13, s5, 0
	s_mov_b32 s4, 0
	s_waitcnt lgkmcnt(0)
	s_waitcnt vmcnt(0)
	s_add_i32 s15, s4, 2
	s_add_u32 s10, s0, 0x80
	s_addc_u32 s5, s1, 0
	s_add_i32 s16, 0, 0x10000
	v_add_u32_e32 v142, s16, v205
	ds_read_b128 v[130:133], v142
	ds_read_b128 v[134:137], v142 offset:1024
	ds_read_b128 v[138:141], v142 offset:2048
	ds_read_b128 v[142:145], v142 offset:3072
	s_cmp_eq_u32 s79, s4
	s_cselect_b32 s4, s44, s10
	s_cselect_b32 s5, s45, s5
	s_cselect_b32 s11, s47, s13
	s_cselect_b32 s10, s46, s12
	v_lshl_add_u64 v[212:213], s[0:1], 0, v[154:155]
	s_add_i32 m0, s71, 0xc000
	ds_read_b128 v[158:161], v206
	ds_read_b128 v[162:165], v206 offset:1024
	ds_read_b128 v[166:169], v206 offset:2048
	ds_read_b128 v[170:173], v206 offset:3072
	ds_read_b128 v[174:177], v206 offset:4096
	ds_read_b128 v[178:181], v206 offset:5120
	ds_read_b128 v[182:185], v206 offset:6144
	ds_read_b128 v[208:211], v206 offset:7168
	global_load_lds_dwordx4 v[212:213], off
	v_lshl_add_u64 v[212:213], s[0:1], 0, v[156:157]
	s_add_i32 m0, s71, 0xe000
	s_nop 0
	global_load_lds_dwordx4 v[212:213], off
	s_waitcnt lgkmcnt(8)
	s_barrier
	s_waitcnt lgkmcnt(0)
	v_mfma_f32_16x16x32_bf16 v[126:129], v[130:133], v[158:161], 0
	v_mfma_f32_16x16x32_bf16 v[122:125], v[138:141], v[158:161], 0
	v_mfma_f32_16x16x32_bf16 v[110:113], v[130:133], v[166:169], 0
	v_mfma_f32_16x16x32_bf16 v[106:109], v[138:141], v[166:169], 0
	v_mfma_f32_16x16x32_bf16 v[94:97], v[130:133], v[174:177], 0
	v_mfma_f32_16x16x32_bf16 v[90:93], v[138:141], v[174:177], 0
	v_mfma_f32_16x16x32_bf16 v[78:81], v[130:133], v[182:185], 0
	v_mfma_f32_16x16x32_bf16 v[74:77], v[138:141], v[182:185], 0
	v_mfma_f32_16x16x32_bf16 v[126:129], v[134:137], v[162:165], v[126:129]
	v_mfma_f32_16x16x32_bf16 v[122:125], v[142:145], v[162:165], v[122:125]
	v_mfma_f32_16x16x32_bf16 v[110:113], v[134:137], v[170:173], v[110:113]
	v_mfma_f32_16x16x32_bf16 v[106:109], v[142:145], v[170:173], v[106:109]
	v_mfma_f32_16x16x32_bf16 v[94:97], v[134:137], v[178:181], v[94:97]
	v_mfma_f32_16x16x32_bf16 v[90:93], v[142:145], v[178:181], v[90:93]
	v_mfma_f32_16x16x32_bf16 v[78:81], v[134:137], v[208:211], v[78:81]
	v_mfma_f32_16x16x32_bf16 v[74:77], v[142:145], v[208:211], v[74:77]
	s_barrier
	s_add_i32 s17, 0, 0x14000
	s_add_i32 s16, s16, s70
	v_add_u32_e32 v207, s17, v205
	v_lshl_add_u64 v[228:229], s[10:11], 0, v[148:149]
	s_mov_b32 m0, s16
	ds_read_b128 v[212:215], v207
	ds_read_b128 v[216:219], v207 offset:1024
	ds_read_b128 v[220:223], v207 offset:2048
	ds_read_b128 v[224:227], v207 offset:3072
	global_load_lds_dwordx4 v[228:229], off
	v_lshl_add_u64 v[230:231], s[10:11], 0, v[152:153]
	s_add_i32 m0, s16, 0x2000
	s_nop 0
	global_load_lds_dwordx4 v[230:231], off
	s_barrier
	s_waitcnt lgkmcnt(0)
	v_mfma_f32_16x16x32_bf16 v[118:121], v[212:215], v[158:161], 0
	v_mfma_f32_16x16x32_bf16 v[114:117], v[220:223], v[158:161], 0
	v_mfma_f32_16x16x32_bf16 v[102:105], v[212:215], v[166:169], 0
	v_mfma_f32_16x16x32_bf16 v[98:101], v[220:223], v[166:169], 0
	v_mfma_f32_16x16x32_bf16 v[86:89], v[212:215], v[174:177], 0
	v_mfma_f32_16x16x32_bf16 v[82:85], v[220:223], v[174:177], 0
	v_mfma_f32_16x16x32_bf16 v[70:73], v[212:215], v[182:185], 0
	v_mfma_f32_16x16x32_bf16 v[66:69], v[220:223], v[182:185], 0
	v_mfma_f32_16x16x32_bf16 v[118:121], v[216:219], v[162:165], v[118:121]
	v_mfma_f32_16x16x32_bf16 v[114:117], v[224:227], v[162:165], v[114:117]
	v_mfma_f32_16x16x32_bf16 v[102:105], v[216:219], v[170:173], v[102:105]
	v_mfma_f32_16x16x32_bf16 v[98:101], v[224:227], v[170:173], v[98:101]
	v_mfma_f32_16x16x32_bf16 v[86:89], v[216:219], v[178:181], v[86:89]
	v_mfma_f32_16x16x32_bf16 v[82:85], v[224:227], v[178:181], v[82:85]
	v_mfma_f32_16x16x32_bf16 v[70:73], v[216:219], v[208:211], v[70:73]
	v_mfma_f32_16x16x32_bf16 v[66:69], v[224:227], v[208:211], v[66:69]
	s_barrier
	s_mov_b32 m0, s71
	v_lshl_add_u64 v[232:233], s[4:5], 0, v[146:147]
	ds_read_b128 v[158:161], v206 offset:16384
	ds_read_b128 v[162:165], v206 offset:17408
	ds_read_b128 v[166:169], v206 offset:18432
	ds_read_b128 v[170:173], v206 offset:19456
	ds_read_b128 v[174:177], v206 offset:20480
	ds_read_b128 v[178:181], v206 offset:21504
	ds_read_b128 v[182:185], v206 offset:22528
	ds_read_b128 v[208:211], v206 offset:23552
	global_load_lds_dwordx4 v[232:233], off
	v_lshl_add_u64 v[234:235], s[4:5], 0, v[150:151]
	s_mov_b32 m0, s72
	s_nop 0
	global_load_lds_dwordx4 v[234:235], off
	s_barrier
	s_waitcnt lgkmcnt(0)
	v_mfma_f32_16x16x32_bf16 v[62:65], v[130:133], v[158:161], 0
	v_mfma_f32_16x16x32_bf16 v[58:61], v[138:141], v[158:161], 0
	v_mfma_f32_16x16x32_bf16 v[46:49], v[130:133], v[166:169], 0
	v_mfma_f32_16x16x32_bf16 v[42:45], v[138:141], v[166:169], 0
	v_mfma_f32_16x16x32_bf16 v[30:33], v[130:133], v[174:177], 0
	v_mfma_f32_16x16x32_bf16 v[26:29], v[138:141], v[174:177], 0
	v_mfma_f32_16x16x32_bf16 v[14:17], v[130:133], v[182:185], 0
	v_mfma_f32_16x16x32_bf16 v[10:13], v[138:141], v[182:185], 0
	v_mfma_f32_16x16x32_bf16 v[62:65], v[134:137], v[162:165], v[62:65]
	v_mfma_f32_16x16x32_bf16 v[58:61], v[142:145], v[162:165], v[58:61]
	v_mfma_f32_16x16x32_bf16 v[46:49], v[134:137], v[170:173], v[46:49]
	v_mfma_f32_16x16x32_bf16 v[42:45], v[142:145], v[170:173], v[42:45]
	v_mfma_f32_16x16x32_bf16 v[30:33], v[134:137], v[178:181], v[30:33]
	v_mfma_f32_16x16x32_bf16 v[26:29], v[142:145], v[178:181], v[26:29]
	v_mfma_f32_16x16x32_bf16 v[14:17], v[134:137], v[208:211], v[14:17]
	v_mfma_f32_16x16x32_bf16 v[10:13], v[142:145], v[208:211], v[10:13]
	s_barrier
	s_add_u32 s10, s10, s92
	s_addc_u32 s11, s11, 0
	s_add_i32 s16, s17, s70
	v_lshl_add_u64 v[236:237], s[10:11], 0, v[148:149]
	s_mov_b32 m0, s16
	v_lshl_add_u64 v[238:239], s[10:11], 0, v[152:153]
	global_load_lds_dwordx4 v[236:237], off
	s_add_i32 m0, s16, 0x2000
	s_nop 0
	global_load_lds_dwordx4 v[238:239], off
	s_waitcnt vmcnt(6)
	s_barrier
	v_mfma_f32_16x16x32_bf16 v[54:57], v[212:215], v[158:161], 0
	v_mfma_f32_16x16x32_bf16 v[50:53], v[220:223], v[158:161], 0
	v_mfma_f32_16x16x32_bf16 v[38:41], v[212:215], v[166:169], 0
	v_mfma_f32_16x16x32_bf16 v[34:37], v[220:223], v[166:169], 0
	v_mfma_f32_16x16x32_bf16 v[22:25], v[212:215], v[174:177], 0
	v_mfma_f32_16x16x32_bf16 v[18:21], v[220:223], v[174:177], 0
	v_mfma_f32_16x16x32_bf16 v[6:9], v[212:215], v[182:185], 0
	v_mfma_f32_16x16x32_bf16 v[2:5], v[220:223], v[182:185], 0
	v_mfma_f32_16x16x32_bf16 v[54:57], v[216:219], v[162:165], v[54:57]
	v_mfma_f32_16x16x32_bf16 v[50:53], v[224:227], v[162:165], v[50:53]
	v_mfma_f32_16x16x32_bf16 v[38:41], v[216:219], v[170:173], v[38:41]
	v_mfma_f32_16x16x32_bf16 v[34:37], v[224:227], v[170:173], v[34:37]
	v_mfma_f32_16x16x32_bf16 v[22:25], v[216:219], v[178:181], v[22:25]
	v_mfma_f32_16x16x32_bf16 v[18:21], v[224:227], v[178:181], v[18:21]
	v_mfma_f32_16x16x32_bf16 v[6:9], v[216:219], v[208:211], v[6:9]
	v_mfma_f32_16x16x32_bf16 v[2:5], v[224:227], v[208:211], v[2:5]
	s_barrier
	s_add_i32 s10, 0, 0x18000
	v_add_u32_e32 v142, s10, v205
	ds_read_b128 v[130:133], v142
	ds_read_b128 v[134:137], v142 offset:1024
	ds_read_b128 v[138:141], v142 offset:2048
	ds_read_b128 v[142:145], v142 offset:3072
	s_add_u32 s4, s4, s92
	s_addc_u32 s5, s5, 0
	s_mov_b32 m0, s73
	v_lshl_add_u64 v[212:213], s[4:5], 0, v[146:147]
	ds_read_b128 v[158:161], v206 offset:32768
	ds_read_b128 v[162:165], v206 offset:33792
	ds_read_b128 v[166:169], v206 offset:34816
	ds_read_b128 v[170:173], v206 offset:35840
	ds_read_b128 v[174:177], v206 offset:36864
	ds_read_b128 v[178:181], v206 offset:37888
	ds_read_b128 v[182:185], v206 offset:38912
	ds_read_b128 v[208:211], v206 offset:39936
	global_load_lds_dwordx4 v[212:213], off
	v_lshl_add_u64 v[212:213], s[4:5], 0, v[150:151]
	s_mov_b32 m0, s74
	s_nop 0
	global_load_lds_dwordx4 v[212:213], off
	s_waitcnt lgkmcnt(8)
	s_barrier
	s_waitcnt lgkmcnt(0)
	v_mfma_f32_16x16x32_bf16 v[126:129], v[130:133], v[158:161], v[126:129]
	v_mfma_f32_16x16x32_bf16 v[122:125], v[138:141], v[158:161], v[122:125]
	v_mfma_f32_16x16x32_bf16 v[110:113], v[130:133], v[166:169], v[110:113]
	v_mfma_f32_16x16x32_bf16 v[106:109], v[138:141], v[166:169], v[106:109]
	v_mfma_f32_16x16x32_bf16 v[94:97], v[130:133], v[174:177], v[94:97]
	v_mfma_f32_16x16x32_bf16 v[90:93], v[138:141], v[174:177], v[90:93]
	v_mfma_f32_16x16x32_bf16 v[78:81], v[130:133], v[182:185], v[78:81]
	v_mfma_f32_16x16x32_bf16 v[74:77], v[138:141], v[182:185], v[74:77]
	v_mfma_f32_16x16x32_bf16 v[126:129], v[134:137], v[162:165], v[126:129]
	v_mfma_f32_16x16x32_bf16 v[122:125], v[142:145], v[162:165], v[122:125]
	v_mfma_f32_16x16x32_bf16 v[110:113], v[134:137], v[170:173], v[110:113]
	v_mfma_f32_16x16x32_bf16 v[106:109], v[142:145], v[170:173], v[106:109]
	v_mfma_f32_16x16x32_bf16 v[94:97], v[134:137], v[178:181], v[94:97]
	v_mfma_f32_16x16x32_bf16 v[90:93], v[142:145], v[178:181], v[90:93]
	v_mfma_f32_16x16x32_bf16 v[78:81], v[134:137], v[208:211], v[78:81]
	v_mfma_f32_16x16x32_bf16 v[74:77], v[142:145], v[208:211], v[74:77]
	s_barrier
	s_add_i32 s4, 0, 0x1c000
	s_add_i32 s5, s10, s70
	v_add_u32_e32 v207, s4, v205
	v_lshl_add_u64 v[228:229], v[228:229], 0, s[6:7]
	s_mov_b32 m0, s5
	ds_read_b128 v[212:215], v207
	ds_read_b128 v[216:219], v207 offset:1024
	ds_read_b128 v[220:223], v207 offset:2048
	ds_read_b128 v[224:227], v207 offset:3072
	global_load_lds_dwordx4 v[228:229], off
	v_lshl_add_u64 v[228:229], v[230:231], 0, s[6:7]
	s_add_i32 m0, s5, 0x2000
	s_nop 0
	global_load_lds_dwordx4 v[228:229], off
	s_barrier
	s_waitcnt lgkmcnt(0)
	v_mfma_f32_16x16x32_bf16 v[118:121], v[212:215], v[158:161], v[118:121]
	v_mfma_f32_16x16x32_bf16 v[114:117], v[220:223], v[158:161], v[114:117]
	v_mfma_f32_16x16x32_bf16 v[102:105], v[212:215], v[166:169], v[102:105]
	v_mfma_f32_16x16x32_bf16 v[98:101], v[220:223], v[166:169], v[98:101]
	v_mfma_f32_16x16x32_bf16 v[86:89], v[212:215], v[174:177], v[86:89]
	v_mfma_f32_16x16x32_bf16 v[82:85], v[220:223], v[174:177], v[82:85]
	v_mfma_f32_16x16x32_bf16 v[70:73], v[212:215], v[182:185], v[70:73]
	v_mfma_f32_16x16x32_bf16 v[66:69], v[220:223], v[182:185], v[66:69]
	v_mfma_f32_16x16x32_bf16 v[118:121], v[216:219], v[162:165], v[118:121]
	v_mfma_f32_16x16x32_bf16 v[114:117], v[224:227], v[162:165], v[114:117]
	v_mfma_f32_16x16x32_bf16 v[102:105], v[216:219], v[170:173], v[102:105]
	v_mfma_f32_16x16x32_bf16 v[98:101], v[224:227], v[170:173], v[98:101]
	v_mfma_f32_16x16x32_bf16 v[86:89], v[216:219], v[178:181], v[86:89]
	v_mfma_f32_16x16x32_bf16 v[82:85], v[224:227], v[178:181], v[82:85]
	v_mfma_f32_16x16x32_bf16 v[70:73], v[216:219], v[208:211], v[70:73]
	v_mfma_f32_16x16x32_bf16 v[66:69], v[224:227], v[208:211], v[66:69]
	s_barrier
	s_mov_b32 m0, s77
	v_lshl_add_u64 v[228:229], v[232:233], 0, s[6:7]
	ds_read_b128 v[158:161], v206 offset:49152
	ds_read_b128 v[162:165], v206 offset:50176
	ds_read_b128 v[166:169], v206 offset:51200
	ds_read_b128 v[170:173], v206 offset:52224
	ds_read_b128 v[174:177], v206 offset:53248
	ds_read_b128 v[178:181], v206 offset:54272
	ds_read_b128 v[182:185], v206 offset:55296
	ds_read_b128 v[208:211], v206 offset:56320
	global_load_lds_dwordx4 v[228:229], off
	v_lshl_add_u64 v[228:229], v[234:235], 0, s[6:7]
	s_mov_b32 m0, s78
	s_nop 0
	global_load_lds_dwordx4 v[228:229], off
	s_barrier
	s_waitcnt lgkmcnt(0)
	v_mfma_f32_16x16x32_bf16 v[62:65], v[130:133], v[158:161], v[62:65]
	v_mfma_f32_16x16x32_bf16 v[58:61], v[138:141], v[158:161], v[58:61]
	v_mfma_f32_16x16x32_bf16 v[46:49], v[130:133], v[166:169], v[46:49]
	v_mfma_f32_16x16x32_bf16 v[42:45], v[138:141], v[166:169], v[42:45]
	v_mfma_f32_16x16x32_bf16 v[30:33], v[130:133], v[174:177], v[30:33]
	v_mfma_f32_16x16x32_bf16 v[26:29], v[138:141], v[174:177], v[26:29]
	v_mfma_f32_16x16x32_bf16 v[14:17], v[130:133], v[182:185], v[14:17]
	v_mfma_f32_16x16x32_bf16 v[10:13], v[138:141], v[182:185], v[10:13]
	v_mfma_f32_16x16x32_bf16 v[62:65], v[134:137], v[162:165], v[62:65]
	v_mfma_f32_16x16x32_bf16 v[58:61], v[142:145], v[162:165], v[58:61]
	v_mfma_f32_16x16x32_bf16 v[46:49], v[134:137], v[170:173], v[46:49]
	v_mfma_f32_16x16x32_bf16 v[42:45], v[142:145], v[170:173], v[42:45]
	v_mfma_f32_16x16x32_bf16 v[30:33], v[134:137], v[178:181], v[30:33]
	v_mfma_f32_16x16x32_bf16 v[26:29], v[142:145], v[178:181], v[26:29]
	v_mfma_f32_16x16x32_bf16 v[14:17], v[134:137], v[208:211], v[14:17]
	v_mfma_f32_16x16x32_bf16 v[10:13], v[142:145], v[208:211], v[10:13]
	s_barrier
	s_add_i32 s4, s4, s70
	v_lshl_add_u64 v[130:131], v[236:237], 0, s[6:7]
	s_mov_b32 m0, s4
	s_nop 0
	global_load_lds_dwordx4 v[130:131], off
	v_lshl_add_u64 v[130:131], v[238:239], 0, s[6:7]
	s_add_i32 m0, s4, 0x2000
	s_nop 0
	global_load_lds_dwordx4 v[130:131], off
	s_add_u32 s0, s0, 0x100
	s_addc_u32 s1, s1, 0
	s_add_u32 s12, s12, 0x100
	s_addc_u32 s13, s13, 0
	s_cmp_ge_u32 s15, s75
	s_mov_b32 s4, s15
	s_waitcnt vmcnt(6)
	s_barrier
	v_mfma_f32_16x16x32_bf16 v[54:57], v[212:215], v[158:161], v[54:57]
	v_mfma_f32_16x16x32_bf16 v[50:53], v[220:223], v[158:161], v[50:53]
	v_mfma_f32_16x16x32_bf16 v[38:41], v[212:215], v[166:169], v[38:41]
	v_mfma_f32_16x16x32_bf16 v[34:37], v[220:223], v[166:169], v[34:37]
	v_mfma_f32_16x16x32_bf16 v[22:25], v[212:215], v[174:177], v[22:25]
	v_mfma_f32_16x16x32_bf16 v[18:21], v[220:223], v[174:177], v[18:21]
	v_mfma_f32_16x16x32_bf16 v[6:9], v[212:215], v[182:185], v[6:9]
	v_mfma_f32_16x16x32_bf16 v[2:5], v[220:223], v[182:185], v[2:5]
	v_mfma_f32_16x16x32_bf16 v[54:57], v[216:219], v[162:165], v[54:57]
	v_mfma_f32_16x16x32_bf16 v[50:53], v[224:227], v[162:165], v[50:53]
	v_mfma_f32_16x16x32_bf16 v[38:41], v[216:219], v[170:173], v[38:41]
	v_mfma_f32_16x16x32_bf16 v[34:37], v[224:227], v[170:173], v[34:37]
	v_mfma_f32_16x16x32_bf16 v[22:25], v[216:219], v[178:181], v[22:25]
	v_mfma_f32_16x16x32_bf16 v[18:21], v[224:227], v[178:181], v[18:21]
	v_mfma_f32_16x16x32_bf16 v[6:9], v[216:219], v[208:211], v[6:9]
	v_mfma_f32_16x16x32_bf16 v[2:5], v[224:227], v[208:211], v[2:5]
	s_barrier
	s_cbranch_scc1 .Lkexit_347
.LBB0_347:
	s_add_i32 s15, s4, 2
	s_add_u32 s10, s0, 0x80
	s_addc_u32 s5, s1, 0
	s_add_i32 s16, 0, 0x10000
	v_add_u32_e32 v142, s16, v205
	ds_read_b128 v[130:133], v142
	ds_read_b128 v[134:137], v142 offset:1024
	ds_read_b128 v[138:141], v142 offset:2048
	ds_read_b128 v[142:145], v142 offset:3072
	s_cmp_eq_u32 s79, s4
	s_cselect_b32 s4, s44, s10
	s_cselect_b32 s5, s45, s5
	s_cselect_b32 s11, s47, s13
	s_cselect_b32 s10, s46, s12
	v_lshl_add_u64 v[212:213], s[0:1], 0, v[154:155]
	s_add_i32 m0, s71, 0xc000
	ds_read_b128 v[158:161], v206
	ds_read_b128 v[162:165], v206 offset:1024
	ds_read_b128 v[166:169], v206 offset:2048
	ds_read_b128 v[170:173], v206 offset:3072
	ds_read_b128 v[174:177], v206 offset:4096
	ds_read_b128 v[178:181], v206 offset:5120
	ds_read_b128 v[182:185], v206 offset:6144
	ds_read_b128 v[208:211], v206 offset:7168
	global_load_lds_dwordx4 v[212:213], off
	v_lshl_add_u64 v[212:213], s[0:1], 0, v[156:157]
	s_add_i32 m0, s71, 0xe000
	s_nop 0
	global_load_lds_dwordx4 v[212:213], off
	s_waitcnt lgkmcnt(8)
	s_barrier
	s_waitcnt lgkmcnt(0)
	v_mfma_f32_16x16x32_bf16 v[126:129], v[130:133], v[158:161], v[126:129]
	v_mfma_f32_16x16x32_bf16 v[122:125], v[138:141], v[158:161], v[122:125]
	v_mfma_f32_16x16x32_bf16 v[110:113], v[130:133], v[166:169], v[110:113]
	v_mfma_f32_16x16x32_bf16 v[106:109], v[138:141], v[166:169], v[106:109]
	v_mfma_f32_16x16x32_bf16 v[94:97], v[130:133], v[174:177], v[94:97]
	v_mfma_f32_16x16x32_bf16 v[90:93], v[138:141], v[174:177], v[90:93]
	v_mfma_f32_16x16x32_bf16 v[78:81], v[130:133], v[182:185], v[78:81]
	v_mfma_f32_16x16x32_bf16 v[74:77], v[138:141], v[182:185], v[74:77]
	v_mfma_f32_16x16x32_bf16 v[126:129], v[134:137], v[162:165], v[126:129]
	v_mfma_f32_16x16x32_bf16 v[122:125], v[142:145], v[162:165], v[122:125]
	v_mfma_f32_16x16x32_bf16 v[110:113], v[134:137], v[170:173], v[110:113]
	v_mfma_f32_16x16x32_bf16 v[106:109], v[142:145], v[170:173], v[106:109]
	v_mfma_f32_16x16x32_bf16 v[94:97], v[134:137], v[178:181], v[94:97]
	v_mfma_f32_16x16x32_bf16 v[90:93], v[142:145], v[178:181], v[90:93]
	v_mfma_f32_16x16x32_bf16 v[78:81], v[134:137], v[208:211], v[78:81]
	v_mfma_f32_16x16x32_bf16 v[74:77], v[142:145], v[208:211], v[74:77]
	s_barrier
	s_add_i32 s17, 0, 0x14000
	s_add_i32 s16, s16, s70
	v_add_u32_e32 v207, s17, v205
	v_lshl_add_u64 v[228:229], s[10:11], 0, v[148:149]
	s_mov_b32 m0, s16
	ds_read_b128 v[212:215], v207
	ds_read_b128 v[216:219], v207 offset:1024
	ds_read_b128 v[220:223], v207 offset:2048
	ds_read_b128 v[224:227], v207 offset:3072
	global_load_lds_dwordx4 v[228:229], off
	v_lshl_add_u64 v[230:231], s[10:11], 0, v[152:153]
	s_add_i32 m0, s16, 0x2000
	s_nop 0
	global_load_lds_dwordx4 v[230:231], off
	s_barrier
	s_waitcnt lgkmcnt(0)
	v_mfma_f32_16x16x32_bf16 v[118:121], v[212:215], v[158:161], v[118:121]
	v_mfma_f32_16x16x32_bf16 v[114:117], v[220:223], v[158:161], v[114:117]
	v_mfma_f32_16x16x32_bf16 v[102:105], v[212:215], v[166:169], v[102:105]
	v_mfma_f32_16x16x32_bf16 v[98:101], v[220:223], v[166:169], v[98:101]
	v_mfma_f32_16x16x32_bf16 v[86:89], v[212:215], v[174:177], v[86:89]
	v_mfma_f32_16x16x32_bf16 v[82:85], v[220:223], v[174:177], v[82:85]
	v_mfma_f32_16x16x32_bf16 v[70:73], v[212:215], v[182:185], v[70:73]
	v_mfma_f32_16x16x32_bf16 v[66:69], v[220:223], v[182:185], v[66:69]
	v_mfma_f32_16x16x32_bf16 v[118:121], v[216:219], v[162:165], v[118:121]
	v_mfma_f32_16x16x32_bf16 v[114:117], v[224:227], v[162:165], v[114:117]
	v_mfma_f32_16x16x32_bf16 v[102:105], v[216:219], v[170:173], v[102:105]
	v_mfma_f32_16x16x32_bf16 v[98:101], v[224:227], v[170:173], v[98:101]
	v_mfma_f32_16x16x32_bf16 v[86:89], v[216:219], v[178:181], v[86:89]
	v_mfma_f32_16x16x32_bf16 v[82:85], v[224:227], v[178:181], v[82:85]
	v_mfma_f32_16x16x32_bf16 v[70:73], v[216:219], v[208:211], v[70:73]
	v_mfma_f32_16x16x32_bf16 v[66:69], v[224:227], v[208:211], v[66:69]
	s_barrier
	s_mov_b32 m0, s71
	v_lshl_add_u64 v[232:233], s[4:5], 0, v[146:147]
	ds_read_b128 v[158:161], v206 offset:16384
	ds_read_b128 v[162:165], v206 offset:17408
	ds_read_b128 v[166:169], v206 offset:18432
	ds_read_b128 v[170:173], v206 offset:19456
	ds_read_b128 v[174:177], v206 offset:20480
	ds_read_b128 v[178:181], v206 offset:21504
	ds_read_b128 v[182:185], v206 offset:22528
	ds_read_b128 v[208:211], v206 offset:23552
	global_load_lds_dwordx4 v[232:233], off
	v_lshl_add_u64 v[234:235], s[4:5], 0, v[150:151]
	s_mov_b32 m0, s72
	s_nop 0
	global_load_lds_dwordx4 v[234:235], off
	s_barrier
	s_waitcnt lgkmcnt(0)
	v_mfma_f32_16x16x32_bf16 v[62:65], v[130:133], v[158:161], v[62:65]
	v_mfma_f32_16x16x32_bf16 v[58:61], v[138:141], v[158:161], v[58:61]
	v_mfma_f32_16x16x32_bf16 v[46:49], v[130:133], v[166:169], v[46:49]
	v_mfma_f32_16x16x32_bf16 v[42:45], v[138:141], v[166:169], v[42:45]
	v_mfma_f32_16x16x32_bf16 v[30:33], v[130:133], v[174:177], v[30:33]
	v_mfma_f32_16x16x32_bf16 v[26:29], v[138:141], v[174:177], v[26:29]
	v_mfma_f32_16x16x32_bf16 v[14:17], v[130:133], v[182:185], v[14:17]
	v_mfma_f32_16x16x32_bf16 v[10:13], v[138:141], v[182:185], v[10:13]
	v_mfma_f32_16x16x32_bf16 v[62:65], v[134:137], v[162:165], v[62:65]
	v_mfma_f32_16x16x32_bf16 v[58:61], v[142:145], v[162:165], v[58:61]
	v_mfma_f32_16x16x32_bf16 v[46:49], v[134:137], v[170:173], v[46:49]
	v_mfma_f32_16x16x32_bf16 v[42:45], v[142:145], v[170:173], v[42:45]
	v_mfma_f32_16x16x32_bf16 v[30:33], v[134:137], v[178:181], v[30:33]
	v_mfma_f32_16x16x32_bf16 v[26:29], v[142:145], v[178:181], v[26:29]
	v_mfma_f32_16x16x32_bf16 v[14:17], v[134:137], v[208:211], v[14:17]
	v_mfma_f32_16x16x32_bf16 v[10:13], v[142:145], v[208:211], v[10:13]
	s_barrier
	s_add_u32 s10, s10, s92
	s_addc_u32 s11, s11, 0
	s_add_i32 s16, s17, s70
	v_lshl_add_u64 v[236:237], s[10:11], 0, v[148:149]
	s_mov_b32 m0, s16
	v_lshl_add_u64 v[238:239], s[10:11], 0, v[152:153]
	global_load_lds_dwordx4 v[236:237], off
	s_add_i32 m0, s16, 0x2000
	s_nop 0
	global_load_lds_dwordx4 v[238:239], off
	s_waitcnt vmcnt(6)
	s_barrier
	v_mfma_f32_16x16x32_bf16 v[54:57], v[212:215], v[158:161], v[54:57]
	v_mfma_f32_16x16x32_bf16 v[50:53], v[220:223], v[158:161], v[50:53]
	v_mfma_f32_16x16x32_bf16 v[38:41], v[212:215], v[166:169], v[38:41]
	v_mfma_f32_16x16x32_bf16 v[34:37], v[220:223], v[166:169], v[34:37]
	v_mfma_f32_16x16x32_bf16 v[22:25], v[212:215], v[174:177], v[22:25]
	v_mfma_f32_16x16x32_bf16 v[18:21], v[220:223], v[174:177], v[18:21]
	v_mfma_f32_16x16x32_bf16 v[6:9], v[212:215], v[182:185], v[6:9]
	v_mfma_f32_16x16x32_bf16 v[2:5], v[220:223], v[182:185], v[2:5]
	v_mfma_f32_16x16x32_bf16 v[54:57], v[216:219], v[162:165], v[54:57]
	v_mfma_f32_16x16x32_bf16 v[50:53], v[224:227], v[162:165], v[50:53]
	v_mfma_f32_16x16x32_bf16 v[38:41], v[216:219], v[170:173], v[38:41]
	v_mfma_f32_16x16x32_bf16 v[34:37], v[224:227], v[170:173], v[34:37]
	v_mfma_f32_16x16x32_bf16 v[22:25], v[216:219], v[178:181], v[22:25]
	v_mfma_f32_16x16x32_bf16 v[18:21], v[224:227], v[178:181], v[18:21]
	v_mfma_f32_16x16x32_bf16 v[6:9], v[216:219], v[208:211], v[6:9]
	v_mfma_f32_16x16x32_bf16 v[2:5], v[224:227], v[208:211], v[2:5]
	s_barrier
	s_add_i32 s10, 0, 0x18000
	v_add_u32_e32 v142, s10, v205
	ds_read_b128 v[130:133], v142
	ds_read_b128 v[134:137], v142 offset:1024
	ds_read_b128 v[138:141], v142 offset:2048
	ds_read_b128 v[142:145], v142 offset:3072
	s_add_u32 s4, s4, s92
	s_addc_u32 s5, s5, 0
	s_mov_b32 m0, s73
	v_lshl_add_u64 v[212:213], s[4:5], 0, v[146:147]
	ds_read_b128 v[158:161], v206 offset:32768
	ds_read_b128 v[162:165], v206 offset:33792
	ds_read_b128 v[166:169], v206 offset:34816
	ds_read_b128 v[170:173], v206 offset:35840
	ds_read_b128 v[174:177], v206 offset:36864
	ds_read_b128 v[178:181], v206 offset:37888
	ds_read_b128 v[182:185], v206 offset:38912
	ds_read_b128 v[208:211], v206 offset:39936
	global_load_lds_dwordx4 v[212:213], off
	v_lshl_add_u64 v[212:213], s[4:5], 0, v[150:151]
	s_mov_b32 m0, s74
	s_nop 0
	global_load_lds_dwordx4 v[212:213], off
	s_waitcnt lgkmcnt(8)
	s_barrier
	s_waitcnt lgkmcnt(0)
	v_mfma_f32_16x16x32_bf16 v[126:129], v[130:133], v[158:161], v[126:129]
	v_mfma_f32_16x16x32_bf16 v[122:125], v[138:141], v[158:161], v[122:125]
	v_mfma_f32_16x16x32_bf16 v[110:113], v[130:133], v[166:169], v[110:113]
	v_mfma_f32_16x16x32_bf16 v[106:109], v[138:141], v[166:169], v[106:109]
	v_mfma_f32_16x16x32_bf16 v[94:97], v[130:133], v[174:177], v[94:97]
	v_mfma_f32_16x16x32_bf16 v[90:93], v[138:141], v[174:177], v[90:93]
	v_mfma_f32_16x16x32_bf16 v[78:81], v[130:133], v[182:185], v[78:81]
	v_mfma_f32_16x16x32_bf16 v[74:77], v[138:141], v[182:185], v[74:77]
	v_mfma_f32_16x16x32_bf16 v[126:129], v[134:137], v[162:165], v[126:129]
	v_mfma_f32_16x16x32_bf16 v[122:125], v[142:145], v[162:165], v[122:125]
	v_mfma_f32_16x16x32_bf16 v[110:113], v[134:137], v[170:173], v[110:113]
	v_mfma_f32_16x16x32_bf16 v[106:109], v[142:145], v[170:173], v[106:109]
	v_mfma_f32_16x16x32_bf16 v[94:97], v[134:137], v[178:181], v[94:97]
	v_mfma_f32_16x16x32_bf16 v[90:93], v[142:145], v[178:181], v[90:93]
	v_mfma_f32_16x16x32_bf16 v[78:81], v[134:137], v[208:211], v[78:81]
	v_mfma_f32_16x16x32_bf16 v[74:77], v[142:145], v[208:211], v[74:77]
	s_barrier
	s_add_i32 s4, 0, 0x1c000
	s_add_i32 s5, s10, s70
	v_add_u32_e32 v207, s4, v205
	v_lshl_add_u64 v[228:229], v[228:229], 0, s[6:7]
	s_mov_b32 m0, s5
	ds_read_b128 v[212:215], v207
	ds_read_b128 v[216:219], v207 offset:1024
	ds_read_b128 v[220:223], v207 offset:2048
	ds_read_b128 v[224:227], v207 offset:3072
	global_load_lds_dwordx4 v[228:229], off
	v_lshl_add_u64 v[228:229], v[230:231], 0, s[6:7]
	s_add_i32 m0, s5, 0x2000
	s_nop 0
	global_load_lds_dwordx4 v[228:229], off
	s_barrier
	s_waitcnt lgkmcnt(0)
	v_mfma_f32_16x16x32_bf16 v[118:121], v[212:215], v[158:161], v[118:121]
	v_mfma_f32_16x16x32_bf16 v[114:117], v[220:223], v[158:161], v[114:117]
	v_mfma_f32_16x16x32_bf16 v[102:105], v[212:215], v[166:169], v[102:105]
	v_mfma_f32_16x16x32_bf16 v[98:101], v[220:223], v[166:169], v[98:101]
	v_mfma_f32_16x16x32_bf16 v[86:89], v[212:215], v[174:177], v[86:89]
	v_mfma_f32_16x16x32_bf16 v[82:85], v[220:223], v[174:177], v[82:85]
	v_mfma_f32_16x16x32_bf16 v[70:73], v[212:215], v[182:185], v[70:73]
	v_mfma_f32_16x16x32_bf16 v[66:69], v[220:223], v[182:185], v[66:69]
	v_mfma_f32_16x16x32_bf16 v[118:121], v[216:219], v[162:165], v[118:121]
	v_mfma_f32_16x16x32_bf16 v[114:117], v[224:227], v[162:165], v[114:117]
	v_mfma_f32_16x16x32_bf16 v[102:105], v[216:219], v[170:173], v[102:105]
	v_mfma_f32_16x16x32_bf16 v[98:101], v[224:227], v[170:173], v[98:101]
	v_mfma_f32_16x16x32_bf16 v[86:89], v[216:219], v[178:181], v[86:89]
	v_mfma_f32_16x16x32_bf16 v[82:85], v[224:227], v[178:181], v[82:85]
	v_mfma_f32_16x16x32_bf16 v[70:73], v[216:219], v[208:211], v[70:73]
	v_mfma_f32_16x16x32_bf16 v[66:69], v[224:227], v[208:211], v[66:69]
	s_barrier
	s_mov_b32 m0, s77
	v_lshl_add_u64 v[228:229], v[232:233], 0, s[6:7]
	ds_read_b128 v[158:161], v206 offset:49152
	ds_read_b128 v[162:165], v206 offset:50176
	ds_read_b128 v[166:169], v206 offset:51200
	ds_read_b128 v[170:173], v206 offset:52224
	ds_read_b128 v[174:177], v206 offset:53248
	ds_read_b128 v[178:181], v206 offset:54272
	ds_read_b128 v[182:185], v206 offset:55296
	ds_read_b128 v[208:211], v206 offset:56320
	global_load_lds_dwordx4 v[228:229], off
	v_lshl_add_u64 v[228:229], v[234:235], 0, s[6:7]
	s_mov_b32 m0, s78
	s_nop 0
	global_load_lds_dwordx4 v[228:229], off
	s_barrier
	s_waitcnt lgkmcnt(0)
	v_mfma_f32_16x16x32_bf16 v[62:65], v[130:133], v[158:161], v[62:65]
	v_mfma_f32_16x16x32_bf16 v[58:61], v[138:141], v[158:161], v[58:61]
	v_mfma_f32_16x16x32_bf16 v[46:49], v[130:133], v[166:169], v[46:49]
	v_mfma_f32_16x16x32_bf16 v[42:45], v[138:141], v[166:169], v[42:45]
	v_mfma_f32_16x16x32_bf16 v[30:33], v[130:133], v[174:177], v[30:33]
	v_mfma_f32_16x16x32_bf16 v[26:29], v[138:141], v[174:177], v[26:29]
	v_mfma_f32_16x16x32_bf16 v[14:17], v[130:133], v[182:185], v[14:17]
	v_mfma_f32_16x16x32_bf16 v[10:13], v[138:141], v[182:185], v[10:13]
	v_mfma_f32_16x16x32_bf16 v[62:65], v[134:137], v[162:165], v[62:65]
	v_mfma_f32_16x16x32_bf16 v[58:61], v[142:145], v[162:165], v[58:61]
	v_mfma_f32_16x16x32_bf16 v[46:49], v[134:137], v[170:173], v[46:49]
	v_mfma_f32_16x16x32_bf16 v[42:45], v[142:145], v[170:173], v[42:45]
	v_mfma_f32_16x16x32_bf16 v[30:33], v[134:137], v[178:181], v[30:33]
	v_mfma_f32_16x16x32_bf16 v[26:29], v[142:145], v[178:181], v[26:29]
	v_mfma_f32_16x16x32_bf16 v[14:17], v[134:137], v[208:211], v[14:17]
	v_mfma_f32_16x16x32_bf16 v[10:13], v[142:145], v[208:211], v[10:13]
	s_barrier
	s_add_i32 s4, s4, s70
	v_lshl_add_u64 v[130:131], v[236:237], 0, s[6:7]
	s_mov_b32 m0, s4
	s_nop 0
	global_load_lds_dwordx4 v[130:131], off
	v_lshl_add_u64 v[130:131], v[238:239], 0, s[6:7]
	s_add_i32 m0, s4, 0x2000
	s_nop 0
	global_load_lds_dwordx4 v[130:131], off
	s_add_u32 s0, s0, 0x100
	s_addc_u32 s1, s1, 0
	s_add_u32 s12, s12, 0x100
	s_addc_u32 s13, s13, 0
	s_cmp_ge_u32 s15, s75
	s_mov_b32 s4, s15
	s_waitcnt vmcnt(6)
	s_barrier
	v_mfma_f32_16x16x32_bf16 v[54:57], v[212:215], v[158:161], v[54:57]
	v_mfma_f32_16x16x32_bf16 v[50:53], v[220:223], v[158:161], v[50:53]
	v_mfma_f32_16x16x32_bf16 v[38:41], v[212:215], v[166:169], v[38:41]
	v_mfma_f32_16x16x32_bf16 v[34:37], v[220:223], v[166:169], v[34:37]
	v_mfma_f32_16x16x32_bf16 v[22:25], v[212:215], v[174:177], v[22:25]
	v_mfma_f32_16x16x32_bf16 v[18:21], v[220:223], v[174:177], v[18:21]
	v_mfma_f32_16x16x32_bf16 v[6:9], v[212:215], v[182:185], v[6:9]
	v_mfma_f32_16x16x32_bf16 v[2:5], v[220:223], v[182:185], v[2:5]
	v_mfma_f32_16x16x32_bf16 v[54:57], v[216:219], v[162:165], v[54:57]
	v_mfma_f32_16x16x32_bf16 v[50:53], v[224:227], v[162:165], v[50:53]
	v_mfma_f32_16x16x32_bf16 v[38:41], v[216:219], v[170:173], v[38:41]
	v_mfma_f32_16x16x32_bf16 v[34:37], v[224:227], v[170:173], v[34:37]
	v_mfma_f32_16x16x32_bf16 v[22:25], v[216:219], v[178:181], v[22:25]
	v_mfma_f32_16x16x32_bf16 v[18:21], v[224:227], v[178:181], v[18:21]
	v_mfma_f32_16x16x32_bf16 v[6:9], v[216:219], v[208:211], v[6:9]
	v_mfma_f32_16x16x32_bf16 v[2:5], v[224:227], v[208:211], v[2:5]
	s_barrier
	s_cbranch_scc0 .LBB0_347

.LBB0_663:
	s_add_u32 s0, s0, 0x80
	s_addc_u32 s1, s1, 0
	s_add_u32 s49, s4, 0x100
	s_addc_u32 s65, s5, 0
	s_mov_b32 s4, 0
	s_waitcnt lgkmcnt(0)
	s_waitcnt vmcnt(0)
	s_add_i32 s66, s4, 2
	s_add_u32 s18, s0, 0x80
	s_addc_u32 s5, s1, 0
	s_add_i32 s68, 0, 0x10000
	v_add_u32_e32 v150, s68, v153
	ds_read_b128 v[142:145], v150
	ds_read_b128 v[146:149], v150 offset:1024
	ds_read_b128 v[156:159], v150 offset:2048
	ds_read_b128 v[160:163], v150 offset:3072
	s_cmp_eq_u32 s43, s4
	s_cselect_b32 s4, s10, s18
	s_cselect_b32 s5, s11, s5
	s_cselect_b32 s19, s13, s65
	s_cselect_b32 s18, s12, s49
	v_lshl_add_u64 v[150:151], s[0:1], 0, v[138:139]
	s_add_i32 m0, s28, 0xc000
	ds_read_b128 v[164:167], v154
	ds_read_b128 v[168:171], v154 offset:1024
	ds_read_b128 v[172:175], v154 offset:2048
	ds_read_b128 v[176:179], v154 offset:3072
	ds_read_b128 v[180:183], v154 offset:4096
	ds_read_b128 v[204:207], v154 offset:5120
	ds_read_b128 v[208:211], v154 offset:6144
	ds_read_b128 v[212:215], v154 offset:7168
	global_load_lds_dwordx4 v[150:151], off
	v_lshl_add_u64 v[150:151], s[0:1], 0, v[140:141]
	s_add_i32 m0, s28, 0xe000
	s_nop 0
	global_load_lds_dwordx4 v[150:151], off
	s_waitcnt lgkmcnt(8)
	s_barrier
	s_waitcnt lgkmcnt(0)
	v_mfma_f32_16x16x32_bf16 v[126:129], v[142:145], v[164:167], 0
	v_mfma_f32_16x16x32_bf16 v[122:125], v[156:159], v[164:167], 0
	v_mfma_f32_16x16x32_bf16 v[110:113], v[142:145], v[172:175], 0
	v_mfma_f32_16x16x32_bf16 v[106:109], v[156:159], v[172:175], 0
	v_mfma_f32_16x16x32_bf16 v[94:97], v[142:145], v[180:183], 0
	v_mfma_f32_16x16x32_bf16 v[90:93], v[156:159], v[180:183], 0
	v_mfma_f32_16x16x32_bf16 v[78:81], v[142:145], v[208:211], 0
	v_mfma_f32_16x16x32_bf16 v[74:77], v[156:159], v[208:211], 0
	v_mfma_f32_16x16x32_bf16 v[126:129], v[146:149], v[168:171], v[126:129]
	v_mfma_f32_16x16x32_bf16 v[122:125], v[160:163], v[168:171], v[122:125]
	v_mfma_f32_16x16x32_bf16 v[110:113], v[146:149], v[176:179], v[110:113]
	v_mfma_f32_16x16x32_bf16 v[106:109], v[160:163], v[176:179], v[106:109]
	v_mfma_f32_16x16x32_bf16 v[94:97], v[146:149], v[204:207], v[94:97]
	v_mfma_f32_16x16x32_bf16 v[90:93], v[160:163], v[204:207], v[90:93]
	v_mfma_f32_16x16x32_bf16 v[78:81], v[146:149], v[212:215], v[78:81]
	v_mfma_f32_16x16x32_bf16 v[74:77], v[160:163], v[212:215], v[74:77]
	s_barrier
	s_add_i32 s69, 0, 0x14000
	v_add_u32_e32 v150, s69, v153
	s_add_i32 s68, s68, s25
	ds_read_b128 v[216:219], v150
	ds_read_b128 v[220:223], v150 offset:1024
	ds_read_b128 v[224:227], v150 offset:2048
	ds_read_b128 v[228:231], v150 offset:3072
	v_lshl_add_u64 v[150:151], s[18:19], 0, v[132:133]
	s_mov_b32 m0, s68
	v_lshl_add_u64 v[184:185], s[18:19], 0, v[136:137]
	global_load_lds_dwordx4 v[150:151], off
	s_add_i32 m0, s68, 0x2000
	s_nop 0
	global_load_lds_dwordx4 v[184:185], off
	s_barrier
	s_waitcnt lgkmcnt(0)
	v_mfma_f32_16x16x32_bf16 v[118:121], v[216:219], v[164:167], 0
	v_mfma_f32_16x16x32_bf16 v[114:117], v[224:227], v[164:167], 0
	v_mfma_f32_16x16x32_bf16 v[102:105], v[216:219], v[172:175], 0
	v_mfma_f32_16x16x32_bf16 v[98:101], v[224:227], v[172:175], 0
	v_mfma_f32_16x16x32_bf16 v[86:89], v[216:219], v[180:183], 0
	v_mfma_f32_16x16x32_bf16 v[82:85], v[224:227], v[180:183], 0
	v_mfma_f32_16x16x32_bf16 v[70:73], v[216:219], v[208:211], 0
	v_mfma_f32_16x16x32_bf16 v[66:69], v[224:227], v[208:211], 0
	v_mfma_f32_16x16x32_bf16 v[118:121], v[220:223], v[168:171], v[118:121]
	v_mfma_f32_16x16x32_bf16 v[114:117], v[228:231], v[168:171], v[114:117]
	v_mfma_f32_16x16x32_bf16 v[102:105], v[220:223], v[176:179], v[102:105]
	v_mfma_f32_16x16x32_bf16 v[98:101], v[228:231], v[176:179], v[98:101]
	v_mfma_f32_16x16x32_bf16 v[86:89], v[220:223], v[204:207], v[86:89]
	v_mfma_f32_16x16x32_bf16 v[82:85], v[228:231], v[204:207], v[82:85]
	v_mfma_f32_16x16x32_bf16 v[70:73], v[220:223], v[212:215], v[70:73]
	v_mfma_f32_16x16x32_bf16 v[66:69], v[228:231], v[212:215], v[66:69]
	s_barrier
	s_mov_b32 m0, s28
	v_lshl_add_u64 v[232:233], s[4:5], 0, v[130:131]
	ds_read_b128 v[164:167], v154 offset:16384
	ds_read_b128 v[168:171], v154 offset:17408
	ds_read_b128 v[172:175], v154 offset:18432
	ds_read_b128 v[176:179], v154 offset:19456
	ds_read_b128 v[180:183], v154 offset:20480
	ds_read_b128 v[204:207], v154 offset:21504
	ds_read_b128 v[208:211], v154 offset:22528
	ds_read_b128 v[212:215], v154 offset:23552
	global_load_lds_dwordx4 v[232:233], off
	v_lshl_add_u64 v[234:235], s[4:5], 0, v[134:135]
	s_mov_b32 m0, s29
	s_nop 0
	global_load_lds_dwordx4 v[234:235], off
	s_barrier
	s_waitcnt lgkmcnt(0)
	v_mfma_f32_16x16x32_bf16 v[62:65], v[142:145], v[164:167], 0
	v_mfma_f32_16x16x32_bf16 v[58:61], v[156:159], v[164:167], 0
	v_mfma_f32_16x16x32_bf16 v[46:49], v[142:145], v[172:175], 0
	v_mfma_f32_16x16x32_bf16 v[42:45], v[156:159], v[172:175], 0
	v_mfma_f32_16x16x32_bf16 v[30:33], v[142:145], v[180:183], 0
	v_mfma_f32_16x16x32_bf16 v[26:29], v[156:159], v[180:183], 0
	v_mfma_f32_16x16x32_bf16 v[14:17], v[142:145], v[208:211], 0
	v_mfma_f32_16x16x32_bf16 v[10:13], v[156:159], v[208:211], 0
	v_mfma_f32_16x16x32_bf16 v[62:65], v[146:149], v[168:171], v[62:65]
	v_mfma_f32_16x16x32_bf16 v[58:61], v[160:163], v[168:171], v[58:61]
	v_mfma_f32_16x16x32_bf16 v[46:49], v[146:149], v[176:179], v[46:49]
	v_mfma_f32_16x16x32_bf16 v[42:45], v[160:163], v[176:179], v[42:45]
	v_mfma_f32_16x16x32_bf16 v[30:33], v[146:149], v[204:207], v[30:33]
	v_mfma_f32_16x16x32_bf16 v[26:29], v[160:163], v[204:207], v[26:29]
	v_mfma_f32_16x16x32_bf16 v[14:17], v[146:149], v[212:215], v[14:17]
	v_mfma_f32_16x16x32_bf16 v[10:13], v[160:163], v[212:215], v[10:13]
	s_barrier
	s_add_u32 s18, s18, s14
	s_addc_u32 s19, s19, 0
	s_add_i32 s68, s69, s25
	v_lshl_add_u64 v[236:237], s[18:19], 0, v[132:133]
	s_mov_b32 m0, s68
	v_lshl_add_u64 v[238:239], s[18:19], 0, v[136:137]
	global_load_lds_dwordx4 v[236:237], off
	s_add_i32 m0, s68, 0x2000
	s_nop 0
	global_load_lds_dwordx4 v[238:239], off
	s_waitcnt vmcnt(6)
	s_barrier
	v_mfma_f32_16x16x32_bf16 v[54:57], v[216:219], v[164:167], 0
	v_mfma_f32_16x16x32_bf16 v[50:53], v[224:227], v[164:167], 0
	v_mfma_f32_16x16x32_bf16 v[38:41], v[216:219], v[172:175], 0
	v_mfma_f32_16x16x32_bf16 v[34:37], v[224:227], v[172:175], 0
	v_mfma_f32_16x16x32_bf16 v[22:25], v[216:219], v[180:183], 0
	v_mfma_f32_16x16x32_bf16 v[18:21], v[224:227], v[180:183], 0
	v_mfma_f32_16x16x32_bf16 v[6:9], v[216:219], v[208:211], 0
	v_mfma_f32_16x16x32_bf16 v[2:5], v[224:227], v[208:211], 0
	v_mfma_f32_16x16x32_bf16 v[54:57], v[220:223], v[168:171], v[54:57]
	v_mfma_f32_16x16x32_bf16 v[50:53], v[228:231], v[168:171], v[50:53]
	v_mfma_f32_16x16x32_bf16 v[38:41], v[220:223], v[176:179], v[38:41]
	v_mfma_f32_16x16x32_bf16 v[34:37], v[228:231], v[176:179], v[34:37]
	v_mfma_f32_16x16x32_bf16 v[22:25], v[220:223], v[204:207], v[22:25]
	v_mfma_f32_16x16x32_bf16 v[18:21], v[228:231], v[204:207], v[18:21]
	v_mfma_f32_16x16x32_bf16 v[6:9], v[220:223], v[212:215], v[6:9]
	v_mfma_f32_16x16x32_bf16 v[2:5], v[228:231], v[212:215], v[2:5]
	s_barrier
	s_add_i32 s18, 0, 0x18000
	v_add_u32_e32 v155, s18, v153
	ds_read_b128 v[142:145], v155
	ds_read_b128 v[146:149], v155 offset:1024
	ds_read_b128 v[156:159], v155 offset:2048
	ds_read_b128 v[160:163], v155 offset:3072
	s_add_u32 s4, s4, s14
	s_addc_u32 s5, s5, 0
	s_mov_b32 m0, s31
	v_lshl_add_u64 v[216:217], s[4:5], 0, v[130:131]
	ds_read_b128 v[164:167], v154 offset:32768
	ds_read_b128 v[168:171], v154 offset:33792
	ds_read_b128 v[172:175], v154 offset:34816
	ds_read_b128 v[176:179], v154 offset:35840
	ds_read_b128 v[180:183], v154 offset:36864
	ds_read_b128 v[204:207], v154 offset:37888
	ds_read_b128 v[208:211], v154 offset:38912
	ds_read_b128 v[212:215], v154 offset:39936
	global_load_lds_dwordx4 v[216:217], off
	v_lshl_add_u64 v[216:217], s[4:5], 0, v[134:135]
	s_mov_b32 m0, s34
	s_nop 0
	global_load_lds_dwordx4 v[216:217], off
	s_waitcnt lgkmcnt(8)
	s_barrier
	s_waitcnt lgkmcnt(0)
	v_mfma_f32_16x16x32_bf16 v[126:129], v[142:145], v[164:167], v[126:129]
	v_mfma_f32_16x16x32_bf16 v[122:125], v[156:159], v[164:167], v[122:125]
	v_mfma_f32_16x16x32_bf16 v[110:113], v[142:145], v[172:175], v[110:113]
	v_mfma_f32_16x16x32_bf16 v[106:109], v[156:159], v[172:175], v[106:109]
	v_mfma_f32_16x16x32_bf16 v[94:97], v[142:145], v[180:183], v[94:97]
	v_mfma_f32_16x16x32_bf16 v[90:93], v[156:159], v[180:183], v[90:93]
	v_mfma_f32_16x16x32_bf16 v[78:81], v[142:145], v[208:211], v[78:81]
	v_mfma_f32_16x16x32_bf16 v[74:77], v[156:159], v[208:211], v[74:77]
	v_mfma_f32_16x16x32_bf16 v[126:129], v[146:149], v[168:171], v[126:129]
	v_mfma_f32_16x16x32_bf16 v[122:125], v[160:163], v[168:171], v[122:125]
	v_mfma_f32_16x16x32_bf16 v[110:113], v[146:149], v[176:179], v[110:113]
	v_mfma_f32_16x16x32_bf16 v[106:109], v[160:163], v[176:179], v[106:109]
	v_mfma_f32_16x16x32_bf16 v[94:97], v[146:149], v[204:207], v[94:97]
	v_mfma_f32_16x16x32_bf16 v[90:93], v[160:163], v[204:207], v[90:93]
	v_mfma_f32_16x16x32_bf16 v[78:81], v[146:149], v[212:215], v[78:81]
	v_mfma_f32_16x16x32_bf16 v[74:77], v[160:163], v[212:215], v[74:77]
	s_barrier
	s_add_i32 s4, 0, 0x1c000
	s_add_i32 s5, s18, s25
	v_add_u32_e32 v155, s4, v153
	v_lshl_add_u64 v[150:151], v[150:151], 0, s[6:7]
	s_mov_b32 m0, s5
	ds_read_b128 v[216:219], v155
	ds_read_b128 v[220:223], v155 offset:1024
	ds_read_b128 v[224:227], v155 offset:2048
	ds_read_b128 v[228:231], v155 offset:3072
	global_load_lds_dwordx4 v[150:151], off
	v_lshl_add_u64 v[150:151], v[184:185], 0, s[6:7]
	s_add_i32 m0, s5, 0x2000
	s_nop 0
	global_load_lds_dwordx4 v[150:151], off
	s_barrier
	s_waitcnt lgkmcnt(0)
	v_mfma_f32_16x16x32_bf16 v[118:121], v[216:219], v[164:167], v[118:121]
	v_mfma_f32_16x16x32_bf16 v[114:117], v[224:227], v[164:167], v[114:117]
	v_mfma_f32_16x16x32_bf16 v[102:105], v[216:219], v[172:175], v[102:105]
	v_mfma_f32_16x16x32_bf16 v[98:101], v[224:227], v[172:175], v[98:101]
	v_mfma_f32_16x16x32_bf16 v[86:89], v[216:219], v[180:183], v[86:89]
	v_mfma_f32_16x16x32_bf16 v[82:85], v[224:227], v[180:183], v[82:85]
	v_mfma_f32_16x16x32_bf16 v[70:73], v[216:219], v[208:211], v[70:73]
	v_mfma_f32_16x16x32_bf16 v[66:69], v[224:227], v[208:211], v[66:69]
	v_mfma_f32_16x16x32_bf16 v[118:121], v[220:223], v[168:171], v[118:121]
	v_mfma_f32_16x16x32_bf16 v[114:117], v[228:231], v[168:171], v[114:117]
	v_mfma_f32_16x16x32_bf16 v[102:105], v[220:223], v[176:179], v[102:105]
	v_mfma_f32_16x16x32_bf16 v[98:101], v[228:231], v[176:179], v[98:101]
	v_mfma_f32_16x16x32_bf16 v[86:89], v[220:223], v[204:207], v[86:89]
	v_mfma_f32_16x16x32_bf16 v[82:85], v[228:231], v[204:207], v[82:85]
	v_mfma_f32_16x16x32_bf16 v[70:73], v[220:223], v[212:215], v[70:73]
	v_mfma_f32_16x16x32_bf16 v[66:69], v[228:231], v[212:215], v[66:69]
	s_barrier
	s_mov_b32 m0, s41
	v_lshl_add_u64 v[150:151], v[232:233], 0, s[6:7]
	ds_read_b128 v[164:167], v154 offset:49152
	ds_read_b128 v[168:171], v154 offset:50176
	ds_read_b128 v[172:175], v154 offset:51200
	ds_read_b128 v[176:179], v154 offset:52224
	ds_read_b128 v[180:183], v154 offset:53248
	ds_read_b128 v[204:207], v154 offset:54272
	ds_read_b128 v[208:211], v154 offset:55296
	ds_read_b128 v[212:215], v154 offset:56320
	global_load_lds_dwordx4 v[150:151], off
	v_lshl_add_u64 v[150:151], v[234:235], 0, s[6:7]
	s_mov_b32 m0, s42
	s_nop 0
	global_load_lds_dwordx4 v[150:151], off
	s_barrier
	s_waitcnt lgkmcnt(0)
	v_mfma_f32_16x16x32_bf16 v[62:65], v[142:145], v[164:167], v[62:65]
	v_mfma_f32_16x16x32_bf16 v[58:61], v[156:159], v[164:167], v[58:61]
	v_mfma_f32_16x16x32_bf16 v[46:49], v[142:145], v[172:175], v[46:49]
	v_mfma_f32_16x16x32_bf16 v[42:45], v[156:159], v[172:175], v[42:45]
	v_mfma_f32_16x16x32_bf16 v[30:33], v[142:145], v[180:183], v[30:33]
	v_mfma_f32_16x16x32_bf16 v[26:29], v[156:159], v[180:183], v[26:29]
	v_mfma_f32_16x16x32_bf16 v[14:17], v[142:145], v[208:211], v[14:17]
	v_mfma_f32_16x16x32_bf16 v[10:13], v[156:159], v[208:211], v[10:13]
	v_mfma_f32_16x16x32_bf16 v[62:65], v[146:149], v[168:171], v[62:65]
	v_mfma_f32_16x16x32_bf16 v[58:61], v[160:163], v[168:171], v[58:61]
	v_mfma_f32_16x16x32_bf16 v[46:49], v[146:149], v[176:179], v[46:49]
	v_mfma_f32_16x16x32_bf16 v[42:45], v[160:163], v[176:179], v[42:45]
	v_mfma_f32_16x16x32_bf16 v[30:33], v[146:149], v[204:207], v[30:33]
	v_mfma_f32_16x16x32_bf16 v[26:29], v[160:163], v[204:207], v[26:29]
	v_mfma_f32_16x16x32_bf16 v[14:17], v[146:149], v[212:215], v[14:17]
	v_mfma_f32_16x16x32_bf16 v[10:13], v[160:163], v[212:215], v[10:13]
	s_barrier
	s_add_i32 s4, s4, s25
	v_lshl_add_u64 v[142:143], v[236:237], 0, s[6:7]
	s_mov_b32 m0, s4
	s_nop 0
	global_load_lds_dwordx4 v[142:143], off
	v_lshl_add_u64 v[142:143], v[238:239], 0, s[6:7]
	s_add_i32 m0, s4, 0x2000
	s_nop 0
	global_load_lds_dwordx4 v[142:143], off
	s_add_u32 s0, s0, 0x100
	s_addc_u32 s1, s1, 0
	s_add_u32 s49, s49, 0x100
	s_addc_u32 s65, s65, 0
	s_cmp_ge_u32 s66, s35
	s_mov_b32 s4, s66
	s_waitcnt vmcnt(6)
	s_barrier
	v_mfma_f32_16x16x32_bf16 v[54:57], v[216:219], v[164:167], v[54:57]
	v_mfma_f32_16x16x32_bf16 v[50:53], v[224:227], v[164:167], v[50:53]
	v_mfma_f32_16x16x32_bf16 v[38:41], v[216:219], v[172:175], v[38:41]
	v_mfma_f32_16x16x32_bf16 v[34:37], v[224:227], v[172:175], v[34:37]
	v_mfma_f32_16x16x32_bf16 v[22:25], v[216:219], v[180:183], v[22:25]
	v_mfma_f32_16x16x32_bf16 v[18:21], v[224:227], v[180:183], v[18:21]
	v_mfma_f32_16x16x32_bf16 v[6:9], v[216:219], v[208:211], v[6:9]
	v_mfma_f32_16x16x32_bf16 v[2:5], v[224:227], v[208:211], v[2:5]
	v_mfma_f32_16x16x32_bf16 v[54:57], v[220:223], v[168:171], v[54:57]
	v_mfma_f32_16x16x32_bf16 v[50:53], v[228:231], v[168:171], v[50:53]
	v_mfma_f32_16x16x32_bf16 v[38:41], v[220:223], v[176:179], v[38:41]
	v_mfma_f32_16x16x32_bf16 v[34:37], v[228:231], v[176:179], v[34:37]
	v_mfma_f32_16x16x32_bf16 v[22:25], v[220:223], v[204:207], v[22:25]
	v_mfma_f32_16x16x32_bf16 v[18:21], v[228:231], v[204:207], v[18:21]
	v_mfma_f32_16x16x32_bf16 v[6:9], v[220:223], v[212:215], v[6:9]
	v_mfma_f32_16x16x32_bf16 v[2:5], v[228:231], v[212:215], v[2:5]
	s_barrier
	s_cbranch_scc1 .Lkexit_664
.LBB0_664:
	s_add_i32 s66, s4, 2
	s_add_u32 s18, s0, 0x80
	s_addc_u32 s5, s1, 0
	s_add_i32 s68, 0, 0x10000
	v_add_u32_e32 v150, s68, v153
	ds_read_b128 v[142:145], v150
	ds_read_b128 v[146:149], v150 offset:1024
	ds_read_b128 v[156:159], v150 offset:2048
	ds_read_b128 v[160:163], v150 offset:3072
	s_cmp_eq_u32 s43, s4
	s_cselect_b32 s4, s10, s18
	s_cselect_b32 s5, s11, s5
	s_cselect_b32 s19, s13, s65
	s_cselect_b32 s18, s12, s49
	v_lshl_add_u64 v[150:151], s[0:1], 0, v[138:139]
	s_add_i32 m0, s28, 0xc000
	ds_read_b128 v[164:167], v154
	ds_read_b128 v[168:171], v154 offset:1024
	ds_read_b128 v[172:175], v154 offset:2048
	ds_read_b128 v[176:179], v154 offset:3072
	ds_read_b128 v[180:183], v154 offset:4096
	ds_read_b128 v[204:207], v154 offset:5120
	ds_read_b128 v[208:211], v154 offset:6144
	ds_read_b128 v[212:215], v154 offset:7168
	global_load_lds_dwordx4 v[150:151], off
	v_lshl_add_u64 v[150:151], s[0:1], 0, v[140:141]
	s_add_i32 m0, s28, 0xe000
	s_nop 0
	global_load_lds_dwordx4 v[150:151], off
	s_waitcnt lgkmcnt(8)
	s_barrier
	s_waitcnt lgkmcnt(0)
	v_mfma_f32_16x16x32_bf16 v[126:129], v[142:145], v[164:167], v[126:129]
	v_mfma_f32_16x16x32_bf16 v[122:125], v[156:159], v[164:167], v[122:125]
	v_mfma_f32_16x16x32_bf16 v[110:113], v[142:145], v[172:175], v[110:113]
	v_mfma_f32_16x16x32_bf16 v[106:109], v[156:159], v[172:175], v[106:109]
	v_mfma_f32_16x16x32_bf16 v[94:97], v[142:145], v[180:183], v[94:97]
	v_mfma_f32_16x16x32_bf16 v[90:93], v[156:159], v[180:183], v[90:93]
	v_mfma_f32_16x16x32_bf16 v[78:81], v[142:145], v[208:211], v[78:81]
	v_mfma_f32_16x16x32_bf16 v[74:77], v[156:159], v[208:211], v[74:77]
	v_mfma_f32_16x16x32_bf16 v[126:129], v[146:149], v[168:171], v[126:129]
	v_mfma_f32_16x16x32_bf16 v[122:125], v[160:163], v[168:171], v[122:125]
	v_mfma_f32_16x16x32_bf16 v[110:113], v[146:149], v[176:179], v[110:113]
	v_mfma_f32_16x16x32_bf16 v[106:109], v[160:163], v[176:179], v[106:109]
	v_mfma_f32_16x16x32_bf16 v[94:97], v[146:149], v[204:207], v[94:97]
	v_mfma_f32_16x16x32_bf16 v[90:93], v[160:163], v[204:207], v[90:93]
	v_mfma_f32_16x16x32_bf16 v[78:81], v[146:149], v[212:215], v[78:81]
	v_mfma_f32_16x16x32_bf16 v[74:77], v[160:163], v[212:215], v[74:77]
	s_barrier
	s_add_i32 s69, 0, 0x14000
	v_add_u32_e32 v150, s69, v153
	s_add_i32 s68, s68, s25
	ds_read_b128 v[216:219], v150
	ds_read_b128 v[220:223], v150 offset:1024
	ds_read_b128 v[224:227], v150 offset:2048
	ds_read_b128 v[228:231], v150 offset:3072
	v_lshl_add_u64 v[150:151], s[18:19], 0, v[132:133]
	s_mov_b32 m0, s68
	v_lshl_add_u64 v[184:185], s[18:19], 0, v[136:137]
	global_load_lds_dwordx4 v[150:151], off
	s_add_i32 m0, s68, 0x2000
	s_nop 0
	global_load_lds_dwordx4 v[184:185], off
	s_barrier
	s_waitcnt lgkmcnt(0)
	v_mfma_f32_16x16x32_bf16 v[118:121], v[216:219], v[164:167], v[118:121]
	v_mfma_f32_16x16x32_bf16 v[114:117], v[224:227], v[164:167], v[114:117]
	v_mfma_f32_16x16x32_bf16 v[102:105], v[216:219], v[172:175], v[102:105]
	v_mfma_f32_16x16x32_bf16 v[98:101], v[224:227], v[172:175], v[98:101]
	v_mfma_f32_16x16x32_bf16 v[86:89], v[216:219], v[180:183], v[86:89]
	v_mfma_f32_16x16x32_bf16 v[82:85], v[224:227], v[180:183], v[82:85]
	v_mfma_f32_16x16x32_bf16 v[70:73], v[216:219], v[208:211], v[70:73]
	v_mfma_f32_16x16x32_bf16 v[66:69], v[224:227], v[208:211], v[66:69]
	v_mfma_f32_16x16x32_bf16 v[118:121], v[220:223], v[168:171], v[118:121]
	v_mfma_f32_16x16x32_bf16 v[114:117], v[228:231], v[168:171], v[114:117]
	v_mfma_f32_16x16x32_bf16 v[102:105], v[220:223], v[176:179], v[102:105]
	v_mfma_f32_16x16x32_bf16 v[98:101], v[228:231], v[176:179], v[98:101]
	v_mfma_f32_16x16x32_bf16 v[86:89], v[220:223], v[204:207], v[86:89]
	v_mfma_f32_16x16x32_bf16 v[82:85], v[228:231], v[204:207], v[82:85]
	v_mfma_f32_16x16x32_bf16 v[70:73], v[220:223], v[212:215], v[70:73]
	v_mfma_f32_16x16x32_bf16 v[66:69], v[228:231], v[212:215], v[66:69]
	s_barrier
	s_mov_b32 m0, s28
	v_lshl_add_u64 v[232:233], s[4:5], 0, v[130:131]
	ds_read_b128 v[164:167], v154 offset:16384
	ds_read_b128 v[168:171], v154 offset:17408
	ds_read_b128 v[172:175], v154 offset:18432
	ds_read_b128 v[176:179], v154 offset:19456
	ds_read_b128 v[180:183], v154 offset:20480
	ds_read_b128 v[204:207], v154 offset:21504
	ds_read_b128 v[208:211], v154 offset:22528
	ds_read_b128 v[212:215], v154 offset:23552
	global_load_lds_dwordx4 v[232:233], off
	v_lshl_add_u64 v[234:235], s[4:5], 0, v[134:135]
	s_mov_b32 m0, s29
	s_nop 0
	global_load_lds_dwordx4 v[234:235], off
	s_barrier
	s_waitcnt lgkmcnt(0)
	v_mfma_f32_16x16x32_bf16 v[62:65], v[142:145], v[164:167], v[62:65]
	v_mfma_f32_16x16x32_bf16 v[58:61], v[156:159], v[164:167], v[58:61]
	v_mfma_f32_16x16x32_bf16 v[46:49], v[142:145], v[172:175], v[46:49]
	v_mfma_f32_16x16x32_bf16 v[42:45], v[156:159], v[172:175], v[42:45]
	v_mfma_f32_16x16x32_bf16 v[30:33], v[142:145], v[180:183], v[30:33]
	v_mfma_f32_16x16x32_bf16 v[26:29], v[156:159], v[180:183], v[26:29]
	v_mfma_f32_16x16x32_bf16 v[14:17], v[142:145], v[208:211], v[14:17]
	v_mfma_f32_16x16x32_bf16 v[10:13], v[156:159], v[208:211], v[10:13]
	v_mfma_f32_16x16x32_bf16 v[62:65], v[146:149], v[168:171], v[62:65]
	v_mfma_f32_16x16x32_bf16 v[58:61], v[160:163], v[168:171], v[58:61]
	v_mfma_f32_16x16x32_bf16 v[46:49], v[146:149], v[176:179], v[46:49]
	v_mfma_f32_16x16x32_bf16 v[42:45], v[160:163], v[176:179], v[42:45]
	v_mfma_f32_16x16x32_bf16 v[30:33], v[146:149], v[204:207], v[30:33]
	v_mfma_f32_16x16x32_bf16 v[26:29], v[160:163], v[204:207], v[26:29]
	v_mfma_f32_16x16x32_bf16 v[14:17], v[146:149], v[212:215], v[14:17]
	v_mfma_f32_16x16x32_bf16 v[10:13], v[160:163], v[212:215], v[10:13]
	s_barrier
	s_add_u32 s18, s18, s14
	s_addc_u32 s19, s19, 0
	s_add_i32 s68, s69, s25
	v_lshl_add_u64 v[236:237], s[18:19], 0, v[132:133]
	s_mov_b32 m0, s68
	v_lshl_add_u64 v[238:239], s[18:19], 0, v[136:137]
	global_load_lds_dwordx4 v[236:237], off
	s_add_i32 m0, s68, 0x2000
	s_nop 0
	global_load_lds_dwordx4 v[238:239], off
	s_waitcnt vmcnt(6)
	s_barrier
	v_mfma_f32_16x16x32_bf16 v[54:57], v[216:219], v[164:167], v[54:57]
	v_mfma_f32_16x16x32_bf16 v[50:53], v[224:227], v[164:167], v[50:53]
	v_mfma_f32_16x16x32_bf16 v[38:41], v[216:219], v[172:175], v[38:41]
	v_mfma_f32_16x16x32_bf16 v[34:37], v[224:227], v[172:175], v[34:37]
	v_mfma_f32_16x16x32_bf16 v[22:25], v[216:219], v[180:183], v[22:25]
	v_mfma_f32_16x16x32_bf16 v[18:21], v[224:227], v[180:183], v[18:21]
	v_mfma_f32_16x16x32_bf16 v[6:9], v[216:219], v[208:211], v[6:9]
	v_mfma_f32_16x16x32_bf16 v[2:5], v[224:227], v[208:211], v[2:5]
	v_mfma_f32_16x16x32_bf16 v[54:57], v[220:223], v[168:171], v[54:57]
	v_mfma_f32_16x16x32_bf16 v[50:53], v[228:231], v[168:171], v[50:53]
	v_mfma_f32_16x16x32_bf16 v[38:41], v[220:223], v[176:179], v[38:41]
	v_mfma_f32_16x16x32_bf16 v[34:37], v[228:231], v[176:179], v[34:37]
	v_mfma_f32_16x16x32_bf16 v[22:25], v[220:223], v[204:207], v[22:25]
	v_mfma_f32_16x16x32_bf16 v[18:21], v[228:231], v[204:207], v[18:21]
	v_mfma_f32_16x16x32_bf16 v[6:9], v[220:223], v[212:215], v[6:9]
	v_mfma_f32_16x16x32_bf16 v[2:5], v[228:231], v[212:215], v[2:5]
	s_barrier
	s_add_i32 s18, 0, 0x18000
	v_add_u32_e32 v155, s18, v153
	ds_read_b128 v[142:145], v155
	ds_read_b128 v[146:149], v155 offset:1024
	ds_read_b128 v[156:159], v155 offset:2048
	ds_read_b128 v[160:163], v155 offset:3072
	s_add_u32 s4, s4, s14
	s_addc_u32 s5, s5, 0
	s_mov_b32 m0, s31
	v_lshl_add_u64 v[216:217], s[4:5], 0, v[130:131]
	ds_read_b128 v[164:167], v154 offset:32768
	ds_read_b128 v[168:171], v154 offset:33792
	ds_read_b128 v[172:175], v154 offset:34816
	ds_read_b128 v[176:179], v154 offset:35840
	ds_read_b128 v[180:183], v154 offset:36864
	ds_read_b128 v[204:207], v154 offset:37888
	ds_read_b128 v[208:211], v154 offset:38912
	ds_read_b128 v[212:215], v154 offset:39936
	global_load_lds_dwordx4 v[216:217], off
	v_lshl_add_u64 v[216:217], s[4:5], 0, v[134:135]
	s_mov_b32 m0, s34
	s_nop 0
	global_load_lds_dwordx4 v[216:217], off
	s_waitcnt lgkmcnt(8)
	s_barrier
	s_waitcnt lgkmcnt(0)
	v_mfma_f32_16x16x32_bf16 v[126:129], v[142:145], v[164:167], v[126:129]
	v_mfma_f32_16x16x32_bf16 v[122:125], v[156:159], v[164:167], v[122:125]
	v_mfma_f32_16x16x32_bf16 v[110:113], v[142:145], v[172:175], v[110:113]
	v_mfma_f32_16x16x32_bf16 v[106:109], v[156:159], v[172:175], v[106:109]
	v_mfma_f32_16x16x32_bf16 v[94:97], v[142:145], v[180:183], v[94:97]
	v_mfma_f32_16x16x32_bf16 v[90:93], v[156:159], v[180:183], v[90:93]
	v_mfma_f32_16x16x32_bf16 v[78:81], v[142:145], v[208:211], v[78:81]
	v_mfma_f32_16x16x32_bf16 v[74:77], v[156:159], v[208:211], v[74:77]
	v_mfma_f32_16x16x32_bf16 v[126:129], v[146:149], v[168:171], v[126:129]
	v_mfma_f32_16x16x32_bf16 v[122:125], v[160:163], v[168:171], v[122:125]
	v_mfma_f32_16x16x32_bf16 v[110:113], v[146:149], v[176:179], v[110:113]
	v_mfma_f32_16x16x32_bf16 v[106:109], v[160:163], v[176:179], v[106:109]
	v_mfma_f32_16x16x32_bf16 v[94:97], v[146:149], v[204:207], v[94:97]
	v_mfma_f32_16x16x32_bf16 v[90:93], v[160:163], v[204:207], v[90:93]
	v_mfma_f32_16x16x32_bf16 v[78:81], v[146:149], v[212:215], v[78:81]
	v_mfma_f32_16x16x32_bf16 v[74:77], v[160:163], v[212:215], v[74:77]
	s_barrier
	s_add_i32 s4, 0, 0x1c000
	s_add_i32 s5, s18, s25
	v_add_u32_e32 v155, s4, v153
	v_lshl_add_u64 v[150:151], v[150:151], 0, s[6:7]
	s_mov_b32 m0, s5
	ds_read_b128 v[216:219], v155
	ds_read_b128 v[220:223], v155 offset:1024
	ds_read_b128 v[224:227], v155 offset:2048
	ds_read_b128 v[228:231], v155 offset:3072
	global_load_lds_dwordx4 v[150:151], off
	v_lshl_add_u64 v[150:151], v[184:185], 0, s[6:7]
	s_add_i32 m0, s5, 0x2000
	s_nop 0
	global_load_lds_dwordx4 v[150:151], off
	s_barrier
	s_waitcnt lgkmcnt(0)
	v_mfma_f32_16x16x32_bf16 v[118:121], v[216:219], v[164:167], v[118:121]
	v_mfma_f32_16x16x32_bf16 v[114:117], v[224:227], v[164:167], v[114:117]
	v_mfma_f32_16x16x32_bf16 v[102:105], v[216:219], v[172:175], v[102:105]
	v_mfma_f32_16x16x32_bf16 v[98:101], v[224:227], v[172:175], v[98:101]
	v_mfma_f32_16x16x32_bf16 v[86:89], v[216:219], v[180:183], v[86:89]
	v_mfma_f32_16x16x32_bf16 v[82:85], v[224:227], v[180:183], v[82:85]
	v_mfma_f32_16x16x32_bf16 v[70:73], v[216:219], v[208:211], v[70:73]
	v_mfma_f32_16x16x32_bf16 v[66:69], v[224:227], v[208:211], v[66:69]
	v_mfma_f32_16x16x32_bf16 v[118:121], v[220:223], v[168:171], v[118:121]
	v_mfma_f32_16x16x32_bf16 v[114:117], v[228:231], v[168:171], v[114:117]
	v_mfma_f32_16x16x32_bf16 v[102:105], v[220:223], v[176:179], v[102:105]
	v_mfma_f32_16x16x32_bf16 v[98:101], v[228:231], v[176:179], v[98:101]
	v_mfma_f32_16x16x32_bf16 v[86:89], v[220:223], v[204:207], v[86:89]
	v_mfma_f32_16x16x32_bf16 v[82:85], v[228:231], v[204:207], v[82:85]
	v_mfma_f32_16x16x32_bf16 v[70:73], v[220:223], v[212:215], v[70:73]
	v_mfma_f32_16x16x32_bf16 v[66:69], v[228:231], v[212:215], v[66:69]
	s_barrier
	s_mov_b32 m0, s41
	v_lshl_add_u64 v[150:151], v[232:233], 0, s[6:7]
	ds_read_b128 v[164:167], v154 offset:49152
	ds_read_b128 v[168:171], v154 offset:50176
	ds_read_b128 v[172:175], v154 offset:51200
	ds_read_b128 v[176:179], v154 offset:52224
	ds_read_b128 v[180:183], v154 offset:53248
	ds_read_b128 v[204:207], v154 offset:54272
	ds_read_b128 v[208:211], v154 offset:55296
	ds_read_b128 v[212:215], v154 offset:56320
	global_load_lds_dwordx4 v[150:151], off
	v_lshl_add_u64 v[150:151], v[234:235], 0, s[6:7]
	s_mov_b32 m0, s42
	s_nop 0
	global_load_lds_dwordx4 v[150:151], off
	s_barrier
	s_waitcnt lgkmcnt(0)
	v_mfma_f32_16x16x32_bf16 v[62:65], v[142:145], v[164:167], v[62:65]
	v_mfma_f32_16x16x32_bf16 v[58:61], v[156:159], v[164:167], v[58:61]
	v_mfma_f32_16x16x32_bf16 v[46:49], v[142:145], v[172:175], v[46:49]
	v_mfma_f32_16x16x32_bf16 v[42:45], v[156:159], v[172:175], v[42:45]
	v_mfma_f32_16x16x32_bf16 v[30:33], v[142:145], v[180:183], v[30:33]
	v_mfma_f32_16x16x32_bf16 v[26:29], v[156:159], v[180:183], v[26:29]
	v_mfma_f32_16x16x32_bf16 v[14:17], v[142:145], v[208:211], v[14:17]
	v_mfma_f32_16x16x32_bf16 v[10:13], v[156:159], v[208:211], v[10:13]
	v_mfma_f32_16x16x32_bf16 v[62:65], v[146:149], v[168:171], v[62:65]
	v_mfma_f32_16x16x32_bf16 v[58:61], v[160:163], v[168:171], v[58:61]
	v_mfma_f32_16x16x32_bf16 v[46:49], v[146:149], v[176:179], v[46:49]
	v_mfma_f32_16x16x32_bf16 v[42:45], v[160:163], v[176:179], v[42:45]
	v_mfma_f32_16x16x32_bf16 v[30:33], v[146:149], v[204:207], v[30:33]
	v_mfma_f32_16x16x32_bf16 v[26:29], v[160:163], v[204:207], v[26:29]
	v_mfma_f32_16x16x32_bf16 v[14:17], v[146:149], v[212:215], v[14:17]
	v_mfma_f32_16x16x32_bf16 v[10:13], v[160:163], v[212:215], v[10:13]
	s_barrier
	s_add_i32 s4, s4, s25
	v_lshl_add_u64 v[142:143], v[236:237], 0, s[6:7]
	s_mov_b32 m0, s4
	s_nop 0
	global_load_lds_dwordx4 v[142:143], off
	v_lshl_add_u64 v[142:143], v[238:239], 0, s[6:7]
	s_add_i32 m0, s4, 0x2000
	s_nop 0
	global_load_lds_dwordx4 v[142:143], off
	s_add_u32 s0, s0, 0x100
	s_addc_u32 s1, s1, 0
	s_add_u32 s49, s49, 0x100
	s_addc_u32 s65, s65, 0
	s_cmp_ge_u32 s66, s35
	s_mov_b32 s4, s66
	s_waitcnt vmcnt(6)
	s_barrier
	v_mfma_f32_16x16x32_bf16 v[54:57], v[216:219], v[164:167], v[54:57]
	v_mfma_f32_16x16x32_bf16 v[50:53], v[224:227], v[164:167], v[50:53]
	v_mfma_f32_16x16x32_bf16 v[38:41], v[216:219], v[172:175], v[38:41]
	v_mfma_f32_16x16x32_bf16 v[34:37], v[224:227], v[172:175], v[34:37]
	v_mfma_f32_16x16x32_bf16 v[22:25], v[216:219], v[180:183], v[22:25]
	v_mfma_f32_16x16x32_bf16 v[18:21], v[224:227], v[180:183], v[18:21]
	v_mfma_f32_16x16x32_bf16 v[6:9], v[216:219], v[208:211], v[6:9]
	v_mfma_f32_16x16x32_bf16 v[2:5], v[224:227], v[208:211], v[2:5]
	v_mfma_f32_16x16x32_bf16 v[54:57], v[220:223], v[168:171], v[54:57]
	v_mfma_f32_16x16x32_bf16 v[50:53], v[228:231], v[168:171], v[50:53]
	v_mfma_f32_16x16x32_bf16 v[38:41], v[220:223], v[176:179], v[38:41]
	v_mfma_f32_16x16x32_bf16 v[34:37], v[228:231], v[176:179], v[34:37]
	v_mfma_f32_16x16x32_bf16 v[22:25], v[220:223], v[204:207], v[22:25]
	v_mfma_f32_16x16x32_bf16 v[18:21], v[228:231], v[204:207], v[18:21]
	v_mfma_f32_16x16x32_bf16 v[6:9], v[220:223], v[212:215], v[6:9]
	v_mfma_f32_16x16x32_bf16 v[2:5], v[228:231], v[212:215], v[2:5]
	s_barrier
	s_cbranch_scc0 .LBB0_664

.LBB0_697:
	s_add_u32 s0, s0, 0x80
	s_addc_u32 s1, s1, 0
	s_add_u32 s48, s4, 0x100
	s_addc_u32 s49, s5, 0
	s_mov_b32 s4, 0
	s_waitcnt lgkmcnt(0)
	s_waitcnt vmcnt(0)
	s_add_i32 s65, s4, 2
	s_add_u32 s18, s0, 0x80
	s_addc_u32 s5, s1, 0
	s_add_i32 s66, 0, 0x10000
	v_add_u32_e32 v146, s66, v149
	ds_read_b128 v[142:145], v146
	ds_read_b128 v[152:155], v146 offset:1024
	ds_read_b128 v[156:159], v146 offset:2048
	ds_read_b128 v[160:163], v146 offset:3072
	s_cmp_eq_u32 s34, s4
	s_cselect_b32 s4, s10, s18
	s_cselect_b32 s5, s11, s5
	s_cselect_b32 s19, s13, s49
	s_cselect_b32 s18, s12, s48
	v_lshl_add_u64 v[146:147], s[0:1], 0, v[138:139]
	s_add_i32 m0, s22, 0xc000
	ds_read_b128 v[164:167], v150
	ds_read_b128 v[168:171], v150 offset:1024
	ds_read_b128 v[172:175], v150 offset:2048
	ds_read_b128 v[176:179], v150 offset:3072
	ds_read_b128 v[180:183], v150 offset:4096
	ds_read_b128 v[204:207], v150 offset:5120
	ds_read_b128 v[208:211], v150 offset:6144
	ds_read_b128 v[212:215], v150 offset:7168
	global_load_lds_dwordx4 v[146:147], off
	v_lshl_add_u64 v[146:147], s[0:1], 0, v[140:141]
	s_add_i32 m0, s22, 0xe000
	s_nop 0
	global_load_lds_dwordx4 v[146:147], off
	s_waitcnt lgkmcnt(8)
	s_barrier
	s_waitcnt lgkmcnt(0)
	v_mfma_f32_16x16x32_bf16 v[126:129], v[142:145], v[164:167], 0
	v_mfma_f32_16x16x32_bf16 v[122:125], v[156:159], v[164:167], 0
	v_mfma_f32_16x16x32_bf16 v[110:113], v[142:145], v[172:175], 0
	v_mfma_f32_16x16x32_bf16 v[106:109], v[156:159], v[172:175], 0
	v_mfma_f32_16x16x32_bf16 v[94:97], v[142:145], v[180:183], 0
	v_mfma_f32_16x16x32_bf16 v[90:93], v[156:159], v[180:183], 0
	v_mfma_f32_16x16x32_bf16 v[78:81], v[142:145], v[208:211], 0
	v_mfma_f32_16x16x32_bf16 v[74:77], v[156:159], v[208:211], 0
	v_mfma_f32_16x16x32_bf16 v[126:129], v[152:155], v[168:171], v[126:129]
	v_mfma_f32_16x16x32_bf16 v[122:125], v[160:163], v[168:171], v[122:125]
	v_mfma_f32_16x16x32_bf16 v[110:113], v[152:155], v[176:179], v[110:113]
	v_mfma_f32_16x16x32_bf16 v[106:109], v[160:163], v[176:179], v[106:109]
	v_mfma_f32_16x16x32_bf16 v[94:97], v[152:155], v[204:207], v[94:97]
	v_mfma_f32_16x16x32_bf16 v[90:93], v[160:163], v[204:207], v[90:93]
	v_mfma_f32_16x16x32_bf16 v[78:81], v[152:155], v[212:215], v[78:81]
	v_mfma_f32_16x16x32_bf16 v[74:77], v[160:163], v[212:215], v[74:77]
	s_barrier
	s_add_i32 s67, 0, 0x14000
	v_add_u32_e32 v146, s67, v149
	s_add_i32 s66, s66, s21
	ds_read_b128 v[216:219], v146
	ds_read_b128 v[220:223], v146 offset:1024
	ds_read_b128 v[224:227], v146 offset:2048
	ds_read_b128 v[228:231], v146 offset:3072
	v_lshl_add_u64 v[146:147], s[18:19], 0, v[132:133]
	s_mov_b32 m0, s66
	v_lshl_add_u64 v[184:185], s[18:19], 0, v[136:137]
	global_load_lds_dwordx4 v[146:147], off
	s_add_i32 m0, s66, 0x2000
	s_nop 0
	global_load_lds_dwordx4 v[184:185], off
	s_barrier
	s_waitcnt lgkmcnt(0)
	v_mfma_f32_16x16x32_bf16 v[118:121], v[216:219], v[164:167], 0
	v_mfma_f32_16x16x32_bf16 v[114:117], v[224:227], v[164:167], 0
	v_mfma_f32_16x16x32_bf16 v[102:105], v[216:219], v[172:175], 0
	v_mfma_f32_16x16x32_bf16 v[98:101], v[224:227], v[172:175], 0
	v_mfma_f32_16x16x32_bf16 v[86:89], v[216:219], v[180:183], 0
	v_mfma_f32_16x16x32_bf16 v[82:85], v[224:227], v[180:183], 0
	v_mfma_f32_16x16x32_bf16 v[70:73], v[216:219], v[208:211], 0
	v_mfma_f32_16x16x32_bf16 v[66:69], v[224:227], v[208:211], 0
	v_mfma_f32_16x16x32_bf16 v[118:121], v[220:223], v[168:171], v[118:121]
	v_mfma_f32_16x16x32_bf16 v[114:117], v[228:231], v[168:171], v[114:117]
	v_mfma_f32_16x16x32_bf16 v[102:105], v[220:223], v[176:179], v[102:105]
	v_mfma_f32_16x16x32_bf16 v[98:101], v[228:231], v[176:179], v[98:101]
	v_mfma_f32_16x16x32_bf16 v[86:89], v[220:223], v[204:207], v[86:89]
	v_mfma_f32_16x16x32_bf16 v[82:85], v[228:231], v[204:207], v[82:85]
	v_mfma_f32_16x16x32_bf16 v[70:73], v[220:223], v[212:215], v[70:73]
	v_mfma_f32_16x16x32_bf16 v[66:69], v[228:231], v[212:215], v[66:69]
	s_barrier
	s_mov_b32 m0, s22
	v_lshl_add_u64 v[232:233], s[4:5], 0, v[130:131]
	ds_read_b128 v[164:167], v150 offset:16384
	ds_read_b128 v[168:171], v150 offset:17408
	ds_read_b128 v[172:175], v150 offset:18432
	ds_read_b128 v[176:179], v150 offset:19456
	ds_read_b128 v[180:183], v150 offset:20480
	ds_read_b128 v[204:207], v150 offset:21504
	ds_read_b128 v[208:211], v150 offset:22528
	ds_read_b128 v[212:215], v150 offset:23552
	global_load_lds_dwordx4 v[232:233], off
	v_lshl_add_u64 v[234:235], s[4:5], 0, v[134:135]
	s_mov_b32 m0, s23
	s_nop 0
	global_load_lds_dwordx4 v[234:235], off
	s_barrier
	s_waitcnt lgkmcnt(0)
	v_mfma_f32_16x16x32_bf16 v[62:65], v[142:145], v[164:167], 0
	v_mfma_f32_16x16x32_bf16 v[58:61], v[156:159], v[164:167], 0
	v_mfma_f32_16x16x32_bf16 v[46:49], v[142:145], v[172:175], 0
	v_mfma_f32_16x16x32_bf16 v[42:45], v[156:159], v[172:175], 0
	v_mfma_f32_16x16x32_bf16 v[30:33], v[142:145], v[180:183], 0
	v_mfma_f32_16x16x32_bf16 v[26:29], v[156:159], v[180:183], 0
	v_mfma_f32_16x16x32_bf16 v[14:17], v[142:145], v[208:211], 0
	v_mfma_f32_16x16x32_bf16 v[10:13], v[156:159], v[208:211], 0
	v_mfma_f32_16x16x32_bf16 v[62:65], v[152:155], v[168:171], v[62:65]
	v_mfma_f32_16x16x32_bf16 v[58:61], v[160:163], v[168:171], v[58:61]
	v_mfma_f32_16x16x32_bf16 v[46:49], v[152:155], v[176:179], v[46:49]
	v_mfma_f32_16x16x32_bf16 v[42:45], v[160:163], v[176:179], v[42:45]
	v_mfma_f32_16x16x32_bf16 v[30:33], v[152:155], v[204:207], v[30:33]
	v_mfma_f32_16x16x32_bf16 v[26:29], v[160:163], v[204:207], v[26:29]
	v_mfma_f32_16x16x32_bf16 v[14:17], v[152:155], v[212:215], v[14:17]
	v_mfma_f32_16x16x32_bf16 v[10:13], v[160:163], v[212:215], v[10:13]
	s_barrier
	s_add_u32 s18, s18, s2
	s_addc_u32 s19, s19, 0
	s_add_i32 s66, s67, s21
	v_lshl_add_u64 v[236:237], s[18:19], 0, v[132:133]
	s_mov_b32 m0, s66
	v_lshl_add_u64 v[238:239], s[18:19], 0, v[136:137]
	global_load_lds_dwordx4 v[236:237], off
	s_add_i32 m0, s66, 0x2000
	s_nop 0
	global_load_lds_dwordx4 v[238:239], off
	s_waitcnt vmcnt(6)
	s_barrier
	v_mfma_f32_16x16x32_bf16 v[54:57], v[216:219], v[164:167], 0
	v_mfma_f32_16x16x32_bf16 v[50:53], v[224:227], v[164:167], 0
	v_mfma_f32_16x16x32_bf16 v[38:41], v[216:219], v[172:175], 0
	v_mfma_f32_16x16x32_bf16 v[34:37], v[224:227], v[172:175], 0
	v_mfma_f32_16x16x32_bf16 v[22:25], v[216:219], v[180:183], 0
	v_mfma_f32_16x16x32_bf16 v[18:21], v[224:227], v[180:183], 0
	v_mfma_f32_16x16x32_bf16 v[6:9], v[216:219], v[208:211], 0
	v_mfma_f32_16x16x32_bf16 v[2:5], v[224:227], v[208:211], 0
	v_mfma_f32_16x16x32_bf16 v[54:57], v[220:223], v[168:171], v[54:57]
	v_mfma_f32_16x16x32_bf16 v[50:53], v[228:231], v[168:171], v[50:53]
	v_mfma_f32_16x16x32_bf16 v[38:41], v[220:223], v[176:179], v[38:41]
	v_mfma_f32_16x16x32_bf16 v[34:37], v[228:231], v[176:179], v[34:37]
	v_mfma_f32_16x16x32_bf16 v[22:25], v[220:223], v[204:207], v[22:25]
	v_mfma_f32_16x16x32_bf16 v[18:21], v[228:231], v[204:207], v[18:21]
	v_mfma_f32_16x16x32_bf16 v[6:9], v[220:223], v[212:215], v[6:9]
	v_mfma_f32_16x16x32_bf16 v[2:5], v[228:231], v[212:215], v[2:5]
	s_barrier
	s_add_i32 s18, 0, 0x18000
	v_add_u32_e32 v151, s18, v149
	ds_read_b128 v[142:145], v151
	ds_read_b128 v[152:155], v151 offset:1024
	ds_read_b128 v[156:159], v151 offset:2048
	ds_read_b128 v[160:163], v151 offset:3072
	s_add_u32 s4, s4, s2
	s_addc_u32 s5, s5, 0
	s_mov_b32 m0, s24
	v_lshl_add_u64 v[216:217], s[4:5], 0, v[130:131]
	ds_read_b128 v[164:167], v150 offset:32768
	ds_read_b128 v[168:171], v150 offset:33792
	ds_read_b128 v[172:175], v150 offset:34816
	ds_read_b128 v[176:179], v150 offset:35840
	ds_read_b128 v[180:183], v150 offset:36864
	ds_read_b128 v[204:207], v150 offset:37888
	ds_read_b128 v[208:211], v150 offset:38912
	ds_read_b128 v[212:215], v150 offset:39936
	global_load_lds_dwordx4 v[216:217], off
	v_lshl_add_u64 v[216:217], s[4:5], 0, v[134:135]
	s_mov_b32 m0, s25
	s_nop 0
	global_load_lds_dwordx4 v[216:217], off
	s_waitcnt lgkmcnt(8)
	s_barrier
	s_waitcnt lgkmcnt(0)
	v_mfma_f32_16x16x32_bf16 v[126:129], v[142:145], v[164:167], v[126:129]
	v_mfma_f32_16x16x32_bf16 v[122:125], v[156:159], v[164:167], v[122:125]
	v_mfma_f32_16x16x32_bf16 v[110:113], v[142:145], v[172:175], v[110:113]
	v_mfma_f32_16x16x32_bf16 v[106:109], v[156:159], v[172:175], v[106:109]
	v_mfma_f32_16x16x32_bf16 v[94:97], v[142:145], v[180:183], v[94:97]
	v_mfma_f32_16x16x32_bf16 v[90:93], v[156:159], v[180:183], v[90:93]
	v_mfma_f32_16x16x32_bf16 v[78:81], v[142:145], v[208:211], v[78:81]
	v_mfma_f32_16x16x32_bf16 v[74:77], v[156:159], v[208:211], v[74:77]
	v_mfma_f32_16x16x32_bf16 v[126:129], v[152:155], v[168:171], v[126:129]
	v_mfma_f32_16x16x32_bf16 v[122:125], v[160:163], v[168:171], v[122:125]
	v_mfma_f32_16x16x32_bf16 v[110:113], v[152:155], v[176:179], v[110:113]
	v_mfma_f32_16x16x32_bf16 v[106:109], v[160:163], v[176:179], v[106:109]
	v_mfma_f32_16x16x32_bf16 v[94:97], v[152:155], v[204:207], v[94:97]
	v_mfma_f32_16x16x32_bf16 v[90:93], v[160:163], v[204:207], v[90:93]
	v_mfma_f32_16x16x32_bf16 v[78:81], v[152:155], v[212:215], v[78:81]
	v_mfma_f32_16x16x32_bf16 v[74:77], v[160:163], v[212:215], v[74:77]
	s_barrier
	s_add_i32 s4, 0, 0x1c000
	s_add_i32 s5, s18, s21
	v_add_u32_e32 v151, s4, v149
	v_lshl_add_u64 v[146:147], v[146:147], 0, s[6:7]
	s_mov_b32 m0, s5
	ds_read_b128 v[216:219], v151
	ds_read_b128 v[220:223], v151 offset:1024
	ds_read_b128 v[224:227], v151 offset:2048
	ds_read_b128 v[228:231], v151 offset:3072
	global_load_lds_dwordx4 v[146:147], off
	v_lshl_add_u64 v[146:147], v[184:185], 0, s[6:7]
	s_add_i32 m0, s5, 0x2000
	s_nop 0
	global_load_lds_dwordx4 v[146:147], off
	s_barrier
	s_waitcnt lgkmcnt(0)
	v_mfma_f32_16x16x32_bf16 v[118:121], v[216:219], v[164:167], v[118:121]
	v_mfma_f32_16x16x32_bf16 v[114:117], v[224:227], v[164:167], v[114:117]
	v_mfma_f32_16x16x32_bf16 v[102:105], v[216:219], v[172:175], v[102:105]
	v_mfma_f32_16x16x32_bf16 v[98:101], v[224:227], v[172:175], v[98:101]
	v_mfma_f32_16x16x32_bf16 v[86:89], v[216:219], v[180:183], v[86:89]
	v_mfma_f32_16x16x32_bf16 v[82:85], v[224:227], v[180:183], v[82:85]
	v_mfma_f32_16x16x32_bf16 v[70:73], v[216:219], v[208:211], v[70:73]
	v_mfma_f32_16x16x32_bf16 v[66:69], v[224:227], v[208:211], v[66:69]
	v_mfma_f32_16x16x32_bf16 v[118:121], v[220:223], v[168:171], v[118:121]
	v_mfma_f32_16x16x32_bf16 v[114:117], v[228:231], v[168:171], v[114:117]
	v_mfma_f32_16x16x32_bf16 v[102:105], v[220:223], v[176:179], v[102:105]
	v_mfma_f32_16x16x32_bf16 v[98:101], v[228:231], v[176:179], v[98:101]
	v_mfma_f32_16x16x32_bf16 v[86:89], v[220:223], v[204:207], v[86:89]
	v_mfma_f32_16x16x32_bf16 v[82:85], v[228:231], v[204:207], v[82:85]
	v_mfma_f32_16x16x32_bf16 v[70:73], v[220:223], v[212:215], v[70:73]
	v_mfma_f32_16x16x32_bf16 v[66:69], v[228:231], v[212:215], v[66:69]
	s_barrier
	s_mov_b32 m0, s30
	v_lshl_add_u64 v[146:147], v[232:233], 0, s[6:7]
	ds_read_b128 v[164:167], v150 offset:49152
	ds_read_b128 v[168:171], v150 offset:50176
	ds_read_b128 v[172:175], v150 offset:51200
	ds_read_b128 v[176:179], v150 offset:52224
	ds_read_b128 v[180:183], v150 offset:53248
	ds_read_b128 v[204:207], v150 offset:54272
	ds_read_b128 v[208:211], v150 offset:55296
	ds_read_b128 v[212:215], v150 offset:56320
	global_load_lds_dwordx4 v[146:147], off
	v_lshl_add_u64 v[146:147], v[234:235], 0, s[6:7]
	s_mov_b32 m0, s31
	s_nop 0
	global_load_lds_dwordx4 v[146:147], off
	s_barrier
	s_waitcnt lgkmcnt(0)
	v_mfma_f32_16x16x32_bf16 v[62:65], v[142:145], v[164:167], v[62:65]
	v_mfma_f32_16x16x32_bf16 v[58:61], v[156:159], v[164:167], v[58:61]
	v_mfma_f32_16x16x32_bf16 v[46:49], v[142:145], v[172:175], v[46:49]
	v_mfma_f32_16x16x32_bf16 v[42:45], v[156:159], v[172:175], v[42:45]
	v_mfma_f32_16x16x32_bf16 v[30:33], v[142:145], v[180:183], v[30:33]
	v_mfma_f32_16x16x32_bf16 v[26:29], v[156:159], v[180:183], v[26:29]
	v_mfma_f32_16x16x32_bf16 v[14:17], v[142:145], v[208:211], v[14:17]
	v_mfma_f32_16x16x32_bf16 v[10:13], v[156:159], v[208:211], v[10:13]
	v_mfma_f32_16x16x32_bf16 v[62:65], v[152:155], v[168:171], v[62:65]
	v_mfma_f32_16x16x32_bf16 v[58:61], v[160:163], v[168:171], v[58:61]
	v_mfma_f32_16x16x32_bf16 v[46:49], v[152:155], v[176:179], v[46:49]
	v_mfma_f32_16x16x32_bf16 v[42:45], v[160:163], v[176:179], v[42:45]
	v_mfma_f32_16x16x32_bf16 v[30:33], v[152:155], v[204:207], v[30:33]
	v_mfma_f32_16x16x32_bf16 v[26:29], v[160:163], v[204:207], v[26:29]
	v_mfma_f32_16x16x32_bf16 v[14:17], v[152:155], v[212:215], v[14:17]
	v_mfma_f32_16x16x32_bf16 v[10:13], v[160:163], v[212:215], v[10:13]
	s_barrier
	s_add_i32 s4, s4, s21
	v_lshl_add_u64 v[142:143], v[236:237], 0, s[6:7]
	s_mov_b32 m0, s4
	s_nop 0
	global_load_lds_dwordx4 v[142:143], off
	v_lshl_add_u64 v[142:143], v[238:239], 0, s[6:7]
	s_add_i32 m0, s4, 0x2000
	s_nop 0
	global_load_lds_dwordx4 v[142:143], off
	s_add_u32 s0, s0, 0x100
	s_addc_u32 s1, s1, 0
	s_add_u32 s48, s48, 0x100
	s_addc_u32 s49, s49, 0
	s_cmp_ge_u32 s65, s27
	s_mov_b32 s4, s65
	s_waitcnt vmcnt(6)
	s_barrier
	v_mfma_f32_16x16x32_bf16 v[54:57], v[216:219], v[164:167], v[54:57]
	v_mfma_f32_16x16x32_bf16 v[50:53], v[224:227], v[164:167], v[50:53]
	v_mfma_f32_16x16x32_bf16 v[38:41], v[216:219], v[172:175], v[38:41]
	v_mfma_f32_16x16x32_bf16 v[34:37], v[224:227], v[172:175], v[34:37]
	v_mfma_f32_16x16x32_bf16 v[22:25], v[216:219], v[180:183], v[22:25]
	v_mfma_f32_16x16x32_bf16 v[18:21], v[224:227], v[180:183], v[18:21]
	v_mfma_f32_16x16x32_bf16 v[6:9], v[216:219], v[208:211], v[6:9]
	v_mfma_f32_16x16x32_bf16 v[2:5], v[224:227], v[208:211], v[2:5]
	v_mfma_f32_16x16x32_bf16 v[54:57], v[220:223], v[168:171], v[54:57]
	v_mfma_f32_16x16x32_bf16 v[50:53], v[228:231], v[168:171], v[50:53]
	v_mfma_f32_16x16x32_bf16 v[38:41], v[220:223], v[176:179], v[38:41]
	v_mfma_f32_16x16x32_bf16 v[34:37], v[228:231], v[176:179], v[34:37]
	v_mfma_f32_16x16x32_bf16 v[22:25], v[220:223], v[204:207], v[22:25]
	v_mfma_f32_16x16x32_bf16 v[18:21], v[228:231], v[204:207], v[18:21]
	v_mfma_f32_16x16x32_bf16 v[6:9], v[220:223], v[212:215], v[6:9]
	v_mfma_f32_16x16x32_bf16 v[2:5], v[228:231], v[212:215], v[2:5]
	s_barrier
	s_cbranch_scc1 .Lkexit_698
.LBB0_698:
	s_add_i32 s65, s4, 2
	s_add_u32 s18, s0, 0x80
	s_addc_u32 s5, s1, 0
	s_add_i32 s66, 0, 0x10000
	v_add_u32_e32 v146, s66, v149
	ds_read_b128 v[142:145], v146
	ds_read_b128 v[152:155], v146 offset:1024
	ds_read_b128 v[156:159], v146 offset:2048
	ds_read_b128 v[160:163], v146 offset:3072
	s_cmp_eq_u32 s34, s4
	s_cselect_b32 s4, s10, s18
	s_cselect_b32 s5, s11, s5
	s_cselect_b32 s19, s13, s49
	s_cselect_b32 s18, s12, s48
	v_lshl_add_u64 v[146:147], s[0:1], 0, v[138:139]
	s_add_i32 m0, s22, 0xc000
	ds_read_b128 v[164:167], v150
	ds_read_b128 v[168:171], v150 offset:1024
	ds_read_b128 v[172:175], v150 offset:2048
	ds_read_b128 v[176:179], v150 offset:3072
	ds_read_b128 v[180:183], v150 offset:4096
	ds_read_b128 v[204:207], v150 offset:5120
	ds_read_b128 v[208:211], v150 offset:6144
	ds_read_b128 v[212:215], v150 offset:7168
	global_load_lds_dwordx4 v[146:147], off
	v_lshl_add_u64 v[146:147], s[0:1], 0, v[140:141]
	s_add_i32 m0, s22, 0xe000
	s_nop 0
	global_load_lds_dwordx4 v[146:147], off
	s_waitcnt lgkmcnt(8)
	s_barrier
	s_waitcnt lgkmcnt(0)
	v_mfma_f32_16x16x32_bf16 v[126:129], v[142:145], v[164:167], v[126:129]
	v_mfma_f32_16x16x32_bf16 v[122:125], v[156:159], v[164:167], v[122:125]
	v_mfma_f32_16x16x32_bf16 v[110:113], v[142:145], v[172:175], v[110:113]
	v_mfma_f32_16x16x32_bf16 v[106:109], v[156:159], v[172:175], v[106:109]
	v_mfma_f32_16x16x32_bf16 v[94:97], v[142:145], v[180:183], v[94:97]
	v_mfma_f32_16x16x32_bf16 v[90:93], v[156:159], v[180:183], v[90:93]
	v_mfma_f32_16x16x32_bf16 v[78:81], v[142:145], v[208:211], v[78:81]
	v_mfma_f32_16x16x32_bf16 v[74:77], v[156:159], v[208:211], v[74:77]
	v_mfma_f32_16x16x32_bf16 v[126:129], v[152:155], v[168:171], v[126:129]
	v_mfma_f32_16x16x32_bf16 v[122:125], v[160:163], v[168:171], v[122:125]
	v_mfma_f32_16x16x32_bf16 v[110:113], v[152:155], v[176:179], v[110:113]
	v_mfma_f32_16x16x32_bf16 v[106:109], v[160:163], v[176:179], v[106:109]
	v_mfma_f32_16x16x32_bf16 v[94:97], v[152:155], v[204:207], v[94:97]
	v_mfma_f32_16x16x32_bf16 v[90:93], v[160:163], v[204:207], v[90:93]
	v_mfma_f32_16x16x32_bf16 v[78:81], v[152:155], v[212:215], v[78:81]
	v_mfma_f32_16x16x32_bf16 v[74:77], v[160:163], v[212:215], v[74:77]
	s_barrier
	s_add_i32 s67, 0, 0x14000
	v_add_u32_e32 v146, s67, v149
	s_add_i32 s66, s66, s21
	ds_read_b128 v[216:219], v146
	ds_read_b128 v[220:223], v146 offset:1024
	ds_read_b128 v[224:227], v146 offset:2048
	ds_read_b128 v[228:231], v146 offset:3072
	v_lshl_add_u64 v[146:147], s[18:19], 0, v[132:133]
	s_mov_b32 m0, s66
	v_lshl_add_u64 v[184:185], s[18:19], 0, v[136:137]
	global_load_lds_dwordx4 v[146:147], off
	s_add_i32 m0, s66, 0x2000
	s_nop 0
	global_load_lds_dwordx4 v[184:185], off
	s_barrier
	s_waitcnt lgkmcnt(0)
	v_mfma_f32_16x16x32_bf16 v[118:121], v[216:219], v[164:167], v[118:121]
	v_mfma_f32_16x16x32_bf16 v[114:117], v[224:227], v[164:167], v[114:117]
	v_mfma_f32_16x16x32_bf16 v[102:105], v[216:219], v[172:175], v[102:105]
	v_mfma_f32_16x16x32_bf16 v[98:101], v[224:227], v[172:175], v[98:101]
	v_mfma_f32_16x16x32_bf16 v[86:89], v[216:219], v[180:183], v[86:89]
	v_mfma_f32_16x16x32_bf16 v[82:85], v[224:227], v[180:183], v[82:85]
	v_mfma_f32_16x16x32_bf16 v[70:73], v[216:219], v[208:211], v[70:73]
	v_mfma_f32_16x16x32_bf16 v[66:69], v[224:227], v[208:211], v[66:69]
	v_mfma_f32_16x16x32_bf16 v[118:121], v[220:223], v[168:171], v[118:121]
	v_mfma_f32_16x16x32_bf16 v[114:117], v[228:231], v[168:171], v[114:117]
	v_mfma_f32_16x16x32_bf16 v[102:105], v[220:223], v[176:179], v[102:105]
	v_mfma_f32_16x16x32_bf16 v[98:101], v[228:231], v[176:179], v[98:101]
	v_mfma_f32_16x16x32_bf16 v[86:89], v[220:223], v[204:207], v[86:89]
	v_mfma_f32_16x16x32_bf16 v[82:85], v[228:231], v[204:207], v[82:85]
	v_mfma_f32_16x16x32_bf16 v[70:73], v[220:223], v[212:215], v[70:73]
	v_mfma_f32_16x16x32_bf16 v[66:69], v[228:231], v[212:215], v[66:69]
	s_barrier
	s_mov_b32 m0, s22
	v_lshl_add_u64 v[232:233], s[4:5], 0, v[130:131]
	ds_read_b128 v[164:167], v150 offset:16384
	ds_read_b128 v[168:171], v150 offset:17408
	ds_read_b128 v[172:175], v150 offset:18432
	ds_read_b128 v[176:179], v150 offset:19456
	ds_read_b128 v[180:183], v150 offset:20480
	ds_read_b128 v[204:207], v150 offset:21504
	ds_read_b128 v[208:211], v150 offset:22528
	ds_read_b128 v[212:215], v150 offset:23552
	global_load_lds_dwordx4 v[232:233], off
	v_lshl_add_u64 v[234:235], s[4:5], 0, v[134:135]
	s_mov_b32 m0, s23
	s_nop 0
	global_load_lds_dwordx4 v[234:235], off
	s_barrier
	s_waitcnt lgkmcnt(0)
	v_mfma_f32_16x16x32_bf16 v[62:65], v[142:145], v[164:167], v[62:65]
	v_mfma_f32_16x16x32_bf16 v[58:61], v[156:159], v[164:167], v[58:61]
	v_mfma_f32_16x16x32_bf16 v[46:49], v[142:145], v[172:175], v[46:49]
	v_mfma_f32_16x16x32_bf16 v[42:45], v[156:159], v[172:175], v[42:45]
	v_mfma_f32_16x16x32_bf16 v[30:33], v[142:145], v[180:183], v[30:33]
	v_mfma_f32_16x16x32_bf16 v[26:29], v[156:159], v[180:183], v[26:29]
	v_mfma_f32_16x16x32_bf16 v[14:17], v[142:145], v[208:211], v[14:17]
	v_mfma_f32_16x16x32_bf16 v[10:13], v[156:159], v[208:211], v[10:13]
	v_mfma_f32_16x16x32_bf16 v[62:65], v[152:155], v[168:171], v[62:65]
	v_mfma_f32_16x16x32_bf16 v[58:61], v[160:163], v[168:171], v[58:61]
	v_mfma_f32_16x16x32_bf16 v[46:49], v[152:155], v[176:179], v[46:49]
	v_mfma_f32_16x16x32_bf16 v[42:45], v[160:163], v[176:179], v[42:45]
	v_mfma_f32_16x16x32_bf16 v[30:33], v[152:155], v[204:207], v[30:33]
	v_mfma_f32_16x16x32_bf16 v[26:29], v[160:163], v[204:207], v[26:29]
	v_mfma_f32_16x16x32_bf16 v[14:17], v[152:155], v[212:215], v[14:17]
	v_mfma_f32_16x16x32_bf16 v[10:13], v[160:163], v[212:215], v[10:13]
	s_barrier
	s_add_u32 s18, s18, s2
	s_addc_u32 s19, s19, 0
	s_add_i32 s66, s67, s21
	v_lshl_add_u64 v[236:237], s[18:19], 0, v[132:133]
	s_mov_b32 m0, s66
	v_lshl_add_u64 v[238:239], s[18:19], 0, v[136:137]
	global_load_lds_dwordx4 v[236:237], off
	s_add_i32 m0, s66, 0x2000
	s_nop 0
	global_load_lds_dwordx4 v[238:239], off
	s_waitcnt vmcnt(6)
	s_barrier
	v_mfma_f32_16x16x32_bf16 v[54:57], v[216:219], v[164:167], v[54:57]
	v_mfma_f32_16x16x32_bf16 v[50:53], v[224:227], v[164:167], v[50:53]
	v_mfma_f32_16x16x32_bf16 v[38:41], v[216:219], v[172:175], v[38:41]
	v_mfma_f32_16x16x32_bf16 v[34:37], v[224:227], v[172:175], v[34:37]
	v_mfma_f32_16x16x32_bf16 v[22:25], v[216:219], v[180:183], v[22:25]
	v_mfma_f32_16x16x32_bf16 v[18:21], v[224:227], v[180:183], v[18:21]
	v_mfma_f32_16x16x32_bf16 v[6:9], v[216:219], v[208:211], v[6:9]
	v_mfma_f32_16x16x32_bf16 v[2:5], v[224:227], v[208:211], v[2:5]
	v_mfma_f32_16x16x32_bf16 v[54:57], v[220:223], v[168:171], v[54:57]
	v_mfma_f32_16x16x32_bf16 v[50:53], v[228:231], v[168:171], v[50:53]
	v_mfma_f32_16x16x32_bf16 v[38:41], v[220:223], v[176:179], v[38:41]
	v_mfma_f32_16x16x32_bf16 v[34:37], v[228:231], v[176:179], v[34:37]
	v_mfma_f32_16x16x32_bf16 v[22:25], v[220:223], v[204:207], v[22:25]
	v_mfma_f32_16x16x32_bf16 v[18:21], v[228:231], v[204:207], v[18:21]
	v_mfma_f32_16x16x32_bf16 v[6:9], v[220:223], v[212:215], v[6:9]
	v_mfma_f32_16x16x32_bf16 v[2:5], v[228:231], v[212:215], v[2:5]
	s_barrier
	s_add_i32 s18, 0, 0x18000
	v_add_u32_e32 v151, s18, v149
	ds_read_b128 v[142:145], v151
	ds_read_b128 v[152:155], v151 offset:1024
	ds_read_b128 v[156:159], v151 offset:2048
	ds_read_b128 v[160:163], v151 offset:3072
	s_add_u32 s4, s4, s2
	s_addc_u32 s5, s5, 0
	s_mov_b32 m0, s24
	v_lshl_add_u64 v[216:217], s[4:5], 0, v[130:131]
	ds_read_b128 v[164:167], v150 offset:32768
	ds_read_b128 v[168:171], v150 offset:33792
	ds_read_b128 v[172:175], v150 offset:34816
	ds_read_b128 v[176:179], v150 offset:35840
	ds_read_b128 v[180:183], v150 offset:36864
	ds_read_b128 v[204:207], v150 offset:37888
	ds_read_b128 v[208:211], v150 offset:38912
	ds_read_b128 v[212:215], v150 offset:39936
	global_load_lds_dwordx4 v[216:217], off
	v_lshl_add_u64 v[216:217], s[4:5], 0, v[134:135]
	s_mov_b32 m0, s25
	s_nop 0
	global_load_lds_dwordx4 v[216:217], off
	s_waitcnt lgkmcnt(8)
	s_barrier
	s_waitcnt lgkmcnt(0)
	v_mfma_f32_16x16x32_bf16 v[126:129], v[142:145], v[164:167], v[126:129]
	v_mfma_f32_16x16x32_bf16 v[122:125], v[156:159], v[164:167], v[122:125]
	v_mfma_f32_16x16x32_bf16 v[110:113], v[142:145], v[172:175], v[110:113]
	v_mfma_f32_16x16x32_bf16 v[106:109], v[156:159], v[172:175], v[106:109]
	v_mfma_f32_16x16x32_bf16 v[94:97], v[142:145], v[180:183], v[94:97]
	v_mfma_f32_16x16x32_bf16 v[90:93], v[156:159], v[180:183], v[90:93]
	v_mfma_f32_16x16x32_bf16 v[78:81], v[142:145], v[208:211], v[78:81]
	v_mfma_f32_16x16x32_bf16 v[74:77], v[156:159], v[208:211], v[74:77]
	v_mfma_f32_16x16x32_bf16 v[126:129], v[152:155], v[168:171], v[126:129]
	v_mfma_f32_16x16x32_bf16 v[122:125], v[160:163], v[168:171], v[122:125]
	v_mfma_f32_16x16x32_bf16 v[110:113], v[152:155], v[176:179], v[110:113]
	v_mfma_f32_16x16x32_bf16 v[106:109], v[160:163], v[176:179], v[106:109]
	v_mfma_f32_16x16x32_bf16 v[94:97], v[152:155], v[204:207], v[94:97]
	v_mfma_f32_16x16x32_bf16 v[90:93], v[160:163], v[204:207], v[90:93]
	v_mfma_f32_16x16x32_bf16 v[78:81], v[152:155], v[212:215], v[78:81]
	v_mfma_f32_16x16x32_bf16 v[74:77], v[160:163], v[212:215], v[74:77]
	s_barrier
	s_add_i32 s4, 0, 0x1c000
	s_add_i32 s5, s18, s21
	v_add_u32_e32 v151, s4, v149
	v_lshl_add_u64 v[146:147], v[146:147], 0, s[6:7]
	s_mov_b32 m0, s5
	ds_read_b128 v[216:219], v151
	ds_read_b128 v[220:223], v151 offset:1024
	ds_read_b128 v[224:227], v151 offset:2048
	ds_read_b128 v[228:231], v151 offset:3072
	global_load_lds_dwordx4 v[146:147], off
	v_lshl_add_u64 v[146:147], v[184:185], 0, s[6:7]
	s_add_i32 m0, s5, 0x2000
	s_nop 0
	global_load_lds_dwordx4 v[146:147], off
	s_barrier
	s_waitcnt lgkmcnt(0)
	v_mfma_f32_16x16x32_bf16 v[118:121], v[216:219], v[164:167], v[118:121]
	v_mfma_f32_16x16x32_bf16 v[114:117], v[224:227], v[164:167], v[114:117]
	v_mfma_f32_16x16x32_bf16 v[102:105], v[216:219], v[172:175], v[102:105]
	v_mfma_f32_16x16x32_bf16 v[98:101], v[224:227], v[172:175], v[98:101]
	v_mfma_f32_16x16x32_bf16 v[86:89], v[216:219], v[180:183], v[86:89]
	v_mfma_f32_16x16x32_bf16 v[82:85], v[224:227], v[180:183], v[82:85]
	v_mfma_f32_16x16x32_bf16 v[70:73], v[216:219], v[208:211], v[70:73]
	v_mfma_f32_16x16x32_bf16 v[66:69], v[224:227], v[208:211], v[66:69]
	v_mfma_f32_16x16x32_bf16 v[118:121], v[220:223], v[168:171], v[118:121]
	v_mfma_f32_16x16x32_bf16 v[114:117], v[228:231], v[168:171], v[114:117]
	v_mfma_f32_16x16x32_bf16 v[102:105], v[220:223], v[176:179], v[102:105]
	v_mfma_f32_16x16x32_bf16 v[98:101], v[228:231], v[176:179], v[98:101]
	v_mfma_f32_16x16x32_bf16 v[86:89], v[220:223], v[204:207], v[86:89]
	v_mfma_f32_16x16x32_bf16 v[82:85], v[228:231], v[204:207], v[82:85]
	v_mfma_f32_16x16x32_bf16 v[70:73], v[220:223], v[212:215], v[70:73]
	v_mfma_f32_16x16x32_bf16 v[66:69], v[228:231], v[212:215], v[66:69]
	s_barrier
	s_mov_b32 m0, s30
	v_lshl_add_u64 v[146:147], v[232:233], 0, s[6:7]
	ds_read_b128 v[164:167], v150 offset:49152
	ds_read_b128 v[168:171], v150 offset:50176
	ds_read_b128 v[172:175], v150 offset:51200
	ds_read_b128 v[176:179], v150 offset:52224
	ds_read_b128 v[180:183], v150 offset:53248
	ds_read_b128 v[204:207], v150 offset:54272
	ds_read_b128 v[208:211], v150 offset:55296
	ds_read_b128 v[212:215], v150 offset:56320
	global_load_lds_dwordx4 v[146:147], off
	v_lshl_add_u64 v[146:147], v[234:235], 0, s[6:7]
	s_mov_b32 m0, s31
	s_nop 0
	global_load_lds_dwordx4 v[146:147], off
	s_barrier
	s_waitcnt lgkmcnt(0)
	v_mfma_f32_16x16x32_bf16 v[62:65], v[142:145], v[164:167], v[62:65]
	v_mfma_f32_16x16x32_bf16 v[58:61], v[156:159], v[164:167], v[58:61]
	v_mfma_f32_16x16x32_bf16 v[46:49], v[142:145], v[172:175], v[46:49]
	v_mfma_f32_16x16x32_bf16 v[42:45], v[156:159], v[172:175], v[42:45]
	v_mfma_f32_16x16x32_bf16 v[30:33], v[142:145], v[180:183], v[30:33]
	v_mfma_f32_16x16x32_bf16 v[26:29], v[156:159], v[180:183], v[26:29]
	v_mfma_f32_16x16x32_bf16 v[14:17], v[142:145], v[208:211], v[14:17]
	v_mfma_f32_16x16x32_bf16 v[10:13], v[156:159], v[208:211], v[10:13]
	v_mfma_f32_16x16x32_bf16 v[62:65], v[152:155], v[168:171], v[62:65]
	v_mfma_f32_16x16x32_bf16 v[58:61], v[160:163], v[168:171], v[58:61]
	v_mfma_f32_16x16x32_bf16 v[46:49], v[152:155], v[176:179], v[46:49]
	v_mfma_f32_16x16x32_bf16 v[42:45], v[160:163], v[176:179], v[42:45]
	v_mfma_f32_16x16x32_bf16 v[30:33], v[152:155], v[204:207], v[30:33]
	v_mfma_f32_16x16x32_bf16 v[26:29], v[160:163], v[204:207], v[26:29]
	v_mfma_f32_16x16x32_bf16 v[14:17], v[152:155], v[212:215], v[14:17]
	v_mfma_f32_16x16x32_bf16 v[10:13], v[160:163], v[212:215], v[10:13]
	s_barrier
	s_add_i32 s4, s4, s21
	v_lshl_add_u64 v[142:143], v[236:237], 0, s[6:7]
	s_mov_b32 m0, s4
	s_nop 0
	global_load_lds_dwordx4 v[142:143], off
	v_lshl_add_u64 v[142:143], v[238:239], 0, s[6:7]
	s_add_i32 m0, s4, 0x2000
	s_nop 0
	global_load_lds_dwordx4 v[142:143], off
	s_add_u32 s0, s0, 0x100
	s_addc_u32 s1, s1, 0
	s_add_u32 s48, s48, 0x100
	s_addc_u32 s49, s49, 0
	s_cmp_ge_u32 s65, s27
	s_mov_b32 s4, s65
	s_waitcnt vmcnt(6)
	s_barrier
	v_mfma_f32_16x16x32_bf16 v[54:57], v[216:219], v[164:167], v[54:57]
	v_mfma_f32_16x16x32_bf16 v[50:53], v[224:227], v[164:167], v[50:53]
	v_mfma_f32_16x16x32_bf16 v[38:41], v[216:219], v[172:175], v[38:41]
	v_mfma_f32_16x16x32_bf16 v[34:37], v[224:227], v[172:175], v[34:37]
	v_mfma_f32_16x16x32_bf16 v[22:25], v[216:219], v[180:183], v[22:25]
	v_mfma_f32_16x16x32_bf16 v[18:21], v[224:227], v[180:183], v[18:21]
	v_mfma_f32_16x16x32_bf16 v[6:9], v[216:219], v[208:211], v[6:9]
	v_mfma_f32_16x16x32_bf16 v[2:5], v[224:227], v[208:211], v[2:5]
	v_mfma_f32_16x16x32_bf16 v[54:57], v[220:223], v[168:171], v[54:57]
	v_mfma_f32_16x16x32_bf16 v[50:53], v[228:231], v[168:171], v[50:53]
	v_mfma_f32_16x16x32_bf16 v[38:41], v[220:223], v[176:179], v[38:41]
	v_mfma_f32_16x16x32_bf16 v[34:37], v[228:231], v[176:179], v[34:37]
	v_mfma_f32_16x16x32_bf16 v[22:25], v[220:223], v[204:207], v[22:25]
	v_mfma_f32_16x16x32_bf16 v[18:21], v[228:231], v[204:207], v[18:21]
	v_mfma_f32_16x16x32_bf16 v[6:9], v[220:223], v[212:215], v[6:9]
	v_mfma_f32_16x16x32_bf16 v[2:5], v[228:231], v[212:215], v[2:5]
	s_barrier
	s_cbranch_scc0 .LBB0_698

.LBB0_741:
	s_add_u32 s0, s0, 0x80
	s_addc_u32 s1, s1, 0
	s_add_u32 s65, s4, 0x100
	s_addc_u32 s66, s5, 0
	s_mov_b32 s4, 0
	s_add_i32 s70, s4, 2
	s_add_u32 s10, s0, 0x80
	s_addc_u32 s5, s1, 0
	s_add_i32 s71, 0, 0x10000
	v_add_u32_e32 v154, s71, v165
	ds_read_b128 v[142:145], v154
	ds_read_b128 v[146:149], v154 offset:1024
	ds_read_b128 v[150:153], v154 offset:2048
	ds_read_b128 v[154:157], v154 offset:3072
	s_cmp_eq_u32 s43, s4
	s_cselect_b32 s4, s22, s10
	s_cselect_b32 s5, s23, s5
	s_cselect_b32 s11, s13, s66
	s_cselect_b32 s10, s12, s65
	v_lshl_add_u64 v[162:163], s[0:1], 0, v[138:139]
	s_add_i32 m0, s29, 0xc000
	ds_read_b128 v[158:161], v166
	ds_read_b128 v[168:171], v166 offset:1024
	ds_read_b128 v[172:175], v166 offset:2048
	ds_read_b128 v[176:179], v166 offset:3072
	ds_read_b128 v[180:183], v166 offset:4096
	ds_read_b128 v[204:207], v166 offset:5120
	ds_read_b128 v[208:211], v166 offset:6144
	ds_read_b128 v[212:215], v166 offset:7168
	global_load_lds_dwordx4 v[162:163], off
	v_lshl_add_u64 v[162:163], s[0:1], 0, v[140:141]
	s_add_i32 m0, s29, 0xe000
	s_nop 0
	global_load_lds_dwordx4 v[162:163], off
	s_waitcnt lgkmcnt(8)
	s_barrier
	s_waitcnt lgkmcnt(0)
	v_mfma_f32_16x16x32_bf16 v[126:129], v[142:145], v[158:161], 0
	v_mfma_f32_16x16x32_bf16 v[122:125], v[150:153], v[158:161], 0
	v_mfma_f32_16x16x32_bf16 v[110:113], v[142:145], v[172:175], 0
	v_mfma_f32_16x16x32_bf16 v[106:109], v[150:153], v[172:175], 0
	v_mfma_f32_16x16x32_bf16 v[94:97], v[142:145], v[180:183], 0
	v_mfma_f32_16x16x32_bf16 v[90:93], v[150:153], v[180:183], 0
	v_mfma_f32_16x16x32_bf16 v[78:81], v[142:145], v[208:211], 0
	v_mfma_f32_16x16x32_bf16 v[74:77], v[150:153], v[208:211], 0
	v_mfma_f32_16x16x32_bf16 v[126:129], v[146:149], v[168:171], v[126:129]
	v_mfma_f32_16x16x32_bf16 v[122:125], v[154:157], v[168:171], v[122:125]
	v_mfma_f32_16x16x32_bf16 v[110:113], v[146:149], v[176:179], v[110:113]
	v_mfma_f32_16x16x32_bf16 v[106:109], v[154:157], v[176:179], v[106:109]
	v_mfma_f32_16x16x32_bf16 v[94:97], v[146:149], v[204:207], v[94:97]
	v_mfma_f32_16x16x32_bf16 v[90:93], v[154:157], v[204:207], v[90:93]
	v_mfma_f32_16x16x32_bf16 v[78:81], v[146:149], v[212:215], v[78:81]
	v_mfma_f32_16x16x32_bf16 v[74:77], v[154:157], v[212:215], v[74:77]
	s_barrier
	s_add_i32 s72, 0, 0x14000
	v_add_u32_e32 v162, s72, v165
	s_add_i32 s71, s71, s28
	ds_read_b128 v[216:219], v162
	ds_read_b128 v[220:223], v162 offset:1024
	ds_read_b128 v[224:227], v162 offset:2048
	ds_read_b128 v[228:231], v162 offset:3072
	v_lshl_add_u64 v[162:163], s[10:11], 0, v[132:133]
	s_mov_b32 m0, s71
	v_lshl_add_u64 v[184:185], s[10:11], 0, v[136:137]
	global_load_lds_dwordx4 v[162:163], off
	s_add_i32 m0, s71, 0x2000
	s_nop 0
	global_load_lds_dwordx4 v[184:185], off
	s_barrier
	s_waitcnt lgkmcnt(0)
	v_mfma_f32_16x16x32_bf16 v[118:121], v[216:219], v[158:161], 0
	v_mfma_f32_16x16x32_bf16 v[114:117], v[224:227], v[158:161], 0
	v_mfma_f32_16x16x32_bf16 v[102:105], v[216:219], v[172:175], 0
	v_mfma_f32_16x16x32_bf16 v[98:101], v[224:227], v[172:175], 0
	v_mfma_f32_16x16x32_bf16 v[86:89], v[216:219], v[180:183], 0
	v_mfma_f32_16x16x32_bf16 v[82:85], v[224:227], v[180:183], 0
	v_mfma_f32_16x16x32_bf16 v[70:73], v[216:219], v[208:211], 0
	v_mfma_f32_16x16x32_bf16 v[66:69], v[224:227], v[208:211], 0
	v_mfma_f32_16x16x32_bf16 v[118:121], v[220:223], v[168:171], v[118:121]
	v_mfma_f32_16x16x32_bf16 v[114:117], v[228:231], v[168:171], v[114:117]
	v_mfma_f32_16x16x32_bf16 v[102:105], v[220:223], v[176:179], v[102:105]
	v_mfma_f32_16x16x32_bf16 v[98:101], v[228:231], v[176:179], v[98:101]
	v_mfma_f32_16x16x32_bf16 v[86:89], v[220:223], v[204:207], v[86:89]
	v_mfma_f32_16x16x32_bf16 v[82:85], v[228:231], v[204:207], v[82:85]
	v_mfma_f32_16x16x32_bf16 v[70:73], v[220:223], v[212:215], v[70:73]
	v_mfma_f32_16x16x32_bf16 v[66:69], v[228:231], v[212:215], v[66:69]
	s_barrier
	s_mov_b32 m0, s29
	v_lshl_add_u64 v[232:233], s[4:5], 0, v[130:131]
	ds_read_b128 v[158:161], v166 offset:16384
	ds_read_b128 v[168:171], v166 offset:17408
	ds_read_b128 v[172:175], v166 offset:18432
	ds_read_b128 v[176:179], v166 offset:19456
	ds_read_b128 v[180:183], v166 offset:20480
	ds_read_b128 v[204:207], v166 offset:21504
	ds_read_b128 v[208:211], v166 offset:22528
	ds_read_b128 v[212:215], v166 offset:23552
	global_load_lds_dwordx4 v[232:233], off
	v_lshl_add_u64 v[234:235], s[4:5], 0, v[134:135]
	s_mov_b32 m0, s30
	s_nop 0
	global_load_lds_dwordx4 v[234:235], off
	s_barrier
	s_waitcnt lgkmcnt(0)
	v_mfma_f32_16x16x32_bf16 v[62:65], v[142:145], v[158:161], 0
	v_mfma_f32_16x16x32_bf16 v[58:61], v[150:153], v[158:161], 0
	v_mfma_f32_16x16x32_bf16 v[46:49], v[142:145], v[172:175], 0
	v_mfma_f32_16x16x32_bf16 v[42:45], v[150:153], v[172:175], 0
	v_mfma_f32_16x16x32_bf16 v[30:33], v[142:145], v[180:183], 0
	v_mfma_f32_16x16x32_bf16 v[26:29], v[150:153], v[180:183], 0
	v_mfma_f32_16x16x32_bf16 v[14:17], v[142:145], v[208:211], 0
	v_mfma_f32_16x16x32_bf16 v[10:13], v[150:153], v[208:211], 0
	v_mfma_f32_16x16x32_bf16 v[62:65], v[146:149], v[168:171], v[62:65]
	v_mfma_f32_16x16x32_bf16 v[58:61], v[154:157], v[168:171], v[58:61]
	v_mfma_f32_16x16x32_bf16 v[46:49], v[146:149], v[176:179], v[46:49]
	v_mfma_f32_16x16x32_bf16 v[42:45], v[154:157], v[176:179], v[42:45]
	v_mfma_f32_16x16x32_bf16 v[30:33], v[146:149], v[204:207], v[30:33]
	v_mfma_f32_16x16x32_bf16 v[26:29], v[154:157], v[204:207], v[26:29]
	v_mfma_f32_16x16x32_bf16 v[14:17], v[146:149], v[212:215], v[14:17]
	v_mfma_f32_16x16x32_bf16 v[10:13], v[154:157], v[212:215], v[10:13]
	s_barrier
	s_add_u32 s10, s10, s2
	s_addc_u32 s11, s11, 0
	s_add_i32 s71, s72, s28
	v_lshl_add_u64 v[236:237], s[10:11], 0, v[132:133]
	s_mov_b32 m0, s71
	v_lshl_add_u64 v[238:239], s[10:11], 0, v[136:137]
	global_load_lds_dwordx4 v[236:237], off
	s_add_i32 m0, s71, 0x2000
	s_nop 0
	global_load_lds_dwordx4 v[238:239], off
	s_waitcnt vmcnt(6)
	s_barrier
	v_mfma_f32_16x16x32_bf16 v[54:57], v[216:219], v[158:161], 0
	v_mfma_f32_16x16x32_bf16 v[50:53], v[224:227], v[158:161], 0
	v_mfma_f32_16x16x32_bf16 v[38:41], v[216:219], v[172:175], 0
	v_mfma_f32_16x16x32_bf16 v[34:37], v[224:227], v[172:175], 0
	v_mfma_f32_16x16x32_bf16 v[22:25], v[216:219], v[180:183], 0
	v_mfma_f32_16x16x32_bf16 v[18:21], v[224:227], v[180:183], 0
	v_mfma_f32_16x16x32_bf16 v[6:9], v[216:219], v[208:211], 0
	v_mfma_f32_16x16x32_bf16 v[2:5], v[224:227], v[208:211], 0
	v_mfma_f32_16x16x32_bf16 v[54:57], v[220:223], v[168:171], v[54:57]
	v_mfma_f32_16x16x32_bf16 v[50:53], v[228:231], v[168:171], v[50:53]
	v_mfma_f32_16x16x32_bf16 v[38:41], v[220:223], v[176:179], v[38:41]
	v_mfma_f32_16x16x32_bf16 v[34:37], v[228:231], v[176:179], v[34:37]
	v_mfma_f32_16x16x32_bf16 v[22:25], v[220:223], v[204:207], v[22:25]
	v_mfma_f32_16x16x32_bf16 v[18:21], v[228:231], v[204:207], v[18:21]
	v_mfma_f32_16x16x32_bf16 v[6:9], v[220:223], v[212:215], v[6:9]
	v_mfma_f32_16x16x32_bf16 v[2:5], v[228:231], v[212:215], v[2:5]
	s_barrier
	s_add_i32 s10, 0, 0x18000
	v_add_u32_e32 v154, s10, v165
	ds_read_b128 v[142:145], v154
	ds_read_b128 v[146:149], v154 offset:1024
	ds_read_b128 v[150:153], v154 offset:2048
	ds_read_b128 v[154:157], v154 offset:3072
	s_add_u32 s4, s4, s2
	s_addc_u32 s5, s5, 0
	s_mov_b32 m0, s31
	v_lshl_add_u64 v[216:217], s[4:5], 0, v[130:131]
	ds_read_b128 v[158:161], v166 offset:32768
	ds_read_b128 v[168:171], v166 offset:33792
	ds_read_b128 v[172:175], v166 offset:34816
	ds_read_b128 v[176:179], v166 offset:35840
	ds_read_b128 v[180:183], v166 offset:36864
	ds_read_b128 v[204:207], v166 offset:37888
	ds_read_b128 v[208:211], v166 offset:38912
	ds_read_b128 v[212:215], v166 offset:39936
	global_load_lds_dwordx4 v[216:217], off
	v_lshl_add_u64 v[216:217], s[4:5], 0, v[134:135]
	s_mov_b32 m0, s34
	s_nop 0
	global_load_lds_dwordx4 v[216:217], off
	s_waitcnt lgkmcnt(8)
	s_barrier
	s_waitcnt lgkmcnt(0)
	v_mfma_f32_16x16x32_bf16 v[126:129], v[142:145], v[158:161], v[126:129]
	v_mfma_f32_16x16x32_bf16 v[122:125], v[150:153], v[158:161], v[122:125]
	v_mfma_f32_16x16x32_bf16 v[110:113], v[142:145], v[172:175], v[110:113]
	v_mfma_f32_16x16x32_bf16 v[106:109], v[150:153], v[172:175], v[106:109]
	v_mfma_f32_16x16x32_bf16 v[94:97], v[142:145], v[180:183], v[94:97]
	v_mfma_f32_16x16x32_bf16 v[90:93], v[150:153], v[180:183], v[90:93]
	v_mfma_f32_16x16x32_bf16 v[78:81], v[142:145], v[208:211], v[78:81]
	v_mfma_f32_16x16x32_bf16 v[74:77], v[150:153], v[208:211], v[74:77]
	v_mfma_f32_16x16x32_bf16 v[126:129], v[146:149], v[168:171], v[126:129]
	v_mfma_f32_16x16x32_bf16 v[122:125], v[154:157], v[168:171], v[122:125]
	v_mfma_f32_16x16x32_bf16 v[110:113], v[146:149], v[176:179], v[110:113]
	v_mfma_f32_16x16x32_bf16 v[106:109], v[154:157], v[176:179], v[106:109]
	v_mfma_f32_16x16x32_bf16 v[94:97], v[146:149], v[204:207], v[94:97]
	v_mfma_f32_16x16x32_bf16 v[90:93], v[154:157], v[204:207], v[90:93]
	v_mfma_f32_16x16x32_bf16 v[78:81], v[146:149], v[212:215], v[78:81]
	v_mfma_f32_16x16x32_bf16 v[74:77], v[154:157], v[212:215], v[74:77]
	s_barrier
	s_add_i32 s4, 0, 0x1c000
	s_add_i32 s5, s10, s28
	v_add_u32_e32 v167, s4, v165
	v_lshl_add_u64 v[162:163], v[162:163], 0, s[6:7]
	s_mov_b32 m0, s5
	ds_read_b128 v[216:219], v167
	ds_read_b128 v[220:223], v167 offset:1024
	ds_read_b128 v[224:227], v167 offset:2048
	ds_read_b128 v[228:231], v167 offset:3072
	global_load_lds_dwordx4 v[162:163], off
	v_lshl_add_u64 v[162:163], v[184:185], 0, s[6:7]
	s_add_i32 m0, s5, 0x2000
	s_nop 0
	global_load_lds_dwordx4 v[162:163], off
	s_barrier
	s_waitcnt lgkmcnt(0)
	v_mfma_f32_16x16x32_bf16 v[118:121], v[216:219], v[158:161], v[118:121]
	v_mfma_f32_16x16x32_bf16 v[114:117], v[224:227], v[158:161], v[114:117]
	v_mfma_f32_16x16x32_bf16 v[102:105], v[216:219], v[172:175], v[102:105]
	v_mfma_f32_16x16x32_bf16 v[98:101], v[224:227], v[172:175], v[98:101]
	v_mfma_f32_16x16x32_bf16 v[86:89], v[216:219], v[180:183], v[86:89]
	v_mfma_f32_16x16x32_bf16 v[82:85], v[224:227], v[180:183], v[82:85]
	v_mfma_f32_16x16x32_bf16 v[70:73], v[216:219], v[208:211], v[70:73]
	v_mfma_f32_16x16x32_bf16 v[66:69], v[224:227], v[208:211], v[66:69]
	v_mfma_f32_16x16x32_bf16 v[118:121], v[220:223], v[168:171], v[118:121]
	v_mfma_f32_16x16x32_bf16 v[114:117], v[228:231], v[168:171], v[114:117]
	v_mfma_f32_16x16x32_bf16 v[102:105], v[220:223], v[176:179], v[102:105]
	v_mfma_f32_16x16x32_bf16 v[98:101], v[228:231], v[176:179], v[98:101]
	v_mfma_f32_16x16x32_bf16 v[86:89], v[220:223], v[204:207], v[86:89]
	v_mfma_f32_16x16x32_bf16 v[82:85], v[228:231], v[204:207], v[82:85]
	v_mfma_f32_16x16x32_bf16 v[70:73], v[220:223], v[212:215], v[70:73]
	v_mfma_f32_16x16x32_bf16 v[66:69], v[228:231], v[212:215], v[66:69]
	s_barrier
	s_mov_b32 m0, s41
	v_lshl_add_u64 v[162:163], v[232:233], 0, s[6:7]
	ds_read_b128 v[158:161], v166 offset:49152
	ds_read_b128 v[168:171], v166 offset:50176
	ds_read_b128 v[172:175], v166 offset:51200
	ds_read_b128 v[176:179], v166 offset:52224
	ds_read_b128 v[180:183], v166 offset:53248
	ds_read_b128 v[204:207], v166 offset:54272
	ds_read_b128 v[208:211], v166 offset:55296
	ds_read_b128 v[212:215], v166 offset:56320
	global_load_lds_dwordx4 v[162:163], off
	v_lshl_add_u64 v[162:163], v[234:235], 0, s[6:7]
	s_mov_b32 m0, s42
	s_nop 0
	global_load_lds_dwordx4 v[162:163], off
	s_barrier
	s_waitcnt lgkmcnt(0)
	v_mfma_f32_16x16x32_bf16 v[62:65], v[142:145], v[158:161], v[62:65]
	v_mfma_f32_16x16x32_bf16 v[58:61], v[150:153], v[158:161], v[58:61]
	v_mfma_f32_16x16x32_bf16 v[46:49], v[142:145], v[172:175], v[46:49]
	v_mfma_f32_16x16x32_bf16 v[42:45], v[150:153], v[172:175], v[42:45]
	v_mfma_f32_16x16x32_bf16 v[30:33], v[142:145], v[180:183], v[30:33]
	v_mfma_f32_16x16x32_bf16 v[26:29], v[150:153], v[180:183], v[26:29]
	v_mfma_f32_16x16x32_bf16 v[14:17], v[142:145], v[208:211], v[14:17]
	v_mfma_f32_16x16x32_bf16 v[10:13], v[150:153], v[208:211], v[10:13]
	v_mfma_f32_16x16x32_bf16 v[62:65], v[146:149], v[168:171], v[62:65]
	v_mfma_f32_16x16x32_bf16 v[58:61], v[154:157], v[168:171], v[58:61]
	v_mfma_f32_16x16x32_bf16 v[46:49], v[146:149], v[176:179], v[46:49]
	v_mfma_f32_16x16x32_bf16 v[42:45], v[154:157], v[176:179], v[42:45]
	v_mfma_f32_16x16x32_bf16 v[30:33], v[146:149], v[204:207], v[30:33]
	v_mfma_f32_16x16x32_bf16 v[26:29], v[154:157], v[204:207], v[26:29]
	v_mfma_f32_16x16x32_bf16 v[14:17], v[146:149], v[212:215], v[14:17]
	v_mfma_f32_16x16x32_bf16 v[10:13], v[154:157], v[212:215], v[10:13]
	s_barrier
	s_add_i32 s4, s4, s28
	v_lshl_add_u64 v[142:143], v[236:237], 0, s[6:7]
	s_mov_b32 m0, s4
	s_nop 0
	global_load_lds_dwordx4 v[142:143], off
	v_lshl_add_u64 v[142:143], v[238:239], 0, s[6:7]
	s_add_i32 m0, s4, 0x2000
	s_nop 0
	global_load_lds_dwordx4 v[142:143], off
	s_add_u32 s0, s0, 0x100
	s_addc_u32 s1, s1, 0
	s_add_u32 s65, s65, 0x100
	s_addc_u32 s66, s66, 0
	s_cmp_ge_u32 s70, s35
	s_mov_b32 s4, s70
	s_waitcnt vmcnt(6)
	s_barrier
	v_mfma_f32_16x16x32_bf16 v[54:57], v[216:219], v[158:161], v[54:57]
	v_mfma_f32_16x16x32_bf16 v[50:53], v[224:227], v[158:161], v[50:53]
	v_mfma_f32_16x16x32_bf16 v[38:41], v[216:219], v[172:175], v[38:41]
	v_mfma_f32_16x16x32_bf16 v[34:37], v[224:227], v[172:175], v[34:37]
	v_mfma_f32_16x16x32_bf16 v[22:25], v[216:219], v[180:183], v[22:25]
	v_mfma_f32_16x16x32_bf16 v[18:21], v[224:227], v[180:183], v[18:21]
	v_mfma_f32_16x16x32_bf16 v[6:9], v[216:219], v[208:211], v[6:9]
	v_mfma_f32_16x16x32_bf16 v[2:5], v[224:227], v[208:211], v[2:5]
	v_mfma_f32_16x16x32_bf16 v[54:57], v[220:223], v[168:171], v[54:57]
	v_mfma_f32_16x16x32_bf16 v[50:53], v[228:231], v[168:171], v[50:53]
	v_mfma_f32_16x16x32_bf16 v[38:41], v[220:223], v[176:179], v[38:41]
	v_mfma_f32_16x16x32_bf16 v[34:37], v[228:231], v[176:179], v[34:37]
	v_mfma_f32_16x16x32_bf16 v[22:25], v[220:223], v[204:207], v[22:25]
	v_mfma_f32_16x16x32_bf16 v[18:21], v[228:231], v[204:207], v[18:21]
	v_mfma_f32_16x16x32_bf16 v[6:9], v[220:223], v[212:215], v[6:9]
	v_mfma_f32_16x16x32_bf16 v[2:5], v[228:231], v[212:215], v[2:5]
	s_barrier
	s_cbranch_scc1 .Lkexit_742
.LBB0_742:
	s_add_i32 s70, s4, 2
	s_add_u32 s10, s0, 0x80
	s_addc_u32 s5, s1, 0
	s_add_i32 s71, 0, 0x10000
	v_add_u32_e32 v154, s71, v165
	ds_read_b128 v[142:145], v154
	ds_read_b128 v[146:149], v154 offset:1024
	ds_read_b128 v[150:153], v154 offset:2048
	ds_read_b128 v[154:157], v154 offset:3072
	s_cmp_eq_u32 s43, s4
	s_cselect_b32 s4, s22, s10
	s_cselect_b32 s5, s23, s5
	s_cselect_b32 s11, s13, s66
	s_cselect_b32 s10, s12, s65
	v_lshl_add_u64 v[162:163], s[0:1], 0, v[138:139]
	s_add_i32 m0, s29, 0xc000
	ds_read_b128 v[158:161], v166
	ds_read_b128 v[168:171], v166 offset:1024
	ds_read_b128 v[172:175], v166 offset:2048
	ds_read_b128 v[176:179], v166 offset:3072
	ds_read_b128 v[180:183], v166 offset:4096
	ds_read_b128 v[204:207], v166 offset:5120
	ds_read_b128 v[208:211], v166 offset:6144
	ds_read_b128 v[212:215], v166 offset:7168
	global_load_lds_dwordx4 v[162:163], off
	v_lshl_add_u64 v[162:163], s[0:1], 0, v[140:141]
	s_add_i32 m0, s29, 0xe000
	s_nop 0
	global_load_lds_dwordx4 v[162:163], off
	s_waitcnt lgkmcnt(8)
	s_barrier
	s_waitcnt lgkmcnt(0)
	v_mfma_f32_16x16x32_bf16 v[126:129], v[142:145], v[158:161], v[126:129]
	v_mfma_f32_16x16x32_bf16 v[122:125], v[150:153], v[158:161], v[122:125]
	v_mfma_f32_16x16x32_bf16 v[110:113], v[142:145], v[172:175], v[110:113]
	v_mfma_f32_16x16x32_bf16 v[106:109], v[150:153], v[172:175], v[106:109]
	v_mfma_f32_16x16x32_bf16 v[94:97], v[142:145], v[180:183], v[94:97]
	v_mfma_f32_16x16x32_bf16 v[90:93], v[150:153], v[180:183], v[90:93]
	v_mfma_f32_16x16x32_bf16 v[78:81], v[142:145], v[208:211], v[78:81]
	v_mfma_f32_16x16x32_bf16 v[74:77], v[150:153], v[208:211], v[74:77]
	v_mfma_f32_16x16x32_bf16 v[126:129], v[146:149], v[168:171], v[126:129]
	v_mfma_f32_16x16x32_bf16 v[122:125], v[154:157], v[168:171], v[122:125]
	v_mfma_f32_16x16x32_bf16 v[110:113], v[146:149], v[176:179], v[110:113]
	v_mfma_f32_16x16x32_bf16 v[106:109], v[154:157], v[176:179], v[106:109]
	v_mfma_f32_16x16x32_bf16 v[94:97], v[146:149], v[204:207], v[94:97]
	v_mfma_f32_16x16x32_bf16 v[90:93], v[154:157], v[204:207], v[90:93]
	v_mfma_f32_16x16x32_bf16 v[78:81], v[146:149], v[212:215], v[78:81]
	v_mfma_f32_16x16x32_bf16 v[74:77], v[154:157], v[212:215], v[74:77]
	s_barrier
	s_add_i32 s72, 0, 0x14000
	v_add_u32_e32 v162, s72, v165
	s_add_i32 s71, s71, s28
	ds_read_b128 v[216:219], v162
	ds_read_b128 v[220:223], v162 offset:1024
	ds_read_b128 v[224:227], v162 offset:2048
	ds_read_b128 v[228:231], v162 offset:3072
	v_lshl_add_u64 v[162:163], s[10:11], 0, v[132:133]
	s_mov_b32 m0, s71
	v_lshl_add_u64 v[184:185], s[10:11], 0, v[136:137]
	global_load_lds_dwordx4 v[162:163], off
	s_add_i32 m0, s71, 0x2000
	s_nop 0
	global_load_lds_dwordx4 v[184:185], off
	s_barrier
	s_waitcnt lgkmcnt(0)
	v_mfma_f32_16x16x32_bf16 v[118:121], v[216:219], v[158:161], v[118:121]
	v_mfma_f32_16x16x32_bf16 v[114:117], v[224:227], v[158:161], v[114:117]
	v_mfma_f32_16x16x32_bf16 v[102:105], v[216:219], v[172:175], v[102:105]
	v_mfma_f32_16x16x32_bf16 v[98:101], v[224:227], v[172:175], v[98:101]
	v_mfma_f32_16x16x32_bf16 v[86:89], v[216:219], v[180:183], v[86:89]
	v_mfma_f32_16x16x32_bf16 v[82:85], v[224:227], v[180:183], v[82:85]
	v_mfma_f32_16x16x32_bf16 v[70:73], v[216:219], v[208:211], v[70:73]
	v_mfma_f32_16x16x32_bf16 v[66:69], v[224:227], v[208:211], v[66:69]
	v_mfma_f32_16x16x32_bf16 v[118:121], v[220:223], v[168:171], v[118:121]
	v_mfma_f32_16x16x32_bf16 v[114:117], v[228:231], v[168:171], v[114:117]
	v_mfma_f32_16x16x32_bf16 v[102:105], v[220:223], v[176:179], v[102:105]
	v_mfma_f32_16x16x32_bf16 v[98:101], v[228:231], v[176:179], v[98:101]
	v_mfma_f32_16x16x32_bf16 v[86:89], v[220:223], v[204:207], v[86:89]
	v_mfma_f32_16x16x32_bf16 v[82:85], v[228:231], v[204:207], v[82:85]
	v_mfma_f32_16x16x32_bf16 v[70:73], v[220:223], v[212:215], v[70:73]
	v_mfma_f32_16x16x32_bf16 v[66:69], v[228:231], v[212:215], v[66:69]
	s_barrier
	s_mov_b32 m0, s29
	v_lshl_add_u64 v[232:233], s[4:5], 0, v[130:131]
	ds_read_b128 v[158:161], v166 offset:16384
	ds_read_b128 v[168:171], v166 offset:17408
	ds_read_b128 v[172:175], v166 offset:18432
	ds_read_b128 v[176:179], v166 offset:19456
	ds_read_b128 v[180:183], v166 offset:20480
	ds_read_b128 v[204:207], v166 offset:21504
	ds_read_b128 v[208:211], v166 offset:22528
	ds_read_b128 v[212:215], v166 offset:23552
	global_load_lds_dwordx4 v[232:233], off
	v_lshl_add_u64 v[234:235], s[4:5], 0, v[134:135]
	s_mov_b32 m0, s30
	s_nop 0
	global_load_lds_dwordx4 v[234:235], off
	s_barrier
	s_waitcnt lgkmcnt(0)
	v_mfma_f32_16x16x32_bf16 v[62:65], v[142:145], v[158:161], v[62:65]
	v_mfma_f32_16x16x32_bf16 v[58:61], v[150:153], v[158:161], v[58:61]
	v_mfma_f32_16x16x32_bf16 v[46:49], v[142:145], v[172:175], v[46:49]
	v_mfma_f32_16x16x32_bf16 v[42:45], v[150:153], v[172:175], v[42:45]
	v_mfma_f32_16x16x32_bf16 v[30:33], v[142:145], v[180:183], v[30:33]
	v_mfma_f32_16x16x32_bf16 v[26:29], v[150:153], v[180:183], v[26:29]
	v_mfma_f32_16x16x32_bf16 v[14:17], v[142:145], v[208:211], v[14:17]
	v_mfma_f32_16x16x32_bf16 v[10:13], v[150:153], v[208:211], v[10:13]
	v_mfma_f32_16x16x32_bf16 v[62:65], v[146:149], v[168:171], v[62:65]
	v_mfma_f32_16x16x32_bf16 v[58:61], v[154:157], v[168:171], v[58:61]
	v_mfma_f32_16x16x32_bf16 v[46:49], v[146:149], v[176:179], v[46:49]
	v_mfma_f32_16x16x32_bf16 v[42:45], v[154:157], v[176:179], v[42:45]
	v_mfma_f32_16x16x32_bf16 v[30:33], v[146:149], v[204:207], v[30:33]
	v_mfma_f32_16x16x32_bf16 v[26:29], v[154:157], v[204:207], v[26:29]
	v_mfma_f32_16x16x32_bf16 v[14:17], v[146:149], v[212:215], v[14:17]
	v_mfma_f32_16x16x32_bf16 v[10:13], v[154:157], v[212:215], v[10:13]
	s_barrier
	s_add_u32 s10, s10, s2
	s_addc_u32 s11, s11, 0
	s_add_i32 s71, s72, s28
	v_lshl_add_u64 v[236:237], s[10:11], 0, v[132:133]
	s_mov_b32 m0, s71
	v_lshl_add_u64 v[238:239], s[10:11], 0, v[136:137]
	global_load_lds_dwordx4 v[236:237], off
	s_add_i32 m0, s71, 0x2000
	s_nop 0
	global_load_lds_dwordx4 v[238:239], off
	s_waitcnt vmcnt(6)
	s_barrier
	v_mfma_f32_16x16x32_bf16 v[54:57], v[216:219], v[158:161], v[54:57]
	v_mfma_f32_16x16x32_bf16 v[50:53], v[224:227], v[158:161], v[50:53]
	v_mfma_f32_16x16x32_bf16 v[38:41], v[216:219], v[172:175], v[38:41]
	v_mfma_f32_16x16x32_bf16 v[34:37], v[224:227], v[172:175], v[34:37]
	v_mfma_f32_16x16x32_bf16 v[22:25], v[216:219], v[180:183], v[22:25]
	v_mfma_f32_16x16x32_bf16 v[18:21], v[224:227], v[180:183], v[18:21]
	v_mfma_f32_16x16x32_bf16 v[6:9], v[216:219], v[208:211], v[6:9]
	v_mfma_f32_16x16x32_bf16 v[2:5], v[224:227], v[208:211], v[2:5]
	v_mfma_f32_16x16x32_bf16 v[54:57], v[220:223], v[168:171], v[54:57]
	v_mfma_f32_16x16x32_bf16 v[50:53], v[228:231], v[168:171], v[50:53]
	v_mfma_f32_16x16x32_bf16 v[38:41], v[220:223], v[176:179], v[38:41]
	v_mfma_f32_16x16x32_bf16 v[34:37], v[228:231], v[176:179], v[34:37]
	v_mfma_f32_16x16x32_bf16 v[22:25], v[220:223], v[204:207], v[22:25]
	v_mfma_f32_16x16x32_bf16 v[18:21], v[228:231], v[204:207], v[18:21]
	v_mfma_f32_16x16x32_bf16 v[6:9], v[220:223], v[212:215], v[6:9]
	v_mfma_f32_16x16x32_bf16 v[2:5], v[228:231], v[212:215], v[2:5]
	s_barrier
	s_add_i32 s10, 0, 0x18000
	v_add_u32_e32 v154, s10, v165
	ds_read_b128 v[142:145], v154
	ds_read_b128 v[146:149], v154 offset:1024
	ds_read_b128 v[150:153], v154 offset:2048
	ds_read_b128 v[154:157], v154 offset:3072
	s_add_u32 s4, s4, s2
	s_addc_u32 s5, s5, 0
	s_mov_b32 m0, s31
	v_lshl_add_u64 v[216:217], s[4:5], 0, v[130:131]
	ds_read_b128 v[158:161], v166 offset:32768
	ds_read_b128 v[168:171], v166 offset:33792
	ds_read_b128 v[172:175], v166 offset:34816
	ds_read_b128 v[176:179], v166 offset:35840
	ds_read_b128 v[180:183], v166 offset:36864
	ds_read_b128 v[204:207], v166 offset:37888
	ds_read_b128 v[208:211], v166 offset:38912
	ds_read_b128 v[212:215], v166 offset:39936
	global_load_lds_dwordx4 v[216:217], off
	v_lshl_add_u64 v[216:217], s[4:5], 0, v[134:135]
	s_mov_b32 m0, s34
	s_nop 0
	global_load_lds_dwordx4 v[216:217], off
	s_waitcnt lgkmcnt(8)
	s_barrier
	s_waitcnt lgkmcnt(0)
	v_mfma_f32_16x16x32_bf16 v[126:129], v[142:145], v[158:161], v[126:129]
	v_mfma_f32_16x16x32_bf16 v[122:125], v[150:153], v[158:161], v[122:125]
	v_mfma_f32_16x16x32_bf16 v[110:113], v[142:145], v[172:175], v[110:113]
	v_mfma_f32_16x16x32_bf16 v[106:109], v[150:153], v[172:175], v[106:109]
	v_mfma_f32_16x16x32_bf16 v[94:97], v[142:145], v[180:183], v[94:97]
	v_mfma_f32_16x16x32_bf16 v[90:93], v[150:153], v[180:183], v[90:93]
	v_mfma_f32_16x16x32_bf16 v[78:81], v[142:145], v[208:211], v[78:81]
	v_mfma_f32_16x16x32_bf16 v[74:77], v[150:153], v[208:211], v[74:77]
	v_mfma_f32_16x16x32_bf16 v[126:129], v[146:149], v[168:171], v[126:129]
	v_mfma_f32_16x16x32_bf16 v[122:125], v[154:157], v[168:171], v[122:125]
	v_mfma_f32_16x16x32_bf16 v[110:113], v[146:149], v[176:179], v[110:113]
	v_mfma_f32_16x16x32_bf16 v[106:109], v[154:157], v[176:179], v[106:109]
	v_mfma_f32_16x16x32_bf16 v[94:97], v[146:149], v[204:207], v[94:97]
	v_mfma_f32_16x16x32_bf16 v[90:93], v[154:157], v[204:207], v[90:93]
	v_mfma_f32_16x16x32_bf16 v[78:81], v[146:149], v[212:215], v[78:81]
	v_mfma_f32_16x16x32_bf16 v[74:77], v[154:157], v[212:215], v[74:77]
	s_barrier
	s_add_i32 s4, 0, 0x1c000
	s_add_i32 s5, s10, s28
	v_add_u32_e32 v167, s4, v165
	v_lshl_add_u64 v[162:163], v[162:163], 0, s[6:7]
	s_mov_b32 m0, s5
	ds_read_b128 v[216:219], v167
	ds_read_b128 v[220:223], v167 offset:1024
	ds_read_b128 v[224:227], v167 offset:2048
	ds_read_b128 v[228:231], v167 offset:3072
	global_load_lds_dwordx4 v[162:163], off
	v_lshl_add_u64 v[162:163], v[184:185], 0, s[6:7]
	s_add_i32 m0, s5, 0x2000
	s_nop 0
	global_load_lds_dwordx4 v[162:163], off
	s_barrier
	s_waitcnt lgkmcnt(0)
	v_mfma_f32_16x16x32_bf16 v[118:121], v[216:219], v[158:161], v[118:121]
	v_mfma_f32_16x16x32_bf16 v[114:117], v[224:227], v[158:161], v[114:117]
	v_mfma_f32_16x16x32_bf16 v[102:105], v[216:219], v[172:175], v[102:105]
	v_mfma_f32_16x16x32_bf16 v[98:101], v[224:227], v[172:175], v[98:101]
	v_mfma_f32_16x16x32_bf16 v[86:89], v[216:219], v[180:183], v[86:89]
	v_mfma_f32_16x16x32_bf16 v[82:85], v[224:227], v[180:183], v[82:85]
	v_mfma_f32_16x16x32_bf16 v[70:73], v[216:219], v[208:211], v[70:73]
	v_mfma_f32_16x16x32_bf16 v[66:69], v[224:227], v[208:211], v[66:69]
	v_mfma_f32_16x16x32_bf16 v[118:121], v[220:223], v[168:171], v[118:121]
	v_mfma_f32_16x16x32_bf16 v[114:117], v[228:231], v[168:171], v[114:117]
	v_mfma_f32_16x16x32_bf16 v[102:105], v[220:223], v[176:179], v[102:105]
	v_mfma_f32_16x16x32_bf16 v[98:101], v[228:231], v[176:179], v[98:101]
	v_mfma_f32_16x16x32_bf16 v[86:89], v[220:223], v[204:207], v[86:89]
	v_mfma_f32_16x16x32_bf16 v[82:85], v[228:231], v[204:207], v[82:85]
	v_mfma_f32_16x16x32_bf16 v[70:73], v[220:223], v[212:215], v[70:73]
	v_mfma_f32_16x16x32_bf16 v[66:69], v[228:231], v[212:215], v[66:69]
	s_barrier
	s_mov_b32 m0, s41
	v_lshl_add_u64 v[162:163], v[232:233], 0, s[6:7]
	ds_read_b128 v[158:161], v166 offset:49152
	ds_read_b128 v[168:171], v166 offset:50176
	ds_read_b128 v[172:175], v166 offset:51200
	ds_read_b128 v[176:179], v166 offset:52224
	ds_read_b128 v[180:183], v166 offset:53248
	ds_read_b128 v[204:207], v166 offset:54272
	ds_read_b128 v[208:211], v166 offset:55296
	ds_read_b128 v[212:215], v166 offset:56320
	global_load_lds_dwordx4 v[162:163], off
	v_lshl_add_u64 v[162:163], v[234:235], 0, s[6:7]
	s_mov_b32 m0, s42
	s_nop 0
	global_load_lds_dwordx4 v[162:163], off
	s_barrier
	s_waitcnt lgkmcnt(0)
	v_mfma_f32_16x16x32_bf16 v[62:65], v[142:145], v[158:161], v[62:65]
	v_mfma_f32_16x16x32_bf16 v[58:61], v[150:153], v[158:161], v[58:61]
	v_mfma_f32_16x16x32_bf16 v[46:49], v[142:145], v[172:175], v[46:49]
	v_mfma_f32_16x16x32_bf16 v[42:45], v[150:153], v[172:175], v[42:45]
	v_mfma_f32_16x16x32_bf16 v[30:33], v[142:145], v[180:183], v[30:33]
	v_mfma_f32_16x16x32_bf16 v[26:29], v[150:153], v[180:183], v[26:29]
	v_mfma_f32_16x16x32_bf16 v[14:17], v[142:145], v[208:211], v[14:17]
	v_mfma_f32_16x16x32_bf16 v[10:13], v[150:153], v[208:211], v[10:13]
	v_mfma_f32_16x16x32_bf16 v[62:65], v[146:149], v[168:171], v[62:65]
	v_mfma_f32_16x16x32_bf16 v[58:61], v[154:157], v[168:171], v[58:61]
	v_mfma_f32_16x16x32_bf16 v[46:49], v[146:149], v[176:179], v[46:49]
	v_mfma_f32_16x16x32_bf16 v[42:45], v[154:157], v[176:179], v[42:45]
	v_mfma_f32_16x16x32_bf16 v[30:33], v[146:149], v[204:207], v[30:33]
	v_mfma_f32_16x16x32_bf16 v[26:29], v[154:157], v[204:207], v[26:29]
	v_mfma_f32_16x16x32_bf16 v[14:17], v[146:149], v[212:215], v[14:17]
	v_mfma_f32_16x16x32_bf16 v[10:13], v[154:157], v[212:215], v[10:13]
	s_barrier
	s_add_i32 s4, s4, s28
	v_lshl_add_u64 v[142:143], v[236:237], 0, s[6:7]
	s_mov_b32 m0, s4
	s_nop 0
	global_load_lds_dwordx4 v[142:143], off
	v_lshl_add_u64 v[142:143], v[238:239], 0, s[6:7]
	s_add_i32 m0, s4, 0x2000
	s_nop 0
	global_load_lds_dwordx4 v[142:143], off
	s_add_u32 s0, s0, 0x100
	s_addc_u32 s1, s1, 0
	s_add_u32 s65, s65, 0x100
	s_addc_u32 s66, s66, 0
	s_cmp_ge_u32 s70, s35
	s_mov_b32 s4, s70
	s_waitcnt vmcnt(6)
	s_barrier
	v_mfma_f32_16x16x32_bf16 v[54:57], v[216:219], v[158:161], v[54:57]
	v_mfma_f32_16x16x32_bf16 v[50:53], v[224:227], v[158:161], v[50:53]
	v_mfma_f32_16x16x32_bf16 v[38:41], v[216:219], v[172:175], v[38:41]
	v_mfma_f32_16x16x32_bf16 v[34:37], v[224:227], v[172:175], v[34:37]
	v_mfma_f32_16x16x32_bf16 v[22:25], v[216:219], v[180:183], v[22:25]
	v_mfma_f32_16x16x32_bf16 v[18:21], v[224:227], v[180:183], v[18:21]
	v_mfma_f32_16x16x32_bf16 v[6:9], v[216:219], v[208:211], v[6:9]
	v_mfma_f32_16x16x32_bf16 v[2:5], v[224:227], v[208:211], v[2:5]
	v_mfma_f32_16x16x32_bf16 v[54:57], v[220:223], v[168:171], v[54:57]
	v_mfma_f32_16x16x32_bf16 v[50:53], v[228:231], v[168:171], v[50:53]
	v_mfma_f32_16x16x32_bf16 v[38:41], v[220:223], v[176:179], v[38:41]
	v_mfma_f32_16x16x32_bf16 v[34:37], v[228:231], v[176:179], v[34:37]
	v_mfma_f32_16x16x32_bf16 v[22:25], v[220:223], v[204:207], v[22:25]
	v_mfma_f32_16x16x32_bf16 v[18:21], v[228:231], v[204:207], v[18:21]
	v_mfma_f32_16x16x32_bf16 v[6:9], v[220:223], v[212:215], v[6:9]
	v_mfma_f32_16x16x32_bf16 v[2:5], v[228:231], v[212:215], v[2:5]
	s_barrier
	s_cbranch_scc0 .LBB0_742

.LBB0_805:
	s_add_u32 s0, s0, 0x80
	s_addc_u32 s1, s1, 0
	s_add_u32 s12, s4, 0x100
	s_addc_u32 s13, s5, 0
	s_mov_b32 s4, 0
	s_waitcnt vmcnt(0)
	s_add_i32 s27, s4, 2
	s_add_u32 s10, s0, 0x80
	s_addc_u32 s5, s1, 0
	s_add_i32 s28, 0, 0x10000
	v_add_u32_e32 v154, s28, v171
	ds_read_b128 v[142:145], v154
	ds_read_b128 v[146:149], v154 offset:1024
	ds_read_b128 v[150:153], v154 offset:2048
	ds_read_b128 v[154:157], v154 offset:3072
	s_cmp_eq_u32 s48, s4
	s_cselect_b32 s4, s22, s10
	s_cselect_b32 s5, s23, s5
	s_cselect_b32 s11, s25, s13
	s_cselect_b32 s10, s24, s12
	v_lshl_add_u64 v[212:213], s[0:1], 0, v[138:139]
	s_add_i32 m0, s35, 0xc000
	ds_read_b128 v[158:161], v172
	ds_read_b128 v[162:165], v172 offset:1024
	ds_read_b128 v[166:169], v172 offset:2048
	ds_read_b128 v[174:177], v172 offset:3072
	ds_read_b128 v[178:181], v172 offset:4096
	ds_read_b128 v[182:185], v172 offset:5120
	ds_read_b128 v[204:207], v172 offset:6144
	ds_read_b128 v[208:211], v172 offset:7168
	global_load_lds_dwordx4 v[212:213], off
	v_lshl_add_u64 v[212:213], s[0:1], 0, v[140:141]
	s_add_i32 m0, s35, 0xe000
	s_nop 0
	global_load_lds_dwordx4 v[212:213], off
	s_waitcnt lgkmcnt(8)
	s_barrier
	s_waitcnt lgkmcnt(0)
	v_mfma_f32_16x16x32_bf16 v[126:129], v[142:145], v[158:161], 0
	v_mfma_f32_16x16x32_bf16 v[122:125], v[150:153], v[158:161], 0
	v_mfma_f32_16x16x32_bf16 v[110:113], v[142:145], v[166:169], 0
	v_mfma_f32_16x16x32_bf16 v[106:109], v[150:153], v[166:169], 0
	v_mfma_f32_16x16x32_bf16 v[94:97], v[142:145], v[178:181], 0
	v_mfma_f32_16x16x32_bf16 v[90:93], v[150:153], v[178:181], 0
	v_mfma_f32_16x16x32_bf16 v[78:81], v[142:145], v[204:207], 0
	v_mfma_f32_16x16x32_bf16 v[74:77], v[150:153], v[204:207], 0
	v_mfma_f32_16x16x32_bf16 v[126:129], v[146:149], v[162:165], v[126:129]
	v_mfma_f32_16x16x32_bf16 v[122:125], v[154:157], v[162:165], v[122:125]
	v_mfma_f32_16x16x32_bf16 v[110:113], v[146:149], v[174:177], v[110:113]
	v_mfma_f32_16x16x32_bf16 v[106:109], v[154:157], v[174:177], v[106:109]
	v_mfma_f32_16x16x32_bf16 v[94:97], v[146:149], v[182:185], v[94:97]
	v_mfma_f32_16x16x32_bf16 v[90:93], v[154:157], v[182:185], v[90:93]
	v_mfma_f32_16x16x32_bf16 v[78:81], v[146:149], v[208:211], v[78:81]
	v_mfma_f32_16x16x32_bf16 v[74:77], v[154:157], v[208:211], v[74:77]
	s_barrier
	s_add_i32 s29, 0, 0x14000
	s_add_i32 s28, s28, s34
	v_add_u32_e32 v173, s29, v171
	v_lshl_add_u64 v[228:229], s[10:11], 0, v[132:133]
	s_mov_b32 m0, s28
	ds_read_b128 v[212:215], v173
	ds_read_b128 v[216:219], v173 offset:1024
	ds_read_b128 v[220:223], v173 offset:2048
	ds_read_b128 v[224:227], v173 offset:3072
	global_load_lds_dwordx4 v[228:229], off
	v_lshl_add_u64 v[230:231], s[10:11], 0, v[136:137]
	s_add_i32 m0, s28, 0x2000
	s_nop 0
	global_load_lds_dwordx4 v[230:231], off
	s_barrier
	s_waitcnt lgkmcnt(0)
	v_mfma_f32_16x16x32_bf16 v[118:121], v[212:215], v[158:161], 0
	v_mfma_f32_16x16x32_bf16 v[114:117], v[220:223], v[158:161], 0
	v_mfma_f32_16x16x32_bf16 v[102:105], v[212:215], v[166:169], 0
	v_mfma_f32_16x16x32_bf16 v[98:101], v[220:223], v[166:169], 0
	v_mfma_f32_16x16x32_bf16 v[86:89], v[212:215], v[178:181], 0
	v_mfma_f32_16x16x32_bf16 v[82:85], v[220:223], v[178:181], 0
	v_mfma_f32_16x16x32_bf16 v[70:73], v[212:215], v[204:207], 0
	v_mfma_f32_16x16x32_bf16 v[66:69], v[220:223], v[204:207], 0
	v_mfma_f32_16x16x32_bf16 v[118:121], v[216:219], v[162:165], v[118:121]
	v_mfma_f32_16x16x32_bf16 v[114:117], v[224:227], v[162:165], v[114:117]
	v_mfma_f32_16x16x32_bf16 v[102:105], v[216:219], v[174:177], v[102:105]
	v_mfma_f32_16x16x32_bf16 v[98:101], v[224:227], v[174:177], v[98:101]
	v_mfma_f32_16x16x32_bf16 v[86:89], v[216:219], v[182:185], v[86:89]
	v_mfma_f32_16x16x32_bf16 v[82:85], v[224:227], v[182:185], v[82:85]
	v_mfma_f32_16x16x32_bf16 v[70:73], v[216:219], v[208:211], v[70:73]
	v_mfma_f32_16x16x32_bf16 v[66:69], v[224:227], v[208:211], v[66:69]
	s_barrier
	s_mov_b32 m0, s35
	v_lshl_add_u64 v[232:233], s[4:5], 0, v[130:131]
	ds_read_b128 v[158:161], v172 offset:16384
	ds_read_b128 v[162:165], v172 offset:17408
	ds_read_b128 v[166:169], v172 offset:18432
	ds_read_b128 v[174:177], v172 offset:19456
	ds_read_b128 v[178:181], v172 offset:20480
	ds_read_b128 v[182:185], v172 offset:21504
	ds_read_b128 v[204:207], v172 offset:22528
	ds_read_b128 v[208:211], v172 offset:23552
	global_load_lds_dwordx4 v[232:233], off
	v_lshl_add_u64 v[234:235], s[4:5], 0, v[134:135]
	s_mov_b32 m0, s40
	s_nop 0
	global_load_lds_dwordx4 v[234:235], off
	s_barrier
	s_waitcnt lgkmcnt(0)
	v_mfma_f32_16x16x32_bf16 v[62:65], v[142:145], v[158:161], 0
	v_mfma_f32_16x16x32_bf16 v[58:61], v[150:153], v[158:161], 0
	v_mfma_f32_16x16x32_bf16 v[46:49], v[142:145], v[166:169], 0
	v_mfma_f32_16x16x32_bf16 v[42:45], v[150:153], v[166:169], 0
	v_mfma_f32_16x16x32_bf16 v[30:33], v[142:145], v[178:181], 0
	v_mfma_f32_16x16x32_bf16 v[26:29], v[150:153], v[178:181], 0
	v_mfma_f32_16x16x32_bf16 v[14:17], v[142:145], v[204:207], 0
	v_mfma_f32_16x16x32_bf16 v[10:13], v[150:153], v[204:207], 0
	v_mfma_f32_16x16x32_bf16 v[62:65], v[146:149], v[162:165], v[62:65]
	v_mfma_f32_16x16x32_bf16 v[58:61], v[154:157], v[162:165], v[58:61]
	v_mfma_f32_16x16x32_bf16 v[46:49], v[146:149], v[174:177], v[46:49]
	v_mfma_f32_16x16x32_bf16 v[42:45], v[154:157], v[174:177], v[42:45]
	v_mfma_f32_16x16x32_bf16 v[30:33], v[146:149], v[182:185], v[30:33]
	v_mfma_f32_16x16x32_bf16 v[26:29], v[154:157], v[182:185], v[26:29]
	v_mfma_f32_16x16x32_bf16 v[14:17], v[146:149], v[208:211], v[14:17]
	v_mfma_f32_16x16x32_bf16 v[10:13], v[154:157], v[208:211], v[10:13]
	s_barrier
	s_add_u32 s10, s10, s92
	s_addc_u32 s11, s11, 0
	s_add_i32 s28, s29, s34
	v_lshl_add_u64 v[236:237], s[10:11], 0, v[132:133]
	s_mov_b32 m0, s28
	v_lshl_add_u64 v[238:239], s[10:11], 0, v[136:137]
	global_load_lds_dwordx4 v[236:237], off
	s_add_i32 m0, s28, 0x2000
	s_nop 0
	global_load_lds_dwordx4 v[238:239], off
	s_waitcnt vmcnt(6)
	s_barrier
	v_mfma_f32_16x16x32_bf16 v[54:57], v[212:215], v[158:161], 0
	v_mfma_f32_16x16x32_bf16 v[50:53], v[220:223], v[158:161], 0
	v_mfma_f32_16x16x32_bf16 v[38:41], v[212:215], v[166:169], 0
	v_mfma_f32_16x16x32_bf16 v[34:37], v[220:223], v[166:169], 0
	v_mfma_f32_16x16x32_bf16 v[22:25], v[212:215], v[178:181], 0
	v_mfma_f32_16x16x32_bf16 v[18:21], v[220:223], v[178:181], 0
	v_mfma_f32_16x16x32_bf16 v[6:9], v[212:215], v[204:207], 0
	v_mfma_f32_16x16x32_bf16 v[2:5], v[220:223], v[204:207], 0
	v_mfma_f32_16x16x32_bf16 v[54:57], v[216:219], v[162:165], v[54:57]
	v_mfma_f32_16x16x32_bf16 v[50:53], v[224:227], v[162:165], v[50:53]
	v_mfma_f32_16x16x32_bf16 v[38:41], v[216:219], v[174:177], v[38:41]
	v_mfma_f32_16x16x32_bf16 v[34:37], v[224:227], v[174:177], v[34:37]
	v_mfma_f32_16x16x32_bf16 v[22:25], v[216:219], v[182:185], v[22:25]
	v_mfma_f32_16x16x32_bf16 v[18:21], v[224:227], v[182:185], v[18:21]
	v_mfma_f32_16x16x32_bf16 v[6:9], v[216:219], v[208:211], v[6:9]
	v_mfma_f32_16x16x32_bf16 v[2:5], v[224:227], v[208:211], v[2:5]
	s_barrier
	s_add_i32 s10, 0, 0x18000
	v_add_u32_e32 v154, s10, v171
	ds_read_b128 v[142:145], v154
	ds_read_b128 v[146:149], v154 offset:1024
	ds_read_b128 v[150:153], v154 offset:2048
	ds_read_b128 v[154:157], v154 offset:3072
	s_add_u32 s4, s4, s92
	s_addc_u32 s5, s5, 0
	s_mov_b32 m0, s41
	v_lshl_add_u64 v[212:213], s[4:5], 0, v[130:131]
	ds_read_b128 v[158:161], v172 offset:32768
	ds_read_b128 v[162:165], v172 offset:33792
	ds_read_b128 v[166:169], v172 offset:34816
	ds_read_b128 v[174:177], v172 offset:35840
	ds_read_b128 v[178:181], v172 offset:36864
	ds_read_b128 v[182:185], v172 offset:37888
	ds_read_b128 v[204:207], v172 offset:38912
	ds_read_b128 v[208:211], v172 offset:39936
	global_load_lds_dwordx4 v[212:213], off
	v_lshl_add_u64 v[212:213], s[4:5], 0, v[134:135]
	s_mov_b32 m0, s42
	s_nop 0
	global_load_lds_dwordx4 v[212:213], off
	s_waitcnt lgkmcnt(8)
	s_barrier
	s_waitcnt lgkmcnt(0)
	v_mfma_f32_16x16x32_bf16 v[126:129], v[142:145], v[158:161], v[126:129]
	v_mfma_f32_16x16x32_bf16 v[122:125], v[150:153], v[158:161], v[122:125]
	v_mfma_f32_16x16x32_bf16 v[110:113], v[142:145], v[166:169], v[110:113]
	v_mfma_f32_16x16x32_bf16 v[106:109], v[150:153], v[166:169], v[106:109]
	v_mfma_f32_16x16x32_bf16 v[94:97], v[142:145], v[178:181], v[94:97]
	v_mfma_f32_16x16x32_bf16 v[90:93], v[150:153], v[178:181], v[90:93]
	v_mfma_f32_16x16x32_bf16 v[78:81], v[142:145], v[204:207], v[78:81]
	v_mfma_f32_16x16x32_bf16 v[74:77], v[150:153], v[204:207], v[74:77]
	v_mfma_f32_16x16x32_bf16 v[126:129], v[146:149], v[162:165], v[126:129]
	v_mfma_f32_16x16x32_bf16 v[122:125], v[154:157], v[162:165], v[122:125]
	v_mfma_f32_16x16x32_bf16 v[110:113], v[146:149], v[174:177], v[110:113]
	v_mfma_f32_16x16x32_bf16 v[106:109], v[154:157], v[174:177], v[106:109]
	v_mfma_f32_16x16x32_bf16 v[94:97], v[146:149], v[182:185], v[94:97]
	v_mfma_f32_16x16x32_bf16 v[90:93], v[154:157], v[182:185], v[90:93]
	v_mfma_f32_16x16x32_bf16 v[78:81], v[146:149], v[208:211], v[78:81]
	v_mfma_f32_16x16x32_bf16 v[74:77], v[154:157], v[208:211], v[74:77]
	s_barrier
	s_add_i32 s4, 0, 0x1c000
	s_add_i32 s5, s10, s34
	v_add_u32_e32 v173, s4, v171
	v_lshl_add_u64 v[228:229], v[228:229], 0, s[6:7]
	s_mov_b32 m0, s5
	ds_read_b128 v[212:215], v173
	ds_read_b128 v[216:219], v173 offset:1024
	ds_read_b128 v[220:223], v173 offset:2048
	ds_read_b128 v[224:227], v173 offset:3072
	global_load_lds_dwordx4 v[228:229], off
	v_lshl_add_u64 v[228:229], v[230:231], 0, s[6:7]
	s_add_i32 m0, s5, 0x2000
	s_nop 0
	global_load_lds_dwordx4 v[228:229], off
	s_barrier
	s_waitcnt lgkmcnt(0)
	v_mfma_f32_16x16x32_bf16 v[118:121], v[212:215], v[158:161], v[118:121]
	v_mfma_f32_16x16x32_bf16 v[114:117], v[220:223], v[158:161], v[114:117]
	v_mfma_f32_16x16x32_bf16 v[102:105], v[212:215], v[166:169], v[102:105]
	v_mfma_f32_16x16x32_bf16 v[98:101], v[220:223], v[166:169], v[98:101]
	v_mfma_f32_16x16x32_bf16 v[86:89], v[212:215], v[178:181], v[86:89]
	v_mfma_f32_16x16x32_bf16 v[82:85], v[220:223], v[178:181], v[82:85]
	v_mfma_f32_16x16x32_bf16 v[70:73], v[212:215], v[204:207], v[70:73]
	v_mfma_f32_16x16x32_bf16 v[66:69], v[220:223], v[204:207], v[66:69]
	v_mfma_f32_16x16x32_bf16 v[118:121], v[216:219], v[162:165], v[118:121]
	v_mfma_f32_16x16x32_bf16 v[114:117], v[224:227], v[162:165], v[114:117]
	v_mfma_f32_16x16x32_bf16 v[102:105], v[216:219], v[174:177], v[102:105]
	v_mfma_f32_16x16x32_bf16 v[98:101], v[224:227], v[174:177], v[98:101]
	v_mfma_f32_16x16x32_bf16 v[86:89], v[216:219], v[182:185], v[86:89]
	v_mfma_f32_16x16x32_bf16 v[82:85], v[224:227], v[182:185], v[82:85]
	v_mfma_f32_16x16x32_bf16 v[70:73], v[216:219], v[208:211], v[70:73]
	v_mfma_f32_16x16x32_bf16 v[66:69], v[224:227], v[208:211], v[66:69]
	s_barrier
	s_mov_b32 m0, s46
	v_lshl_add_u64 v[228:229], v[232:233], 0, s[6:7]
	ds_read_b128 v[158:161], v172 offset:49152
	ds_read_b128 v[162:165], v172 offset:50176
	ds_read_b128 v[166:169], v172 offset:51200
	ds_read_b128 v[174:177], v172 offset:52224
	ds_read_b128 v[178:181], v172 offset:53248
	ds_read_b128 v[182:185], v172 offset:54272
	ds_read_b128 v[204:207], v172 offset:55296
	ds_read_b128 v[208:211], v172 offset:56320
	global_load_lds_dwordx4 v[228:229], off
	v_lshl_add_u64 v[228:229], v[234:235], 0, s[6:7]
	s_mov_b32 m0, s47
	s_nop 0
	global_load_lds_dwordx4 v[228:229], off
	s_barrier
	s_waitcnt lgkmcnt(0)
	v_mfma_f32_16x16x32_bf16 v[62:65], v[142:145], v[158:161], v[62:65]
	v_mfma_f32_16x16x32_bf16 v[58:61], v[150:153], v[158:161], v[58:61]
	v_mfma_f32_16x16x32_bf16 v[46:49], v[142:145], v[166:169], v[46:49]
	v_mfma_f32_16x16x32_bf16 v[42:45], v[150:153], v[166:169], v[42:45]
	v_mfma_f32_16x16x32_bf16 v[30:33], v[142:145], v[178:181], v[30:33]
	v_mfma_f32_16x16x32_bf16 v[26:29], v[150:153], v[178:181], v[26:29]
	v_mfma_f32_16x16x32_bf16 v[14:17], v[142:145], v[204:207], v[14:17]
	v_mfma_f32_16x16x32_bf16 v[10:13], v[150:153], v[204:207], v[10:13]
	v_mfma_f32_16x16x32_bf16 v[62:65], v[146:149], v[162:165], v[62:65]
	v_mfma_f32_16x16x32_bf16 v[58:61], v[154:157], v[162:165], v[58:61]
	v_mfma_f32_16x16x32_bf16 v[46:49], v[146:149], v[174:177], v[46:49]
	v_mfma_f32_16x16x32_bf16 v[42:45], v[154:157], v[174:177], v[42:45]
	v_mfma_f32_16x16x32_bf16 v[30:33], v[146:149], v[182:185], v[30:33]
	v_mfma_f32_16x16x32_bf16 v[26:29], v[154:157], v[182:185], v[26:29]
	v_mfma_f32_16x16x32_bf16 v[14:17], v[146:149], v[208:211], v[14:17]
	v_mfma_f32_16x16x32_bf16 v[10:13], v[154:157], v[208:211], v[10:13]
	s_barrier
	s_add_i32 s4, s4, s34
	v_lshl_add_u64 v[142:143], v[236:237], 0, s[6:7]
	s_mov_b32 m0, s4
	s_nop 0
	global_load_lds_dwordx4 v[142:143], off
	v_lshl_add_u64 v[142:143], v[238:239], 0, s[6:7]
	s_add_i32 m0, s4, 0x2000
	s_nop 0
	global_load_lds_dwordx4 v[142:143], off
	s_add_u32 s0, s0, 0x100
	s_addc_u32 s1, s1, 0
	s_add_u32 s12, s12, 0x100
	s_addc_u32 s13, s13, 0
	s_cmp_ge_u32 s27, s43
	s_mov_b32 s4, s27
	s_waitcnt vmcnt(6)
	s_barrier
	v_mfma_f32_16x16x32_bf16 v[54:57], v[212:215], v[158:161], v[54:57]
	v_mfma_f32_16x16x32_bf16 v[50:53], v[220:223], v[158:161], v[50:53]
	v_mfma_f32_16x16x32_bf16 v[38:41], v[212:215], v[166:169], v[38:41]
	v_mfma_f32_16x16x32_bf16 v[34:37], v[220:223], v[166:169], v[34:37]
	v_mfma_f32_16x16x32_bf16 v[22:25], v[212:215], v[178:181], v[22:25]
	v_mfma_f32_16x16x32_bf16 v[18:21], v[220:223], v[178:181], v[18:21]
	v_mfma_f32_16x16x32_bf16 v[6:9], v[212:215], v[204:207], v[6:9]
	v_mfma_f32_16x16x32_bf16 v[2:5], v[220:223], v[204:207], v[2:5]
	v_mfma_f32_16x16x32_bf16 v[54:57], v[216:219], v[162:165], v[54:57]
	v_mfma_f32_16x16x32_bf16 v[50:53], v[224:227], v[162:165], v[50:53]
	v_mfma_f32_16x16x32_bf16 v[38:41], v[216:219], v[174:177], v[38:41]
	v_mfma_f32_16x16x32_bf16 v[34:37], v[224:227], v[174:177], v[34:37]
	v_mfma_f32_16x16x32_bf16 v[22:25], v[216:219], v[182:185], v[22:25]
	v_mfma_f32_16x16x32_bf16 v[18:21], v[224:227], v[182:185], v[18:21]
	v_mfma_f32_16x16x32_bf16 v[6:9], v[216:219], v[208:211], v[6:9]
	v_mfma_f32_16x16x32_bf16 v[2:5], v[224:227], v[208:211], v[2:5]
	s_barrier
	s_cbranch_scc1 .Lkexit_806
.LBB0_806:
	s_add_i32 s27, s4, 2
	s_add_u32 s10, s0, 0x80
	s_addc_u32 s5, s1, 0
	s_add_i32 s28, 0, 0x10000
	v_add_u32_e32 v154, s28, v171
	ds_read_b128 v[142:145], v154
	ds_read_b128 v[146:149], v154 offset:1024
	ds_read_b128 v[150:153], v154 offset:2048
	ds_read_b128 v[154:157], v154 offset:3072
	s_cmp_eq_u32 s48, s4
	s_cselect_b32 s4, s22, s10
	s_cselect_b32 s5, s23, s5
	s_cselect_b32 s11, s25, s13
	s_cselect_b32 s10, s24, s12
	v_lshl_add_u64 v[212:213], s[0:1], 0, v[138:139]
	s_add_i32 m0, s35, 0xc000
	ds_read_b128 v[158:161], v172
	ds_read_b128 v[162:165], v172 offset:1024
	ds_read_b128 v[166:169], v172 offset:2048
	ds_read_b128 v[174:177], v172 offset:3072
	ds_read_b128 v[178:181], v172 offset:4096
	ds_read_b128 v[182:185], v172 offset:5120
	ds_read_b128 v[204:207], v172 offset:6144
	ds_read_b128 v[208:211], v172 offset:7168
	global_load_lds_dwordx4 v[212:213], off
	v_lshl_add_u64 v[212:213], s[0:1], 0, v[140:141]
	s_add_i32 m0, s35, 0xe000
	s_nop 0
	global_load_lds_dwordx4 v[212:213], off
	s_waitcnt lgkmcnt(8)
	s_barrier
	s_waitcnt lgkmcnt(0)
	v_mfma_f32_16x16x32_bf16 v[126:129], v[142:145], v[158:161], v[126:129]
	v_mfma_f32_16x16x32_bf16 v[122:125], v[150:153], v[158:161], v[122:125]
	v_mfma_f32_16x16x32_bf16 v[110:113], v[142:145], v[166:169], v[110:113]
	v_mfma_f32_16x16x32_bf16 v[106:109], v[150:153], v[166:169], v[106:109]
	v_mfma_f32_16x16x32_bf16 v[94:97], v[142:145], v[178:181], v[94:97]
	v_mfma_f32_16x16x32_bf16 v[90:93], v[150:153], v[178:181], v[90:93]
	v_mfma_f32_16x16x32_bf16 v[78:81], v[142:145], v[204:207], v[78:81]
	v_mfma_f32_16x16x32_bf16 v[74:77], v[150:153], v[204:207], v[74:77]
	v_mfma_f32_16x16x32_bf16 v[126:129], v[146:149], v[162:165], v[126:129]
	v_mfma_f32_16x16x32_bf16 v[122:125], v[154:157], v[162:165], v[122:125]
	v_mfma_f32_16x16x32_bf16 v[110:113], v[146:149], v[174:177], v[110:113]
	v_mfma_f32_16x16x32_bf16 v[106:109], v[154:157], v[174:177], v[106:109]
	v_mfma_f32_16x16x32_bf16 v[94:97], v[146:149], v[182:185], v[94:97]
	v_mfma_f32_16x16x32_bf16 v[90:93], v[154:157], v[182:185], v[90:93]
	v_mfma_f32_16x16x32_bf16 v[78:81], v[146:149], v[208:211], v[78:81]
	v_mfma_f32_16x16x32_bf16 v[74:77], v[154:157], v[208:211], v[74:77]
	s_barrier
	s_add_i32 s29, 0, 0x14000
	s_add_i32 s28, s28, s34
	v_add_u32_e32 v173, s29, v171
	v_lshl_add_u64 v[228:229], s[10:11], 0, v[132:133]
	s_mov_b32 m0, s28
	ds_read_b128 v[212:215], v173
	ds_read_b128 v[216:219], v173 offset:1024
	ds_read_b128 v[220:223], v173 offset:2048
	ds_read_b128 v[224:227], v173 offset:3072
	global_load_lds_dwordx4 v[228:229], off
	v_lshl_add_u64 v[230:231], s[10:11], 0, v[136:137]
	s_add_i32 m0, s28, 0x2000
	s_nop 0
	global_load_lds_dwordx4 v[230:231], off
	s_barrier
	s_waitcnt lgkmcnt(0)
	v_mfma_f32_16x16x32_bf16 v[118:121], v[212:215], v[158:161], v[118:121]
	v_mfma_f32_16x16x32_bf16 v[114:117], v[220:223], v[158:161], v[114:117]
	v_mfma_f32_16x16x32_bf16 v[102:105], v[212:215], v[166:169], v[102:105]
	v_mfma_f32_16x16x32_bf16 v[98:101], v[220:223], v[166:169], v[98:101]
	v_mfma_f32_16x16x32_bf16 v[86:89], v[212:215], v[178:181], v[86:89]
	v_mfma_f32_16x16x32_bf16 v[82:85], v[220:223], v[178:181], v[82:85]
	v_mfma_f32_16x16x32_bf16 v[70:73], v[212:215], v[204:207], v[70:73]
	v_mfma_f32_16x16x32_bf16 v[66:69], v[220:223], v[204:207], v[66:69]
	v_mfma_f32_16x16x32_bf16 v[118:121], v[216:219], v[162:165], v[118:121]
	v_mfma_f32_16x16x32_bf16 v[114:117], v[224:227], v[162:165], v[114:117]
	v_mfma_f32_16x16x32_bf16 v[102:105], v[216:219], v[174:177], v[102:105]
	v_mfma_f32_16x16x32_bf16 v[98:101], v[224:227], v[174:177], v[98:101]
	v_mfma_f32_16x16x32_bf16 v[86:89], v[216:219], v[182:185], v[86:89]
	v_mfma_f32_16x16x32_bf16 v[82:85], v[224:227], v[182:185], v[82:85]
	v_mfma_f32_16x16x32_bf16 v[70:73], v[216:219], v[208:211], v[70:73]
	v_mfma_f32_16x16x32_bf16 v[66:69], v[224:227], v[208:211], v[66:69]
	s_barrier
	s_mov_b32 m0, s35
	v_lshl_add_u64 v[232:233], s[4:5], 0, v[130:131]
	ds_read_b128 v[158:161], v172 offset:16384
	ds_read_b128 v[162:165], v172 offset:17408
	ds_read_b128 v[166:169], v172 offset:18432
	ds_read_b128 v[174:177], v172 offset:19456
	ds_read_b128 v[178:181], v172 offset:20480
	ds_read_b128 v[182:185], v172 offset:21504
	ds_read_b128 v[204:207], v172 offset:22528
	ds_read_b128 v[208:211], v172 offset:23552
	global_load_lds_dwordx4 v[232:233], off
	v_lshl_add_u64 v[234:235], s[4:5], 0, v[134:135]
	s_mov_b32 m0, s40
	s_nop 0
	global_load_lds_dwordx4 v[234:235], off
	s_barrier
	s_waitcnt lgkmcnt(0)
	v_mfma_f32_16x16x32_bf16 v[62:65], v[142:145], v[158:161], v[62:65]
	v_mfma_f32_16x16x32_bf16 v[58:61], v[150:153], v[158:161], v[58:61]
	v_mfma_f32_16x16x32_bf16 v[46:49], v[142:145], v[166:169], v[46:49]
	v_mfma_f32_16x16x32_bf16 v[42:45], v[150:153], v[166:169], v[42:45]
	v_mfma_f32_16x16x32_bf16 v[30:33], v[142:145], v[178:181], v[30:33]
	v_mfma_f32_16x16x32_bf16 v[26:29], v[150:153], v[178:181], v[26:29]
	v_mfma_f32_16x16x32_bf16 v[14:17], v[142:145], v[204:207], v[14:17]
	v_mfma_f32_16x16x32_bf16 v[10:13], v[150:153], v[204:207], v[10:13]
	v_mfma_f32_16x16x32_bf16 v[62:65], v[146:149], v[162:165], v[62:65]
	v_mfma_f32_16x16x32_bf16 v[58:61], v[154:157], v[162:165], v[58:61]
	v_mfma_f32_16x16x32_bf16 v[46:49], v[146:149], v[174:177], v[46:49]
	v_mfma_f32_16x16x32_bf16 v[42:45], v[154:157], v[174:177], v[42:45]
	v_mfma_f32_16x16x32_bf16 v[30:33], v[146:149], v[182:185], v[30:33]
	v_mfma_f32_16x16x32_bf16 v[26:29], v[154:157], v[182:185], v[26:29]
	v_mfma_f32_16x16x32_bf16 v[14:17], v[146:149], v[208:211], v[14:17]
	v_mfma_f32_16x16x32_bf16 v[10:13], v[154:157], v[208:211], v[10:13]
	s_barrier
	s_add_u32 s10, s10, s92
	s_addc_u32 s11, s11, 0
	s_add_i32 s28, s29, s34
	v_lshl_add_u64 v[236:237], s[10:11], 0, v[132:133]
	s_mov_b32 m0, s28
	v_lshl_add_u64 v[238:239], s[10:11], 0, v[136:137]
	global_load_lds_dwordx4 v[236:237], off
	s_add_i32 m0, s28, 0x2000
	s_nop 0
	global_load_lds_dwordx4 v[238:239], off
	s_waitcnt vmcnt(6)
	s_barrier
	v_mfma_f32_16x16x32_bf16 v[54:57], v[212:215], v[158:161], v[54:57]
	v_mfma_f32_16x16x32_bf16 v[50:53], v[220:223], v[158:161], v[50:53]
	v_mfma_f32_16x16x32_bf16 v[38:41], v[212:215], v[166:169], v[38:41]
	v_mfma_f32_16x16x32_bf16 v[34:37], v[220:223], v[166:169], v[34:37]
	v_mfma_f32_16x16x32_bf16 v[22:25], v[212:215], v[178:181], v[22:25]
	v_mfma_f32_16x16x32_bf16 v[18:21], v[220:223], v[178:181], v[18:21]
	v_mfma_f32_16x16x32_bf16 v[6:9], v[212:215], v[204:207], v[6:9]
	v_mfma_f32_16x16x32_bf16 v[2:5], v[220:223], v[204:207], v[2:5]
	v_mfma_f32_16x16x32_bf16 v[54:57], v[216:219], v[162:165], v[54:57]
	v_mfma_f32_16x16x32_bf16 v[50:53], v[224:227], v[162:165], v[50:53]
	v_mfma_f32_16x16x32_bf16 v[38:41], v[216:219], v[174:177], v[38:41]
	v_mfma_f32_16x16x32_bf16 v[34:37], v[224:227], v[174:177], v[34:37]
	v_mfma_f32_16x16x32_bf16 v[22:25], v[216:219], v[182:185], v[22:25]
	v_mfma_f32_16x16x32_bf16 v[18:21], v[224:227], v[182:185], v[18:21]
	v_mfma_f32_16x16x32_bf16 v[6:9], v[216:219], v[208:211], v[6:9]
	v_mfma_f32_16x16x32_bf16 v[2:5], v[224:227], v[208:211], v[2:5]
	s_barrier
	s_add_i32 s10, 0, 0x18000
	v_add_u32_e32 v154, s10, v171
	ds_read_b128 v[142:145], v154
	ds_read_b128 v[146:149], v154 offset:1024
	ds_read_b128 v[150:153], v154 offset:2048
	ds_read_b128 v[154:157], v154 offset:3072
	s_add_u32 s4, s4, s92
	s_addc_u32 s5, s5, 0
	s_mov_b32 m0, s41
	v_lshl_add_u64 v[212:213], s[4:5], 0, v[130:131]
	ds_read_b128 v[158:161], v172 offset:32768
	ds_read_b128 v[162:165], v172 offset:33792
	ds_read_b128 v[166:169], v172 offset:34816
	ds_read_b128 v[174:177], v172 offset:35840
	ds_read_b128 v[178:181], v172 offset:36864
	ds_read_b128 v[182:185], v172 offset:37888
	ds_read_b128 v[204:207], v172 offset:38912
	ds_read_b128 v[208:211], v172 offset:39936
	global_load_lds_dwordx4 v[212:213], off
	v_lshl_add_u64 v[212:213], s[4:5], 0, v[134:135]
	s_mov_b32 m0, s42
	s_nop 0
	global_load_lds_dwordx4 v[212:213], off
	s_waitcnt lgkmcnt(8)
	s_barrier
	s_waitcnt lgkmcnt(0)
	v_mfma_f32_16x16x32_bf16 v[126:129], v[142:145], v[158:161], v[126:129]
	v_mfma_f32_16x16x32_bf16 v[122:125], v[150:153], v[158:161], v[122:125]
	v_mfma_f32_16x16x32_bf16 v[110:113], v[142:145], v[166:169], v[110:113]
	v_mfma_f32_16x16x32_bf16 v[106:109], v[150:153], v[166:169], v[106:109]
	v_mfma_f32_16x16x32_bf16 v[94:97], v[142:145], v[178:181], v[94:97]
	v_mfma_f32_16x16x32_bf16 v[90:93], v[150:153], v[178:181], v[90:93]
	v_mfma_f32_16x16x32_bf16 v[78:81], v[142:145], v[204:207], v[78:81]
	v_mfma_f32_16x16x32_bf16 v[74:77], v[150:153], v[204:207], v[74:77]
	v_mfma_f32_16x16x32_bf16 v[126:129], v[146:149], v[162:165], v[126:129]
	v_mfma_f32_16x16x32_bf16 v[122:125], v[154:157], v[162:165], v[122:125]
	v_mfma_f32_16x16x32_bf16 v[110:113], v[146:149], v[174:177], v[110:113]
	v_mfma_f32_16x16x32_bf16 v[106:109], v[154:157], v[174:177], v[106:109]
	v_mfma_f32_16x16x32_bf16 v[94:97], v[146:149], v[182:185], v[94:97]
	v_mfma_f32_16x16x32_bf16 v[90:93], v[154:157], v[182:185], v[90:93]
	v_mfma_f32_16x16x32_bf16 v[78:81], v[146:149], v[208:211], v[78:81]
	v_mfma_f32_16x16x32_bf16 v[74:77], v[154:157], v[208:211], v[74:77]
	s_barrier
	s_add_i32 s4, 0, 0x1c000
	s_add_i32 s5, s10, s34
	v_add_u32_e32 v173, s4, v171
	v_lshl_add_u64 v[228:229], v[228:229], 0, s[6:7]
	s_mov_b32 m0, s5
	ds_read_b128 v[212:215], v173
	ds_read_b128 v[216:219], v173 offset:1024
	ds_read_b128 v[220:223], v173 offset:2048
	ds_read_b128 v[224:227], v173 offset:3072
	global_load_lds_dwordx4 v[228:229], off
	v_lshl_add_u64 v[228:229], v[230:231], 0, s[6:7]
	s_add_i32 m0, s5, 0x2000
	s_nop 0
	global_load_lds_dwordx4 v[228:229], off
	s_barrier
	s_waitcnt lgkmcnt(0)
	v_mfma_f32_16x16x32_bf16 v[118:121], v[212:215], v[158:161], v[118:121]
	v_mfma_f32_16x16x32_bf16 v[114:117], v[220:223], v[158:161], v[114:117]
	v_mfma_f32_16x16x32_bf16 v[102:105], v[212:215], v[166:169], v[102:105]
	v_mfma_f32_16x16x32_bf16 v[98:101], v[220:223], v[166:169], v[98:101]
	v_mfma_f32_16x16x32_bf16 v[86:89], v[212:215], v[178:181], v[86:89]
	v_mfma_f32_16x16x32_bf16 v[82:85], v[220:223], v[178:181], v[82:85]
	v_mfma_f32_16x16x32_bf16 v[70:73], v[212:215], v[204:207], v[70:73]
	v_mfma_f32_16x16x32_bf16 v[66:69], v[220:223], v[204:207], v[66:69]
	v_mfma_f32_16x16x32_bf16 v[118:121], v[216:219], v[162:165], v[118:121]
	v_mfma_f32_16x16x32_bf16 v[114:117], v[224:227], v[162:165], v[114:117]
	v_mfma_f32_16x16x32_bf16 v[102:105], v[216:219], v[174:177], v[102:105]
	v_mfma_f32_16x16x32_bf16 v[98:101], v[224:227], v[174:177], v[98:101]
	v_mfma_f32_16x16x32_bf16 v[86:89], v[216:219], v[182:185], v[86:89]
	v_mfma_f32_16x16x32_bf16 v[82:85], v[224:227], v[182:185], v[82:85]
	v_mfma_f32_16x16x32_bf16 v[70:73], v[216:219], v[208:211], v[70:73]
	v_mfma_f32_16x16x32_bf16 v[66:69], v[224:227], v[208:211], v[66:69]
	s_barrier
	s_mov_b32 m0, s46
	v_lshl_add_u64 v[228:229], v[232:233], 0, s[6:7]
	ds_read_b128 v[158:161], v172 offset:49152
	ds_read_b128 v[162:165], v172 offset:50176
	ds_read_b128 v[166:169], v172 offset:51200
	ds_read_b128 v[174:177], v172 offset:52224
	ds_read_b128 v[178:181], v172 offset:53248
	ds_read_b128 v[182:185], v172 offset:54272
	ds_read_b128 v[204:207], v172 offset:55296
	ds_read_b128 v[208:211], v172 offset:56320
	global_load_lds_dwordx4 v[228:229], off
	v_lshl_add_u64 v[228:229], v[234:235], 0, s[6:7]
	s_mov_b32 m0, s47
	s_nop 0
	global_load_lds_dwordx4 v[228:229], off
	s_barrier
	s_waitcnt lgkmcnt(0)
	v_mfma_f32_16x16x32_bf16 v[62:65], v[142:145], v[158:161], v[62:65]
	v_mfma_f32_16x16x32_bf16 v[58:61], v[150:153], v[158:161], v[58:61]
	v_mfma_f32_16x16x32_bf16 v[46:49], v[142:145], v[166:169], v[46:49]
	v_mfma_f32_16x16x32_bf16 v[42:45], v[150:153], v[166:169], v[42:45]
	v_mfma_f32_16x16x32_bf16 v[30:33], v[142:145], v[178:181], v[30:33]
	v_mfma_f32_16x16x32_bf16 v[26:29], v[150:153], v[178:181], v[26:29]
	v_mfma_f32_16x16x32_bf16 v[14:17], v[142:145], v[204:207], v[14:17]
	v_mfma_f32_16x16x32_bf16 v[10:13], v[150:153], v[204:207], v[10:13]
	v_mfma_f32_16x16x32_bf16 v[62:65], v[146:149], v[162:165], v[62:65]
	v_mfma_f32_16x16x32_bf16 v[58:61], v[154:157], v[162:165], v[58:61]
	v_mfma_f32_16x16x32_bf16 v[46:49], v[146:149], v[174:177], v[46:49]
	v_mfma_f32_16x16x32_bf16 v[42:45], v[154:157], v[174:177], v[42:45]
	v_mfma_f32_16x16x32_bf16 v[30:33], v[146:149], v[182:185], v[30:33]
	v_mfma_f32_16x16x32_bf16 v[26:29], v[154:157], v[182:185], v[26:29]
	v_mfma_f32_16x16x32_bf16 v[14:17], v[146:149], v[208:211], v[14:17]
	v_mfma_f32_16x16x32_bf16 v[10:13], v[154:157], v[208:211], v[10:13]
	s_barrier
	s_add_i32 s4, s4, s34
	v_lshl_add_u64 v[142:143], v[236:237], 0, s[6:7]
	s_mov_b32 m0, s4
	s_nop 0
	global_load_lds_dwordx4 v[142:143], off
	v_lshl_add_u64 v[142:143], v[238:239], 0, s[6:7]
	s_add_i32 m0, s4, 0x2000
	s_nop 0
	global_load_lds_dwordx4 v[142:143], off
	s_add_u32 s0, s0, 0x100
	s_addc_u32 s1, s1, 0
	s_add_u32 s12, s12, 0x100
	s_addc_u32 s13, s13, 0
	s_cmp_ge_u32 s27, s43
	s_mov_b32 s4, s27
	s_waitcnt vmcnt(6)
	s_barrier
	v_mfma_f32_16x16x32_bf16 v[54:57], v[212:215], v[158:161], v[54:57]
	v_mfma_f32_16x16x32_bf16 v[50:53], v[220:223], v[158:161], v[50:53]
	v_mfma_f32_16x16x32_bf16 v[38:41], v[212:215], v[166:169], v[38:41]
	v_mfma_f32_16x16x32_bf16 v[34:37], v[220:223], v[166:169], v[34:37]
	v_mfma_f32_16x16x32_bf16 v[22:25], v[212:215], v[178:181], v[22:25]
	v_mfma_f32_16x16x32_bf16 v[18:21], v[220:223], v[178:181], v[18:21]
	v_mfma_f32_16x16x32_bf16 v[6:9], v[212:215], v[204:207], v[6:9]
	v_mfma_f32_16x16x32_bf16 v[2:5], v[220:223], v[204:207], v[2:5]
	v_mfma_f32_16x16x32_bf16 v[54:57], v[216:219], v[162:165], v[54:57]
	v_mfma_f32_16x16x32_bf16 v[50:53], v[224:227], v[162:165], v[50:53]
	v_mfma_f32_16x16x32_bf16 v[38:41], v[216:219], v[174:177], v[38:41]
	v_mfma_f32_16x16x32_bf16 v[34:37], v[224:227], v[174:177], v[34:37]
	v_mfma_f32_16x16x32_bf16 v[22:25], v[216:219], v[182:185], v[22:25]
	v_mfma_f32_16x16x32_bf16 v[18:21], v[224:227], v[182:185], v[18:21]
	v_mfma_f32_16x16x32_bf16 v[6:9], v[216:219], v[208:211], v[6:9]
	v_mfma_f32_16x16x32_bf16 v[2:5], v[224:227], v[208:211], v[2:5]
	s_barrier
	s_cbranch_scc0 .LBB0_806
